# hand-written SSM phase: 32x32x16 MFMA B*u kept in f32 regs + permlane32_swap transpose + DPP re/im; 2-deep u prefetch; XCD-local pair mapping
# speedup vs baseline: 1.0063x; 1.0063x over previous
.LBB0_340:
	s_cmp_lt_i32 s96, 4
	s_cselect_b64 s[0:1], -1, 0
	s_and_b64 s[8:9], s[0:1], s[4:5]
	s_andn2_b64 vcc, exec, s[8:9]
	s_cbranch_vccnz .LBB0_393
	v_cmp_gt_u32_e32 vcc, 2, v190
	s_and_saveexec_b64 s[0:1], vcc
	v_lshlrev_b32_e32 v2, 2, v190
	v_add_u32_e32 v2, 0x21000, v2
	v_mov_b32_e32 v3, 0
	ds_write_b32 v2, v3
	s_mov_b64 exec, s[0:1]
	v_and_b32_e32 v172, 31, v191
	v_lshrrev_b32_e32 v173, 5, v191
	v_and_b32_e32 v174, 1, v191
	v_and_b32_e32 v175, 15, v191
	v_lshrrev_b32_e32 v176, 4, v191
	s_mul_i32 s20, s89, 0x3200
	v_lshl_add_u32 v151, v191, 2, s20
	v_mul_u32_u24_e32 v182, 0x110, v175
	v_lshl_add_u32 v182, v176, 4, v182
	v_add_u32_e32 v152, s20, v182
	v_mul_u32_u24_e32 v182, 0x1800, v172
	v_lshl_add_u32 v150, v173, 4, v182
	v_mul_u32_u24_e32 v182, 0x1800, v175
	v_lshl_add_u32 v154, v176, 3, v182
	v_add_u32_e32 v158, 0x18000, v154
	v_lshlrev_b32_e32 v182, 12, v175
	v_lshl_add_u32 v153, v176, 4, v182
	v_add_u32_e32 v157, 0x10000, v153
	v_lshlrev_b32_e32 v182, 11, v175
	v_lshl_add_u32 v156, v176, 3, v182
	v_add_u32_e32 v159, 0x8000, v156
	s_and_b32 s21, s89, 3
	s_lshl_b32 s21, s21, 13
	s_add_u32 s21, s21, 0x19000
	v_lshlrev_b32_e32 v182, 5, v175
	v_lshl_add_u32 v182, v176, 3, v182
	v_add_u32_e32 v155, s21, v182
	v_lshrrev_b32_e32 v182, 4, v172
	v_lshlrev_b32_e32 v182, 10, v182
	v_lshl_add_u32 v182, v175, 4, v182
	v_lshl_add_u32 v177, v173, 8, v182
	v_lshrrev_b32_e32 v182, 1, v176
	v_lshlrev_b32_e32 v182, 8, v182
	v_and_b32_e32 v183, 1, v176
	v_lshl_add_u32 v182, v183, 3, v182
	v_lshl_add_u32 v178, v175, 4, v182
	v_lshrrev_b32_e32 v182, 1, v172
	v_lshl_add_u32 v182, v173, 5, v182
	v_lshlrev_b32_e32 v179, 3, v182
	v_lshlrev_b32_e32 v183, 14, v174
	v_lshl_add_u32 v180, v182, 2, v183
	v_lshlrev_b32_e32 v181, 4, v176
	s_waitcnt vmcnt(0) lgkmcnt(0)
	s_barrier
	s_cmp_lt_u32 s89, 4
	s_cbranch_scc0 .Lssm_ctx
	s_lshr_b32 s21, s89, 1
	s_and_b32 s22, s2, 7
	s_lshl_b32 s22, s22, 6
	s_lshr_b32 s26, s2, 3
	s_lshl_b32 s26, s26, 1
	s_add_u32 s22, s22, s26
	s_add_u32 s22, s22, s21
	s_lshr_b32 s23, s22, 6
	s_and_b32 s24, s22, 63
	s_lshl_b32 s25, s23, 10
	s_add_u32 s25, s25, 0x2000
	s_and_b32 s26, s89, 1
	s_cmp_eq_u32 s26, 0
	s_cbranch_scc0 .Lssm_lat_bwd
	s_add_u32 s28, s24, 0
	s_lshl_b32 s29, s28, 13
	s_add_u32 s29, s29, 0x200000
	s_add_u32 s10, s62, s29
	s_addc_u32 s11, s63, 0
	global_load_dwordx4 v[84:87], v177, s[10:11]
	global_load_dwordx4 v[88:91], v177, s[10:11] offset:2048
	s_add_u32 s12, s10, 0x1000
	s_addc_u32 s13, s11, 0
	global_load_dwordx4 v[92:95], v177, s[12:13]
	global_load_dwordx4 v[96:99], v177, s[12:13] offset:2048
	s_lshl_b32 s29, s28, 12
	s_add_u32 s29, s29, 0x300000
	s_add_u32 s16, s62, s29
	s_addc_u32 s17, s63, 0
	global_load_dwordx2 v[2:3], v178, s[16:17]
	global_load_dwordx2 v[4:5], v178, s[16:17] offset:1024
	global_load_dwordx2 v[6:7], v178, s[16:17] offset:512
	global_load_dwordx2 v[8:9], v178, s[16:17] offset:1536
	global_load_dwordx2 v[10:11], v178, s[16:17] offset:2048
	global_load_dwordx2 v[12:13], v178, s[16:17] offset:3072
	global_load_dwordx2 v[14:15], v178, s[16:17] offset:2560
	global_load_dwordx2 v[16:17], v178, s[16:17] offset:3584
	s_lshl_b32 s29, s28, 9
	s_add_u32 s29, s29, 0x100000
	s_add_u32 s18, s62, s29
	s_addc_u32 s19, s63, 0
	global_load_dwordx2 v[116:117], v179, s[18:19]
	global_load_dwordx2 v[118:119], v179, s[18:19] offset:128
	s_lshl_b32 s30, s23, 1
	s_lshl_b32 s30, s30, 15
	s_lshl_b32 s31, s24, 8
	s_add_u32 s30, s30, s31
	v_readlane_b32 s34, v254, 10
	v_readlane_b32 s35, v254, 11
	s_nop 3
	s_add_u32 s34, s34, s30
	s_addc_u32 s35, s35, 0
	global_load_dword v120, v180, s[34:35]
	global_load_dword v121, v180, s[34:35] offset:64
	s_mul_i32 s31, s25, 0x1800
	s_lshl_b32 s29, s24, 5
	s_add_u32 s31, s31, s29
	s_add_u32 s31, s31, 0x8801000
	s_add_u32 s4, s62, s31
	s_addc_u32 s5, s63, 0
	s_lshl_b32 s31, s25, 12
	s_lshl_b32 s29, s24, 6
	s_add_u32 s31, s31, s29
	s_add_u32 s6, s60, s31
	s_addc_u32 s7, s61, 0
	s_add_u32 s34, s4, 0
	s_addc_u32 s35, s5, 0
	global_load_dwordx4 v[80:83], v150, s[34:35]
	s_mov_b64 s[10:11], s[34:35]
	s_add_u32 s10, s10, 196608
	s_addc_u32 s11, s11, 0
	global_load_dwordx4 v[144:147], v150, s[10:11]
	s_mov_b64 s[34:35], s[10:11]
	s_add_u32 s10, s10, 196608
	s_addc_u32 s11, s11, 0
	s_add_u32 s12, s6, 0
	s_addc_u32 s13, s7, 0
	s_mov_b32 s14, 0
	s_mov_b32 s40, 0xffff0000
	s_waitcnt vmcnt(0)
	v_and_b32_e32 v182, 0xffff, v2
	v_lshrrev_b32_e32 v183, 16, v2
	v_and_b32_e32 v184, 0xffff, v3
	v_lshrrev_b32_e32 v185, 16, v3
	v_lshl_or_b32 v100, v4, 16, v182
	v_and_or_b32 v101, v4, s40, v183
	v_lshl_or_b32 v102, v5, 16, v184
	v_and_or_b32 v103, v5, s40, v185
	v_and_b32_e32 v182, 0xffff, v6
	v_lshrrev_b32_e32 v183, 16, v6
	v_and_b32_e32 v184, 0xffff, v7
	v_lshrrev_b32_e32 v185, 16, v7
	v_lshl_or_b32 v104, v8, 16, v182
	v_and_or_b32 v105, v8, s40, v183
	v_lshl_or_b32 v106, v9, 16, v184
	v_and_or_b32 v107, v9, s40, v185
	v_and_b32_e32 v182, 0xffff, v10
	v_lshrrev_b32_e32 v183, 16, v10
	v_and_b32_e32 v184, 0xffff, v11
	v_lshrrev_b32_e32 v185, 16, v11
	v_lshl_or_b32 v108, v12, 16, v182
	v_and_or_b32 v109, v12, s40, v183
	v_lshl_or_b32 v110, v13, 16, v184
	v_and_or_b32 v111, v13, s40, v185
	v_and_b32_e32 v182, 0xffff, v14
	v_lshrrev_b32_e32 v183, 16, v14
	v_and_b32_e32 v184, 0xffff, v15
	v_lshrrev_b32_e32 v185, 16, v15
	v_lshl_or_b32 v112, v16, 16, v182
	v_and_or_b32 v113, v16, s40, v183
	v_lshl_or_b32 v114, v17, 16, v184
	v_and_or_b32 v115, v17, s40, v185
	v_cmp_eq_u32_e32 vcc, 1, v174
	v_xor_b32_e32 v182, 0x80000000, v117
	v_xor_b32_e32 v183, 0x80000000, v119
	s_nop 1
	v_cndmask_b32_e32 v122, v182, v117, vcc
	v_cndmask_b32_e32 v123, v183, v119, vcc
.Lssm_tile_d0m0:
	s_waitcnt vmcnt(5)
	v_mfma_f32_32x32x16_bf16 v[16:31], v[80:83], v[84:87], 0
	v_mfma_f32_32x32x16_bf16 v[32:47], v[80:83], v[88:91], 0
	v_mfma_f32_32x32x16_bf16 v[48:63], v[80:83], v[92:95], 0
	v_mfma_f32_32x32x16_bf16 v[64:79], v[80:83], v[96:99], 0
	s_nop 11
	global_load_dwordx4 v[80:83], v150, s[10:11]
	s_add_u32 s34, s34, 196608
	s_addc_u32 s35, s35, 0
	s_add_u32 s10, s10, 196608
	s_addc_u32 s11, s11, 0
	v_permlane32_swap_b32_e32 v16, v48
	v_permlane32_swap_b32_e32 v17, v49
	v_permlane32_swap_b32_e32 v18, v50
	v_permlane32_swap_b32_e32 v19, v51
	v_permlane32_swap_b32_e32 v20, v52
	v_permlane32_swap_b32_e32 v21, v53
	v_permlane32_swap_b32_e32 v22, v54
	v_permlane32_swap_b32_e32 v23, v55
	v_permlane32_swap_b32_e32 v24, v56
	v_permlane32_swap_b32_e32 v25, v57
	v_permlane32_swap_b32_e32 v26, v58
	v_permlane32_swap_b32_e32 v27, v59
	v_permlane32_swap_b32_e32 v28, v60
	v_permlane32_swap_b32_e32 v29, v61
	v_permlane32_swap_b32_e32 v30, v62
	v_permlane32_swap_b32_e32 v31, v63
	v_permlane32_swap_b32_e32 v32, v64
	v_permlane32_swap_b32_e32 v33, v65
	v_permlane32_swap_b32_e32 v34, v66
	v_permlane32_swap_b32_e32 v35, v67
	v_permlane32_swap_b32_e32 v36, v68
	v_permlane32_swap_b32_e32 v37, v69
	v_permlane32_swap_b32_e32 v38, v70
	v_permlane32_swap_b32_e32 v39, v71
	v_permlane32_swap_b32_e32 v40, v72
	v_permlane32_swap_b32_e32 v41, v73
	v_permlane32_swap_b32_e32 v42, v74
	v_permlane32_swap_b32_e32 v43, v75
	v_permlane32_swap_b32_e32 v44, v76
	v_permlane32_swap_b32_e32 v45, v77
	v_permlane32_swap_b32_e32 v46, v78
	v_permlane32_swap_b32_e32 v47, v79
	v_fmac_f32_e32 v16, v116, v120
	v_fmac_f32_e32 v32, v118, v121
	v_fmac_f32_dpp v16, v120, v122 quad_perm:[1,0,3,2] row_mask:0xf bank_mask:0xf
	v_fmac_f32_dpp v32, v121, v123 quad_perm:[1,0,3,2] row_mask:0xf bank_mask:0xf
	v_cvt_pk_bf16_f32 v148, v16, v32
	ds_write_b32 v151, v148
	v_fmac_f32_e32 v17, v116, v16
	v_fmac_f32_e32 v33, v118, v32
	v_fmac_f32_dpp v17, v16, v122 quad_perm:[1,0,3,2] row_mask:0xf bank_mask:0xf
	v_fmac_f32_dpp v33, v32, v123 quad_perm:[1,0,3,2] row_mask:0xf bank_mask:0xf
	v_cvt_pk_bf16_f32 v149, v17, v33
	ds_write_b32 v151, v149 offset:272
	v_fmac_f32_e32 v18, v116, v17
	v_fmac_f32_e32 v34, v118, v33
	v_fmac_f32_dpp v18, v17, v122 quad_perm:[1,0,3,2] row_mask:0xf bank_mask:0xf
	v_fmac_f32_dpp v34, v33, v123 quad_perm:[1,0,3,2] row_mask:0xf bank_mask:0xf
	v_cvt_pk_bf16_f32 v148, v18, v34
	ds_write_b32 v151, v148 offset:544
	v_fmac_f32_e32 v19, v116, v18
	v_fmac_f32_e32 v35, v118, v34
	v_fmac_f32_dpp v19, v18, v122 quad_perm:[1,0,3,2] row_mask:0xf bank_mask:0xf
	v_fmac_f32_dpp v35, v34, v123 quad_perm:[1,0,3,2] row_mask:0xf bank_mask:0xf
	v_cvt_pk_bf16_f32 v149, v19, v35
	ds_write_b32 v151, v149 offset:816
	v_fmac_f32_e32 v48, v116, v19
	v_fmac_f32_e32 v64, v118, v35
	v_fmac_f32_dpp v48, v19, v122 quad_perm:[1,0,3,2] row_mask:0xf bank_mask:0xf
	v_fmac_f32_dpp v64, v35, v123 quad_perm:[1,0,3,2] row_mask:0xf bank_mask:0xf
	v_cvt_pk_bf16_f32 v148, v48, v64
	ds_write_b32 v151, v148 offset:1088
	v_fmac_f32_e32 v49, v116, v48
	v_fmac_f32_e32 v65, v118, v64
	v_fmac_f32_dpp v49, v48, v122 quad_perm:[1,0,3,2] row_mask:0xf bank_mask:0xf
	v_fmac_f32_dpp v65, v64, v123 quad_perm:[1,0,3,2] row_mask:0xf bank_mask:0xf
	v_cvt_pk_bf16_f32 v149, v49, v65
	ds_write_b32 v151, v149 offset:1360
	v_fmac_f32_e32 v50, v116, v49
	v_fmac_f32_e32 v66, v118, v65
	v_fmac_f32_dpp v50, v49, v122 quad_perm:[1,0,3,2] row_mask:0xf bank_mask:0xf
	v_fmac_f32_dpp v66, v65, v123 quad_perm:[1,0,3,2] row_mask:0xf bank_mask:0xf
	v_cvt_pk_bf16_f32 v148, v50, v66
	ds_write_b32 v151, v148 offset:1632
	v_fmac_f32_e32 v51, v116, v50
	v_fmac_f32_e32 v67, v118, v66
	v_fmac_f32_dpp v51, v50, v122 quad_perm:[1,0,3,2] row_mask:0xf bank_mask:0xf
	v_fmac_f32_dpp v67, v66, v123 quad_perm:[1,0,3,2] row_mask:0xf bank_mask:0xf
	v_cvt_pk_bf16_f32 v149, v51, v67
	ds_write_b32 v151, v149 offset:1904
	v_fmac_f32_e32 v20, v116, v51
	v_fmac_f32_e32 v36, v118, v67
	v_fmac_f32_dpp v20, v51, v122 quad_perm:[1,0,3,2] row_mask:0xf bank_mask:0xf
	v_fmac_f32_dpp v36, v67, v123 quad_perm:[1,0,3,2] row_mask:0xf bank_mask:0xf
	v_cvt_pk_bf16_f32 v148, v20, v36
	ds_write_b32 v151, v148 offset:2176
	v_fmac_f32_e32 v21, v116, v20
	v_fmac_f32_e32 v37, v118, v36
	v_fmac_f32_dpp v21, v20, v122 quad_perm:[1,0,3,2] row_mask:0xf bank_mask:0xf
	v_fmac_f32_dpp v37, v36, v123 quad_perm:[1,0,3,2] row_mask:0xf bank_mask:0xf
	v_cvt_pk_bf16_f32 v149, v21, v37
	ds_write_b32 v151, v149 offset:2448
	v_fmac_f32_e32 v22, v116, v21
	v_fmac_f32_e32 v38, v118, v37
	v_fmac_f32_dpp v22, v21, v122 quad_perm:[1,0,3,2] row_mask:0xf bank_mask:0xf
	v_fmac_f32_dpp v38, v37, v123 quad_perm:[1,0,3,2] row_mask:0xf bank_mask:0xf
	v_cvt_pk_bf16_f32 v148, v22, v38
	ds_write_b32 v151, v148 offset:2720
	v_fmac_f32_e32 v23, v116, v22
	v_fmac_f32_e32 v39, v118, v38
	v_fmac_f32_dpp v23, v22, v122 quad_perm:[1,0,3,2] row_mask:0xf bank_mask:0xf
	v_fmac_f32_dpp v39, v38, v123 quad_perm:[1,0,3,2] row_mask:0xf bank_mask:0xf
	v_cvt_pk_bf16_f32 v149, v23, v39
	ds_write_b32 v151, v149 offset:2992
	v_fmac_f32_e32 v52, v116, v23
	v_fmac_f32_e32 v68, v118, v39
	v_fmac_f32_dpp v52, v23, v122 quad_perm:[1,0,3,2] row_mask:0xf bank_mask:0xf
	v_fmac_f32_dpp v68, v39, v123 quad_perm:[1,0,3,2] row_mask:0xf bank_mask:0xf
	v_cvt_pk_bf16_f32 v148, v52, v68
	ds_write_b32 v151, v148 offset:3264
	v_fmac_f32_e32 v53, v116, v52
	v_fmac_f32_e32 v69, v118, v68
	v_fmac_f32_dpp v53, v52, v122 quad_perm:[1,0,3,2] row_mask:0xf bank_mask:0xf
	v_fmac_f32_dpp v69, v68, v123 quad_perm:[1,0,3,2] row_mask:0xf bank_mask:0xf
	v_cvt_pk_bf16_f32 v149, v53, v69
	ds_write_b32 v151, v149 offset:3536
	v_fmac_f32_e32 v54, v116, v53
	v_fmac_f32_e32 v70, v118, v69
	v_fmac_f32_dpp v54, v53, v122 quad_perm:[1,0,3,2] row_mask:0xf bank_mask:0xf
	v_fmac_f32_dpp v70, v69, v123 quad_perm:[1,0,3,2] row_mask:0xf bank_mask:0xf
	v_cvt_pk_bf16_f32 v148, v54, v70
	ds_write_b32 v151, v148 offset:3808
	v_fmac_f32_e32 v55, v116, v54
	v_fmac_f32_e32 v71, v118, v70
	v_fmac_f32_dpp v55, v54, v122 quad_perm:[1,0,3,2] row_mask:0xf bank_mask:0xf
	v_fmac_f32_dpp v71, v70, v123 quad_perm:[1,0,3,2] row_mask:0xf bank_mask:0xf
	v_cvt_pk_bf16_f32 v149, v55, v71
	ds_write_b32 v151, v149 offset:4080
	v_fmac_f32_e32 v24, v116, v55
	v_fmac_f32_e32 v40, v118, v71
	v_fmac_f32_dpp v24, v55, v122 quad_perm:[1,0,3,2] row_mask:0xf bank_mask:0xf
	v_fmac_f32_dpp v40, v71, v123 quad_perm:[1,0,3,2] row_mask:0xf bank_mask:0xf
	v_cvt_pk_bf16_f32 v148, v24, v40
	ds_write_b32 v151, v148 offset:4352
	v_fmac_f32_e32 v25, v116, v24
	v_fmac_f32_e32 v41, v118, v40
	v_fmac_f32_dpp v25, v24, v122 quad_perm:[1,0,3,2] row_mask:0xf bank_mask:0xf
	v_fmac_f32_dpp v41, v40, v123 quad_perm:[1,0,3,2] row_mask:0xf bank_mask:0xf
	v_cvt_pk_bf16_f32 v149, v25, v41
	ds_write_b32 v151, v149 offset:4624
	v_fmac_f32_e32 v26, v116, v25
	v_fmac_f32_e32 v42, v118, v41
	v_fmac_f32_dpp v26, v25, v122 quad_perm:[1,0,3,2] row_mask:0xf bank_mask:0xf
	v_fmac_f32_dpp v42, v41, v123 quad_perm:[1,0,3,2] row_mask:0xf bank_mask:0xf
	v_cvt_pk_bf16_f32 v148, v26, v42
	ds_write_b32 v151, v148 offset:4896
	v_fmac_f32_e32 v27, v116, v26
	v_fmac_f32_e32 v43, v118, v42
	v_fmac_f32_dpp v27, v26, v122 quad_perm:[1,0,3,2] row_mask:0xf bank_mask:0xf
	v_fmac_f32_dpp v43, v42, v123 quad_perm:[1,0,3,2] row_mask:0xf bank_mask:0xf
	v_cvt_pk_bf16_f32 v149, v27, v43
	ds_write_b32 v151, v149 offset:5168
	v_fmac_f32_e32 v56, v116, v27
	v_fmac_f32_e32 v72, v118, v43
	v_fmac_f32_dpp v56, v27, v122 quad_perm:[1,0,3,2] row_mask:0xf bank_mask:0xf
	v_fmac_f32_dpp v72, v43, v123 quad_perm:[1,0,3,2] row_mask:0xf bank_mask:0xf
	v_cvt_pk_bf16_f32 v148, v56, v72
	ds_write_b32 v151, v148 offset:5440
	v_fmac_f32_e32 v57, v116, v56
	v_fmac_f32_e32 v73, v118, v72
	v_fmac_f32_dpp v57, v56, v122 quad_perm:[1,0,3,2] row_mask:0xf bank_mask:0xf
	v_fmac_f32_dpp v73, v72, v123 quad_perm:[1,0,3,2] row_mask:0xf bank_mask:0xf
	v_cvt_pk_bf16_f32 v149, v57, v73
	ds_write_b32 v151, v149 offset:5712
	v_fmac_f32_e32 v58, v116, v57
	v_fmac_f32_e32 v74, v118, v73
	v_fmac_f32_dpp v58, v57, v122 quad_perm:[1,0,3,2] row_mask:0xf bank_mask:0xf
	v_fmac_f32_dpp v74, v73, v123 quad_perm:[1,0,3,2] row_mask:0xf bank_mask:0xf
	v_cvt_pk_bf16_f32 v148, v58, v74
	ds_write_b32 v151, v148 offset:5984
	v_fmac_f32_e32 v59, v116, v58
	v_fmac_f32_e32 v75, v118, v74
	v_fmac_f32_dpp v59, v58, v122 quad_perm:[1,0,3,2] row_mask:0xf bank_mask:0xf
	v_fmac_f32_dpp v75, v74, v123 quad_perm:[1,0,3,2] row_mask:0xf bank_mask:0xf
	v_cvt_pk_bf16_f32 v149, v59, v75
	ds_write_b32 v151, v149 offset:6256
	v_fmac_f32_e32 v28, v116, v59
	v_fmac_f32_e32 v44, v118, v75
	v_fmac_f32_dpp v28, v59, v122 quad_perm:[1,0,3,2] row_mask:0xf bank_mask:0xf
	v_fmac_f32_dpp v44, v75, v123 quad_perm:[1,0,3,2] row_mask:0xf bank_mask:0xf
	v_cvt_pk_bf16_f32 v148, v28, v44
	ds_write_b32 v151, v148 offset:6528
	v_fmac_f32_e32 v29, v116, v28
	v_fmac_f32_e32 v45, v118, v44
	v_fmac_f32_dpp v29, v28, v122 quad_perm:[1,0,3,2] row_mask:0xf bank_mask:0xf
	v_fmac_f32_dpp v45, v44, v123 quad_perm:[1,0,3,2] row_mask:0xf bank_mask:0xf
	v_cvt_pk_bf16_f32 v149, v29, v45
	ds_write_b32 v151, v149 offset:6800
	v_fmac_f32_e32 v30, v116, v29
	v_fmac_f32_e32 v46, v118, v45
	v_fmac_f32_dpp v30, v29, v122 quad_perm:[1,0,3,2] row_mask:0xf bank_mask:0xf
	v_fmac_f32_dpp v46, v45, v123 quad_perm:[1,0,3,2] row_mask:0xf bank_mask:0xf
	v_cvt_pk_bf16_f32 v148, v30, v46
	ds_write_b32 v151, v148 offset:7072
	v_fmac_f32_e32 v31, v116, v30
	v_fmac_f32_e32 v47, v118, v46
	v_fmac_f32_dpp v31, v30, v122 quad_perm:[1,0,3,2] row_mask:0xf bank_mask:0xf
	v_fmac_f32_dpp v47, v46, v123 quad_perm:[1,0,3,2] row_mask:0xf bank_mask:0xf
	v_cvt_pk_bf16_f32 v149, v31, v47
	ds_write_b32 v151, v149 offset:7344
	v_fmac_f32_e32 v60, v116, v31
	v_fmac_f32_e32 v76, v118, v47
	v_fmac_f32_dpp v60, v31, v122 quad_perm:[1,0,3,2] row_mask:0xf bank_mask:0xf
	v_fmac_f32_dpp v76, v47, v123 quad_perm:[1,0,3,2] row_mask:0xf bank_mask:0xf
	v_cvt_pk_bf16_f32 v148, v60, v76
	ds_write_b32 v151, v148 offset:7616
	v_fmac_f32_e32 v61, v116, v60
	v_fmac_f32_e32 v77, v118, v76
	v_fmac_f32_dpp v61, v60, v122 quad_perm:[1,0,3,2] row_mask:0xf bank_mask:0xf
	v_fmac_f32_dpp v77, v76, v123 quad_perm:[1,0,3,2] row_mask:0xf bank_mask:0xf
	v_cvt_pk_bf16_f32 v149, v61, v77
	ds_write_b32 v151, v149 offset:7888
	v_fmac_f32_e32 v62, v116, v61
	v_fmac_f32_e32 v78, v118, v77
	v_fmac_f32_dpp v62, v61, v122 quad_perm:[1,0,3,2] row_mask:0xf bank_mask:0xf
	v_fmac_f32_dpp v78, v77, v123 quad_perm:[1,0,3,2] row_mask:0xf bank_mask:0xf
	v_cvt_pk_bf16_f32 v148, v62, v78
	ds_write_b32 v151, v148 offset:8160
	v_fmac_f32_e32 v63, v116, v62
	v_fmac_f32_e32 v79, v118, v78
	v_fmac_f32_dpp v63, v62, v122 quad_perm:[1,0,3,2] row_mask:0xf bank_mask:0xf
	v_fmac_f32_dpp v79, v78, v123 quad_perm:[1,0,3,2] row_mask:0xf bank_mask:0xf
	v_cvt_pk_bf16_f32 v149, v63, v79
	ds_write_b32 v151, v149 offset:8432
	v_mov_b32_e32 v120, v63
	v_mov_b32_e32 v121, v79
	ds_read_b128 v[124:127], v152
	ds_read_b128 v[128:131], v152 offset:64
	ds_read_b128 v[132:135], v152 offset:128
	ds_read_b128 v[136:139], v152 offset:192
	s_waitcnt lgkmcnt(3)
	v_mfma_f32_16x16x32_bf16 v[140:143], v[100:103], v[124:127], 0
	s_waitcnt lgkmcnt(2)
	v_mfma_f32_16x16x32_bf16 v[140:143], v[104:107], v[128:131], v[140:143]
	s_waitcnt lgkmcnt(1)
	v_mfma_f32_16x16x32_bf16 v[140:143], v[108:111], v[132:135], v[140:143]
	s_waitcnt lgkmcnt(0)
	v_mfma_f32_16x16x32_bf16 v[140:143], v[112:115], v[136:139], v[140:143]
	s_nop 9
	global_store_dwordx4 v153, v[140:143], s[12:13]
	s_nop 1
	ds_read_b128 v[124:127], v152 offset:4352
	ds_read_b128 v[128:131], v152 offset:4416
	ds_read_b128 v[132:135], v152 offset:4480
	ds_read_b128 v[136:139], v152 offset:4544
	s_waitcnt lgkmcnt(3)
	v_mfma_f32_16x16x32_bf16 v[140:143], v[100:103], v[124:127], 0
	s_waitcnt lgkmcnt(2)
	v_mfma_f32_16x16x32_bf16 v[140:143], v[104:107], v[128:131], v[140:143]
	s_waitcnt lgkmcnt(1)
	v_mfma_f32_16x16x32_bf16 v[140:143], v[108:111], v[132:135], v[140:143]
	s_waitcnt lgkmcnt(0)
	v_mfma_f32_16x16x32_bf16 v[140:143], v[112:115], v[136:139], v[140:143]
	s_nop 9
	global_store_dwordx4 v157, v[140:143], s[12:13]
	s_nop 1
	s_add_u32 s12, s12, 131072
	s_addc_u32 s13, s13, 0
	s_waitcnt vmcnt(5)
	v_mfma_f32_32x32x16_bf16 v[16:31], v[144:147], v[84:87], 0
	v_mfma_f32_32x32x16_bf16 v[32:47], v[144:147], v[88:91], 0
	v_mfma_f32_32x32x16_bf16 v[48:63], v[144:147], v[92:95], 0
	v_mfma_f32_32x32x16_bf16 v[64:79], v[144:147], v[96:99], 0
	s_nop 11
	global_load_dwordx4 v[144:147], v150, s[10:11]
	s_add_u32 s34, s34, 196608
	s_addc_u32 s35, s35, 0
	s_add_u32 s10, s10, 196608
	s_addc_u32 s11, s11, 0
	v_permlane32_swap_b32_e32 v16, v48
	v_permlane32_swap_b32_e32 v17, v49
	v_permlane32_swap_b32_e32 v18, v50
	v_permlane32_swap_b32_e32 v19, v51
	v_permlane32_swap_b32_e32 v20, v52
	v_permlane32_swap_b32_e32 v21, v53
	v_permlane32_swap_b32_e32 v22, v54
	v_permlane32_swap_b32_e32 v23, v55
	v_permlane32_swap_b32_e32 v24, v56
	v_permlane32_swap_b32_e32 v25, v57
	v_permlane32_swap_b32_e32 v26, v58
	v_permlane32_swap_b32_e32 v27, v59
	v_permlane32_swap_b32_e32 v28, v60
	v_permlane32_swap_b32_e32 v29, v61
	v_permlane32_swap_b32_e32 v30, v62
	v_permlane32_swap_b32_e32 v31, v63
	v_permlane32_swap_b32_e32 v32, v64
	v_permlane32_swap_b32_e32 v33, v65
	v_permlane32_swap_b32_e32 v34, v66
	v_permlane32_swap_b32_e32 v35, v67
	v_permlane32_swap_b32_e32 v36, v68
	v_permlane32_swap_b32_e32 v37, v69
	v_permlane32_swap_b32_e32 v38, v70
	v_permlane32_swap_b32_e32 v39, v71
	v_permlane32_swap_b32_e32 v40, v72
	v_permlane32_swap_b32_e32 v41, v73
	v_permlane32_swap_b32_e32 v42, v74
	v_permlane32_swap_b32_e32 v43, v75
	v_permlane32_swap_b32_e32 v44, v76
	v_permlane32_swap_b32_e32 v45, v77
	v_permlane32_swap_b32_e32 v46, v78
	v_permlane32_swap_b32_e32 v47, v79
	v_fmac_f32_e32 v16, v116, v120
	v_fmac_f32_e32 v32, v118, v121
	v_fmac_f32_dpp v16, v120, v122 quad_perm:[1,0,3,2] row_mask:0xf bank_mask:0xf
	v_fmac_f32_dpp v32, v121, v123 quad_perm:[1,0,3,2] row_mask:0xf bank_mask:0xf
	v_cvt_pk_bf16_f32 v148, v16, v32
	ds_write_b32 v151, v148
	v_fmac_f32_e32 v17, v116, v16
	v_fmac_f32_e32 v33, v118, v32
	v_fmac_f32_dpp v17, v16, v122 quad_perm:[1,0,3,2] row_mask:0xf bank_mask:0xf
	v_fmac_f32_dpp v33, v32, v123 quad_perm:[1,0,3,2] row_mask:0xf bank_mask:0xf
	v_cvt_pk_bf16_f32 v149, v17, v33
	ds_write_b32 v151, v149 offset:272
	v_fmac_f32_e32 v18, v116, v17
	v_fmac_f32_e32 v34, v118, v33
	v_fmac_f32_dpp v18, v17, v122 quad_perm:[1,0,3,2] row_mask:0xf bank_mask:0xf
	v_fmac_f32_dpp v34, v33, v123 quad_perm:[1,0,3,2] row_mask:0xf bank_mask:0xf
	v_cvt_pk_bf16_f32 v148, v18, v34
	ds_write_b32 v151, v148 offset:544
	v_fmac_f32_e32 v19, v116, v18
	v_fmac_f32_e32 v35, v118, v34
	v_fmac_f32_dpp v19, v18, v122 quad_perm:[1,0,3,2] row_mask:0xf bank_mask:0xf
	v_fmac_f32_dpp v35, v34, v123 quad_perm:[1,0,3,2] row_mask:0xf bank_mask:0xf
	v_cvt_pk_bf16_f32 v149, v19, v35
	ds_write_b32 v151, v149 offset:816
	v_fmac_f32_e32 v48, v116, v19
	v_fmac_f32_e32 v64, v118, v35
	v_fmac_f32_dpp v48, v19, v122 quad_perm:[1,0,3,2] row_mask:0xf bank_mask:0xf
	v_fmac_f32_dpp v64, v35, v123 quad_perm:[1,0,3,2] row_mask:0xf bank_mask:0xf
	v_cvt_pk_bf16_f32 v148, v48, v64
	ds_write_b32 v151, v148 offset:1088
	v_fmac_f32_e32 v49, v116, v48
	v_fmac_f32_e32 v65, v118, v64
	v_fmac_f32_dpp v49, v48, v122 quad_perm:[1,0,3,2] row_mask:0xf bank_mask:0xf
	v_fmac_f32_dpp v65, v64, v123 quad_perm:[1,0,3,2] row_mask:0xf bank_mask:0xf
	v_cvt_pk_bf16_f32 v149, v49, v65
	ds_write_b32 v151, v149 offset:1360
	v_fmac_f32_e32 v50, v116, v49
	v_fmac_f32_e32 v66, v118, v65
	v_fmac_f32_dpp v50, v49, v122 quad_perm:[1,0,3,2] row_mask:0xf bank_mask:0xf
	v_fmac_f32_dpp v66, v65, v123 quad_perm:[1,0,3,2] row_mask:0xf bank_mask:0xf
	v_cvt_pk_bf16_f32 v148, v50, v66
	ds_write_b32 v151, v148 offset:1632
	v_fmac_f32_e32 v51, v116, v50
	v_fmac_f32_e32 v67, v118, v66
	v_fmac_f32_dpp v51, v50, v122 quad_perm:[1,0,3,2] row_mask:0xf bank_mask:0xf
	v_fmac_f32_dpp v67, v66, v123 quad_perm:[1,0,3,2] row_mask:0xf bank_mask:0xf
	v_cvt_pk_bf16_f32 v149, v51, v67
	ds_write_b32 v151, v149 offset:1904
	v_fmac_f32_e32 v20, v116, v51
	v_fmac_f32_e32 v36, v118, v67
	v_fmac_f32_dpp v20, v51, v122 quad_perm:[1,0,3,2] row_mask:0xf bank_mask:0xf
	v_fmac_f32_dpp v36, v67, v123 quad_perm:[1,0,3,2] row_mask:0xf bank_mask:0xf
	v_cvt_pk_bf16_f32 v148, v20, v36
	ds_write_b32 v151, v148 offset:2176
	v_fmac_f32_e32 v21, v116, v20
	v_fmac_f32_e32 v37, v118, v36
	v_fmac_f32_dpp v21, v20, v122 quad_perm:[1,0,3,2] row_mask:0xf bank_mask:0xf
	v_fmac_f32_dpp v37, v36, v123 quad_perm:[1,0,3,2] row_mask:0xf bank_mask:0xf
	v_cvt_pk_bf16_f32 v149, v21, v37
	ds_write_b32 v151, v149 offset:2448
	v_fmac_f32_e32 v22, v116, v21
	v_fmac_f32_e32 v38, v118, v37
	v_fmac_f32_dpp v22, v21, v122 quad_perm:[1,0,3,2] row_mask:0xf bank_mask:0xf
	v_fmac_f32_dpp v38, v37, v123 quad_perm:[1,0,3,2] row_mask:0xf bank_mask:0xf
	v_cvt_pk_bf16_f32 v148, v22, v38
	ds_write_b32 v151, v148 offset:2720
	v_fmac_f32_e32 v23, v116, v22
	v_fmac_f32_e32 v39, v118, v38
	v_fmac_f32_dpp v23, v22, v122 quad_perm:[1,0,3,2] row_mask:0xf bank_mask:0xf
	v_fmac_f32_dpp v39, v38, v123 quad_perm:[1,0,3,2] row_mask:0xf bank_mask:0xf
	v_cvt_pk_bf16_f32 v149, v23, v39
	ds_write_b32 v151, v149 offset:2992
	v_fmac_f32_e32 v52, v116, v23
	v_fmac_f32_e32 v68, v118, v39
	v_fmac_f32_dpp v52, v23, v122 quad_perm:[1,0,3,2] row_mask:0xf bank_mask:0xf
	v_fmac_f32_dpp v68, v39, v123 quad_perm:[1,0,3,2] row_mask:0xf bank_mask:0xf
	v_cvt_pk_bf16_f32 v148, v52, v68
	ds_write_b32 v151, v148 offset:3264
	v_fmac_f32_e32 v53, v116, v52
	v_fmac_f32_e32 v69, v118, v68
	v_fmac_f32_dpp v53, v52, v122 quad_perm:[1,0,3,2] row_mask:0xf bank_mask:0xf
	v_fmac_f32_dpp v69, v68, v123 quad_perm:[1,0,3,2] row_mask:0xf bank_mask:0xf
	v_cvt_pk_bf16_f32 v149, v53, v69
	ds_write_b32 v151, v149 offset:3536
	v_fmac_f32_e32 v54, v116, v53
	v_fmac_f32_e32 v70, v118, v69
	v_fmac_f32_dpp v54, v53, v122 quad_perm:[1,0,3,2] row_mask:0xf bank_mask:0xf
	v_fmac_f32_dpp v70, v69, v123 quad_perm:[1,0,3,2] row_mask:0xf bank_mask:0xf
	v_cvt_pk_bf16_f32 v148, v54, v70
	ds_write_b32 v151, v148 offset:3808
	v_fmac_f32_e32 v55, v116, v54
	v_fmac_f32_e32 v71, v118, v70
	v_fmac_f32_dpp v55, v54, v122 quad_perm:[1,0,3,2] row_mask:0xf bank_mask:0xf
	v_fmac_f32_dpp v71, v70, v123 quad_perm:[1,0,3,2] row_mask:0xf bank_mask:0xf
	v_cvt_pk_bf16_f32 v149, v55, v71
	ds_write_b32 v151, v149 offset:4080
	v_fmac_f32_e32 v24, v116, v55
	v_fmac_f32_e32 v40, v118, v71
	v_fmac_f32_dpp v24, v55, v122 quad_perm:[1,0,3,2] row_mask:0xf bank_mask:0xf
	v_fmac_f32_dpp v40, v71, v123 quad_perm:[1,0,3,2] row_mask:0xf bank_mask:0xf
	v_cvt_pk_bf16_f32 v148, v24, v40
	ds_write_b32 v151, v148 offset:4352
	v_fmac_f32_e32 v25, v116, v24
	v_fmac_f32_e32 v41, v118, v40
	v_fmac_f32_dpp v25, v24, v122 quad_perm:[1,0,3,2] row_mask:0xf bank_mask:0xf
	v_fmac_f32_dpp v41, v40, v123 quad_perm:[1,0,3,2] row_mask:0xf bank_mask:0xf
	v_cvt_pk_bf16_f32 v149, v25, v41
	ds_write_b32 v151, v149 offset:4624
	v_fmac_f32_e32 v26, v116, v25
	v_fmac_f32_e32 v42, v118, v41
	v_fmac_f32_dpp v26, v25, v122 quad_perm:[1,0,3,2] row_mask:0xf bank_mask:0xf
	v_fmac_f32_dpp v42, v41, v123 quad_perm:[1,0,3,2] row_mask:0xf bank_mask:0xf
	v_cvt_pk_bf16_f32 v148, v26, v42
	ds_write_b32 v151, v148 offset:4896
	v_fmac_f32_e32 v27, v116, v26
	v_fmac_f32_e32 v43, v118, v42
	v_fmac_f32_dpp v27, v26, v122 quad_perm:[1,0,3,2] row_mask:0xf bank_mask:0xf
	v_fmac_f32_dpp v43, v42, v123 quad_perm:[1,0,3,2] row_mask:0xf bank_mask:0xf
	v_cvt_pk_bf16_f32 v149, v27, v43
	ds_write_b32 v151, v149 offset:5168
	v_fmac_f32_e32 v56, v116, v27
	v_fmac_f32_e32 v72, v118, v43
	v_fmac_f32_dpp v56, v27, v122 quad_perm:[1,0,3,2] row_mask:0xf bank_mask:0xf
	v_fmac_f32_dpp v72, v43, v123 quad_perm:[1,0,3,2] row_mask:0xf bank_mask:0xf
	v_cvt_pk_bf16_f32 v148, v56, v72
	ds_write_b32 v151, v148 offset:5440
	v_fmac_f32_e32 v57, v116, v56
	v_fmac_f32_e32 v73, v118, v72
	v_fmac_f32_dpp v57, v56, v122 quad_perm:[1,0,3,2] row_mask:0xf bank_mask:0xf
	v_fmac_f32_dpp v73, v72, v123 quad_perm:[1,0,3,2] row_mask:0xf bank_mask:0xf
	v_cvt_pk_bf16_f32 v149, v57, v73
	ds_write_b32 v151, v149 offset:5712
	v_fmac_f32_e32 v58, v116, v57
	v_fmac_f32_e32 v74, v118, v73
	v_fmac_f32_dpp v58, v57, v122 quad_perm:[1,0,3,2] row_mask:0xf bank_mask:0xf
	v_fmac_f32_dpp v74, v73, v123 quad_perm:[1,0,3,2] row_mask:0xf bank_mask:0xf
	v_cvt_pk_bf16_f32 v148, v58, v74
	ds_write_b32 v151, v148 offset:5984
	v_fmac_f32_e32 v59, v116, v58
	v_fmac_f32_e32 v75, v118, v74
	v_fmac_f32_dpp v59, v58, v122 quad_perm:[1,0,3,2] row_mask:0xf bank_mask:0xf
	v_fmac_f32_dpp v75, v74, v123 quad_perm:[1,0,3,2] row_mask:0xf bank_mask:0xf
	v_cvt_pk_bf16_f32 v149, v59, v75
	ds_write_b32 v151, v149 offset:6256
	v_fmac_f32_e32 v28, v116, v59
	v_fmac_f32_e32 v44, v118, v75
	v_fmac_f32_dpp v28, v59, v122 quad_perm:[1,0,3,2] row_mask:0xf bank_mask:0xf
	v_fmac_f32_dpp v44, v75, v123 quad_perm:[1,0,3,2] row_mask:0xf bank_mask:0xf
	v_cvt_pk_bf16_f32 v148, v28, v44
	ds_write_b32 v151, v148 offset:6528
	v_fmac_f32_e32 v29, v116, v28
	v_fmac_f32_e32 v45, v118, v44
	v_fmac_f32_dpp v29, v28, v122 quad_perm:[1,0,3,2] row_mask:0xf bank_mask:0xf
	v_fmac_f32_dpp v45, v44, v123 quad_perm:[1,0,3,2] row_mask:0xf bank_mask:0xf
	v_cvt_pk_bf16_f32 v149, v29, v45
	ds_write_b32 v151, v149 offset:6800
	v_fmac_f32_e32 v30, v116, v29
	v_fmac_f32_e32 v46, v118, v45
	v_fmac_f32_dpp v30, v29, v122 quad_perm:[1,0,3,2] row_mask:0xf bank_mask:0xf
	v_fmac_f32_dpp v46, v45, v123 quad_perm:[1,0,3,2] row_mask:0xf bank_mask:0xf
	v_cvt_pk_bf16_f32 v148, v30, v46
	ds_write_b32 v151, v148 offset:7072
	v_fmac_f32_e32 v31, v116, v30
	v_fmac_f32_e32 v47, v118, v46
	v_fmac_f32_dpp v31, v30, v122 quad_perm:[1,0,3,2] row_mask:0xf bank_mask:0xf
	v_fmac_f32_dpp v47, v46, v123 quad_perm:[1,0,3,2] row_mask:0xf bank_mask:0xf
	v_cvt_pk_bf16_f32 v149, v31, v47
	ds_write_b32 v151, v149 offset:7344
	v_fmac_f32_e32 v60, v116, v31
	v_fmac_f32_e32 v76, v118, v47
	v_fmac_f32_dpp v60, v31, v122 quad_perm:[1,0,3,2] row_mask:0xf bank_mask:0xf
	v_fmac_f32_dpp v76, v47, v123 quad_perm:[1,0,3,2] row_mask:0xf bank_mask:0xf
	v_cvt_pk_bf16_f32 v148, v60, v76
	ds_write_b32 v151, v148 offset:7616
	v_fmac_f32_e32 v61, v116, v60
	v_fmac_f32_e32 v77, v118, v76
	v_fmac_f32_dpp v61, v60, v122 quad_perm:[1,0,3,2] row_mask:0xf bank_mask:0xf
	v_fmac_f32_dpp v77, v76, v123 quad_perm:[1,0,3,2] row_mask:0xf bank_mask:0xf
	v_cvt_pk_bf16_f32 v149, v61, v77
	ds_write_b32 v151, v149 offset:7888
	v_fmac_f32_e32 v62, v116, v61
	v_fmac_f32_e32 v78, v118, v77
	v_fmac_f32_dpp v62, v61, v122 quad_perm:[1,0,3,2] row_mask:0xf bank_mask:0xf
	v_fmac_f32_dpp v78, v77, v123 quad_perm:[1,0,3,2] row_mask:0xf bank_mask:0xf
	v_cvt_pk_bf16_f32 v148, v62, v78
	ds_write_b32 v151, v148 offset:8160
	v_fmac_f32_e32 v63, v116, v62
	v_fmac_f32_e32 v79, v118, v78
	v_fmac_f32_dpp v63, v62, v122 quad_perm:[1,0,3,2] row_mask:0xf bank_mask:0xf
	v_fmac_f32_dpp v79, v78, v123 quad_perm:[1,0,3,2] row_mask:0xf bank_mask:0xf
	v_cvt_pk_bf16_f32 v149, v63, v79
	ds_write_b32 v151, v149 offset:8432
	v_mov_b32_e32 v120, v63
	v_mov_b32_e32 v121, v79
	ds_read_b128 v[124:127], v152
	ds_read_b128 v[128:131], v152 offset:64
	ds_read_b128 v[132:135], v152 offset:128
	ds_read_b128 v[136:139], v152 offset:192
	s_waitcnt lgkmcnt(3)
	v_mfma_f32_16x16x32_bf16 v[140:143], v[100:103], v[124:127], 0
	s_waitcnt lgkmcnt(2)
	v_mfma_f32_16x16x32_bf16 v[140:143], v[104:107], v[128:131], v[140:143]
	s_waitcnt lgkmcnt(1)
	v_mfma_f32_16x16x32_bf16 v[140:143], v[108:111], v[132:135], v[140:143]
	s_waitcnt lgkmcnt(0)
	v_mfma_f32_16x16x32_bf16 v[140:143], v[112:115], v[136:139], v[140:143]
	s_nop 9
	global_store_dwordx4 v153, v[140:143], s[12:13]
	s_nop 1
	ds_read_b128 v[124:127], v152 offset:4352
	ds_read_b128 v[128:131], v152 offset:4416
	ds_read_b128 v[132:135], v152 offset:4480
	ds_read_b128 v[136:139], v152 offset:4544
	s_waitcnt lgkmcnt(3)
	v_mfma_f32_16x16x32_bf16 v[140:143], v[100:103], v[124:127], 0
	s_waitcnt lgkmcnt(2)
	v_mfma_f32_16x16x32_bf16 v[140:143], v[104:107], v[128:131], v[140:143]
	s_waitcnt lgkmcnt(1)
	v_mfma_f32_16x16x32_bf16 v[140:143], v[108:111], v[132:135], v[140:143]
	s_waitcnt lgkmcnt(0)
	v_mfma_f32_16x16x32_bf16 v[140:143], v[112:115], v[136:139], v[140:143]
	s_nop 9
	global_store_dwordx4 v157, v[140:143], s[12:13]
	s_nop 1
	s_add_u32 s12, s12, 131072
	s_addc_u32 s13, s13, 0
	s_add_u32 s14, s14, 2
	s_cmp_lt_u32 s14, 32
	s_cbranch_scc1 .Lssm_tile_d0m0
	s_waitcnt vmcnt(0) lgkmcnt(0)
	s_branch .Lssm_lat_join
.Lssm_lat_bwd:
	s_add_u32 s28, s24, 64
	s_lshl_b32 s29, s28, 13
	s_add_u32 s29, s29, 0x200000
	s_add_u32 s10, s62, s29
	s_addc_u32 s11, s63, 0
	global_load_dwordx4 v[84:87], v177, s[10:11]
	global_load_dwordx4 v[88:91], v177, s[10:11] offset:2048
	s_add_u32 s12, s10, 0x1000
	s_addc_u32 s13, s11, 0
	global_load_dwordx4 v[92:95], v177, s[12:13]
	global_load_dwordx4 v[96:99], v177, s[12:13] offset:2048
	s_lshl_b32 s29, s28, 12
	s_add_u32 s29, s29, 0x300000
	s_add_u32 s16, s62, s29
	s_addc_u32 s17, s63, 0
	global_load_dwordx2 v[2:3], v178, s[16:17]
	global_load_dwordx2 v[4:5], v178, s[16:17] offset:1024
	global_load_dwordx2 v[6:7], v178, s[16:17] offset:512
	global_load_dwordx2 v[8:9], v178, s[16:17] offset:1536
	global_load_dwordx2 v[10:11], v178, s[16:17] offset:2048
	global_load_dwordx2 v[12:13], v178, s[16:17] offset:3072
	global_load_dwordx2 v[14:15], v178, s[16:17] offset:2560
	global_load_dwordx2 v[16:17], v178, s[16:17] offset:3584
	s_lshl_b32 s29, s28, 9
	s_add_u32 s29, s29, 0x100000
	s_add_u32 s18, s62, s29
	s_addc_u32 s19, s63, 0
	global_load_dwordx2 v[116:117], v179, s[18:19]
	global_load_dwordx2 v[118:119], v179, s[18:19] offset:128
	s_lshl_b32 s30, s23, 1
	s_add_u32 s30, s30, 1
	s_lshl_b32 s30, s30, 15
	s_lshl_b32 s31, s24, 8
	s_add_u32 s30, s30, s31
	v_readlane_b32 s34, v254, 10
	v_readlane_b32 s35, v254, 11
	s_nop 3
	s_add_u32 s34, s34, s30
	s_addc_u32 s35, s35, 0
	global_load_dword v120, v180, s[34:35]
	global_load_dword v121, v180, s[34:35] offset:64
	s_mul_i32 s31, s25, 0x1800
	s_lshl_b32 s29, s24, 5
	s_add_u32 s31, s31, s29
	s_add_u32 s31, s31, 0x8801000
	s_add_u32 s4, s62, s31
	s_addc_u32 s5, s63, 0
	s_lshl_b32 s31, s25, 12
	s_lshl_b32 s29, s24, 6
	s_add_u32 s31, s31, s29
	s_add_u32 s31, s31, 0x4000000
	s_add_u32 s6, s60, s31
	s_addc_u32 s7, s61, 0
	s_add_u32 s34, s4, 6094848
	s_addc_u32 s35, s5, 0
	global_load_dwordx4 v[80:83], v150, s[34:35]
	s_mov_b64 s[10:11], s[34:35]
	s_sub_u32 s10, s10, 196608
	s_subb_u32 s11, s11, 0
	global_load_dwordx4 v[144:147], v150, s[10:11]
	s_mov_b64 s[34:35], s[10:11]
	s_sub_u32 s10, s10, 196608
	s_subb_u32 s11, s11, 0
	s_add_u32 s12, s6, 4063232
	s_addc_u32 s13, s7, 0
	s_mov_b32 s14, 0
	s_mov_b32 s40, 0xffff0000
	s_waitcnt vmcnt(0)
	v_and_b32_e32 v182, 0xffff, v2
	v_lshrrev_b32_e32 v183, 16, v2
	v_and_b32_e32 v184, 0xffff, v3
	v_lshrrev_b32_e32 v185, 16, v3
	v_lshl_or_b32 v100, v4, 16, v182
	v_and_or_b32 v101, v4, s40, v183
	v_lshl_or_b32 v102, v5, 16, v184
	v_and_or_b32 v103, v5, s40, v185
	v_and_b32_e32 v182, 0xffff, v6
	v_lshrrev_b32_e32 v183, 16, v6
	v_and_b32_e32 v184, 0xffff, v7
	v_lshrrev_b32_e32 v185, 16, v7
	v_lshl_or_b32 v104, v8, 16, v182
	v_and_or_b32 v105, v8, s40, v183
	v_lshl_or_b32 v106, v9, 16, v184
	v_and_or_b32 v107, v9, s40, v185
	v_and_b32_e32 v182, 0xffff, v10
	v_lshrrev_b32_e32 v183, 16, v10
	v_and_b32_e32 v184, 0xffff, v11
	v_lshrrev_b32_e32 v185, 16, v11
	v_lshl_or_b32 v108, v12, 16, v182
	v_and_or_b32 v109, v12, s40, v183
	v_lshl_or_b32 v110, v13, 16, v184
	v_and_or_b32 v111, v13, s40, v185
	v_and_b32_e32 v182, 0xffff, v14
	v_lshrrev_b32_e32 v183, 16, v14
	v_and_b32_e32 v184, 0xffff, v15
	v_lshrrev_b32_e32 v185, 16, v15
	v_lshl_or_b32 v112, v16, 16, v182
	v_and_or_b32 v113, v16, s40, v183
	v_lshl_or_b32 v114, v17, 16, v184
	v_and_or_b32 v115, v17, s40, v185
	v_cmp_eq_u32_e32 vcc, 1, v174
	v_xor_b32_e32 v182, 0x80000000, v117
	v_xor_b32_e32 v183, 0x80000000, v119
	s_nop 1
	v_cndmask_b32_e32 v122, v182, v117, vcc
	v_cndmask_b32_e32 v123, v183, v119, vcc
.Lssm_tile_d1m0:
	s_waitcnt vmcnt(5)
	v_mfma_f32_32x32x16_bf16 v[16:31], v[80:83], v[84:87], 0
	v_mfma_f32_32x32x16_bf16 v[32:47], v[80:83], v[88:91], 0
	v_mfma_f32_32x32x16_bf16 v[48:63], v[80:83], v[92:95], 0
	v_mfma_f32_32x32x16_bf16 v[64:79], v[80:83], v[96:99], 0
	s_nop 11
	global_load_dwordx4 v[80:83], v150, s[10:11]
	s_sub_u32 s34, s34, 196608
	s_subb_u32 s35, s35, 0
	s_sub_u32 s10, s10, 196608
	s_subb_u32 s11, s11, 0
	v_permlane32_swap_b32_e32 v16, v48
	v_permlane32_swap_b32_e32 v17, v49
	v_permlane32_swap_b32_e32 v18, v50
	v_permlane32_swap_b32_e32 v19, v51
	v_permlane32_swap_b32_e32 v20, v52
	v_permlane32_swap_b32_e32 v21, v53
	v_permlane32_swap_b32_e32 v22, v54
	v_permlane32_swap_b32_e32 v23, v55
	v_permlane32_swap_b32_e32 v24, v56
	v_permlane32_swap_b32_e32 v25, v57
	v_permlane32_swap_b32_e32 v26, v58
	v_permlane32_swap_b32_e32 v27, v59
	v_permlane32_swap_b32_e32 v28, v60
	v_permlane32_swap_b32_e32 v29, v61
	v_permlane32_swap_b32_e32 v30, v62
	v_permlane32_swap_b32_e32 v31, v63
	v_permlane32_swap_b32_e32 v32, v64
	v_permlane32_swap_b32_e32 v33, v65
	v_permlane32_swap_b32_e32 v34, v66
	v_permlane32_swap_b32_e32 v35, v67
	v_permlane32_swap_b32_e32 v36, v68
	v_permlane32_swap_b32_e32 v37, v69
	v_permlane32_swap_b32_e32 v38, v70
	v_permlane32_swap_b32_e32 v39, v71
	v_permlane32_swap_b32_e32 v40, v72
	v_permlane32_swap_b32_e32 v41, v73
	v_permlane32_swap_b32_e32 v42, v74
	v_permlane32_swap_b32_e32 v43, v75
	v_permlane32_swap_b32_e32 v44, v76
	v_permlane32_swap_b32_e32 v45, v77
	v_permlane32_swap_b32_e32 v46, v78
	v_permlane32_swap_b32_e32 v47, v79
	v_fmac_f32_e32 v63, v116, v120
	v_fmac_f32_e32 v79, v118, v121
	v_fmac_f32_dpp v63, v120, v122 quad_perm:[1,0,3,2] row_mask:0xf bank_mask:0xf
	v_fmac_f32_dpp v79, v121, v123 quad_perm:[1,0,3,2] row_mask:0xf bank_mask:0xf
	v_cvt_pk_bf16_f32 v148, v63, v79
	ds_write_b32 v151, v148 offset:8432
	v_fmac_f32_e32 v62, v116, v63
	v_fmac_f32_e32 v78, v118, v79
	v_fmac_f32_dpp v62, v63, v122 quad_perm:[1,0,3,2] row_mask:0xf bank_mask:0xf
	v_fmac_f32_dpp v78, v79, v123 quad_perm:[1,0,3,2] row_mask:0xf bank_mask:0xf
	v_cvt_pk_bf16_f32 v149, v62, v78
	ds_write_b32 v151, v149 offset:8160
	v_fmac_f32_e32 v61, v116, v62
	v_fmac_f32_e32 v77, v118, v78
	v_fmac_f32_dpp v61, v62, v122 quad_perm:[1,0,3,2] row_mask:0xf bank_mask:0xf
	v_fmac_f32_dpp v77, v78, v123 quad_perm:[1,0,3,2] row_mask:0xf bank_mask:0xf
	v_cvt_pk_bf16_f32 v148, v61, v77
	ds_write_b32 v151, v148 offset:7888
	v_fmac_f32_e32 v60, v116, v61
	v_fmac_f32_e32 v76, v118, v77
	v_fmac_f32_dpp v60, v61, v122 quad_perm:[1,0,3,2] row_mask:0xf bank_mask:0xf
	v_fmac_f32_dpp v76, v77, v123 quad_perm:[1,0,3,2] row_mask:0xf bank_mask:0xf
	v_cvt_pk_bf16_f32 v149, v60, v76
	ds_write_b32 v151, v149 offset:7616
	v_fmac_f32_e32 v31, v116, v60
	v_fmac_f32_e32 v47, v118, v76
	v_fmac_f32_dpp v31, v60, v122 quad_perm:[1,0,3,2] row_mask:0xf bank_mask:0xf
	v_fmac_f32_dpp v47, v76, v123 quad_perm:[1,0,3,2] row_mask:0xf bank_mask:0xf
	v_cvt_pk_bf16_f32 v148, v31, v47
	ds_write_b32 v151, v148 offset:7344
	v_fmac_f32_e32 v30, v116, v31
	v_fmac_f32_e32 v46, v118, v47
	v_fmac_f32_dpp v30, v31, v122 quad_perm:[1,0,3,2] row_mask:0xf bank_mask:0xf
	v_fmac_f32_dpp v46, v47, v123 quad_perm:[1,0,3,2] row_mask:0xf bank_mask:0xf
	v_cvt_pk_bf16_f32 v149, v30, v46
	ds_write_b32 v151, v149 offset:7072
	v_fmac_f32_e32 v29, v116, v30
	v_fmac_f32_e32 v45, v118, v46
	v_fmac_f32_dpp v29, v30, v122 quad_perm:[1,0,3,2] row_mask:0xf bank_mask:0xf
	v_fmac_f32_dpp v45, v46, v123 quad_perm:[1,0,3,2] row_mask:0xf bank_mask:0xf
	v_cvt_pk_bf16_f32 v148, v29, v45
	ds_write_b32 v151, v148 offset:6800
	v_fmac_f32_e32 v28, v116, v29
	v_fmac_f32_e32 v44, v118, v45
	v_fmac_f32_dpp v28, v29, v122 quad_perm:[1,0,3,2] row_mask:0xf bank_mask:0xf
	v_fmac_f32_dpp v44, v45, v123 quad_perm:[1,0,3,2] row_mask:0xf bank_mask:0xf
	v_cvt_pk_bf16_f32 v149, v28, v44
	ds_write_b32 v151, v149 offset:6528
	v_fmac_f32_e32 v59, v116, v28
	v_fmac_f32_e32 v75, v118, v44
	v_fmac_f32_dpp v59, v28, v122 quad_perm:[1,0,3,2] row_mask:0xf bank_mask:0xf
	v_fmac_f32_dpp v75, v44, v123 quad_perm:[1,0,3,2] row_mask:0xf bank_mask:0xf
	v_cvt_pk_bf16_f32 v148, v59, v75
	ds_write_b32 v151, v148 offset:6256
	v_fmac_f32_e32 v58, v116, v59
	v_fmac_f32_e32 v74, v118, v75
	v_fmac_f32_dpp v58, v59, v122 quad_perm:[1,0,3,2] row_mask:0xf bank_mask:0xf
	v_fmac_f32_dpp v74, v75, v123 quad_perm:[1,0,3,2] row_mask:0xf bank_mask:0xf
	v_cvt_pk_bf16_f32 v149, v58, v74
	ds_write_b32 v151, v149 offset:5984
	v_fmac_f32_e32 v57, v116, v58
	v_fmac_f32_e32 v73, v118, v74
	v_fmac_f32_dpp v57, v58, v122 quad_perm:[1,0,3,2] row_mask:0xf bank_mask:0xf
	v_fmac_f32_dpp v73, v74, v123 quad_perm:[1,0,3,2] row_mask:0xf bank_mask:0xf
	v_cvt_pk_bf16_f32 v148, v57, v73
	ds_write_b32 v151, v148 offset:5712
	v_fmac_f32_e32 v56, v116, v57
	v_fmac_f32_e32 v72, v118, v73
	v_fmac_f32_dpp v56, v57, v122 quad_perm:[1,0,3,2] row_mask:0xf bank_mask:0xf
	v_fmac_f32_dpp v72, v73, v123 quad_perm:[1,0,3,2] row_mask:0xf bank_mask:0xf
	v_cvt_pk_bf16_f32 v149, v56, v72
	ds_write_b32 v151, v149 offset:5440
	v_fmac_f32_e32 v27, v116, v56
	v_fmac_f32_e32 v43, v118, v72
	v_fmac_f32_dpp v27, v56, v122 quad_perm:[1,0,3,2] row_mask:0xf bank_mask:0xf
	v_fmac_f32_dpp v43, v72, v123 quad_perm:[1,0,3,2] row_mask:0xf bank_mask:0xf
	v_cvt_pk_bf16_f32 v148, v27, v43
	ds_write_b32 v151, v148 offset:5168
	v_fmac_f32_e32 v26, v116, v27
	v_fmac_f32_e32 v42, v118, v43
	v_fmac_f32_dpp v26, v27, v122 quad_perm:[1,0,3,2] row_mask:0xf bank_mask:0xf
	v_fmac_f32_dpp v42, v43, v123 quad_perm:[1,0,3,2] row_mask:0xf bank_mask:0xf
	v_cvt_pk_bf16_f32 v149, v26, v42
	ds_write_b32 v151, v149 offset:4896
	v_fmac_f32_e32 v25, v116, v26
	v_fmac_f32_e32 v41, v118, v42
	v_fmac_f32_dpp v25, v26, v122 quad_perm:[1,0,3,2] row_mask:0xf bank_mask:0xf
	v_fmac_f32_dpp v41, v42, v123 quad_perm:[1,0,3,2] row_mask:0xf bank_mask:0xf
	v_cvt_pk_bf16_f32 v148, v25, v41
	ds_write_b32 v151, v148 offset:4624
	v_fmac_f32_e32 v24, v116, v25
	v_fmac_f32_e32 v40, v118, v41
	v_fmac_f32_dpp v24, v25, v122 quad_perm:[1,0,3,2] row_mask:0xf bank_mask:0xf
	v_fmac_f32_dpp v40, v41, v123 quad_perm:[1,0,3,2] row_mask:0xf bank_mask:0xf
	v_cvt_pk_bf16_f32 v149, v24, v40
	ds_write_b32 v151, v149 offset:4352
	v_fmac_f32_e32 v55, v116, v24
	v_fmac_f32_e32 v71, v118, v40
	v_fmac_f32_dpp v55, v24, v122 quad_perm:[1,0,3,2] row_mask:0xf bank_mask:0xf
	v_fmac_f32_dpp v71, v40, v123 quad_perm:[1,0,3,2] row_mask:0xf bank_mask:0xf
	v_cvt_pk_bf16_f32 v148, v55, v71
	ds_write_b32 v151, v148 offset:4080
	v_fmac_f32_e32 v54, v116, v55
	v_fmac_f32_e32 v70, v118, v71
	v_fmac_f32_dpp v54, v55, v122 quad_perm:[1,0,3,2] row_mask:0xf bank_mask:0xf
	v_fmac_f32_dpp v70, v71, v123 quad_perm:[1,0,3,2] row_mask:0xf bank_mask:0xf
	v_cvt_pk_bf16_f32 v149, v54, v70
	ds_write_b32 v151, v149 offset:3808
	v_fmac_f32_e32 v53, v116, v54
	v_fmac_f32_e32 v69, v118, v70
	v_fmac_f32_dpp v53, v54, v122 quad_perm:[1,0,3,2] row_mask:0xf bank_mask:0xf
	v_fmac_f32_dpp v69, v70, v123 quad_perm:[1,0,3,2] row_mask:0xf bank_mask:0xf
	v_cvt_pk_bf16_f32 v148, v53, v69
	ds_write_b32 v151, v148 offset:3536
	v_fmac_f32_e32 v52, v116, v53
	v_fmac_f32_e32 v68, v118, v69
	v_fmac_f32_dpp v52, v53, v122 quad_perm:[1,0,3,2] row_mask:0xf bank_mask:0xf
	v_fmac_f32_dpp v68, v69, v123 quad_perm:[1,0,3,2] row_mask:0xf bank_mask:0xf
	v_cvt_pk_bf16_f32 v149, v52, v68
	ds_write_b32 v151, v149 offset:3264
	v_fmac_f32_e32 v23, v116, v52
	v_fmac_f32_e32 v39, v118, v68
	v_fmac_f32_dpp v23, v52, v122 quad_perm:[1,0,3,2] row_mask:0xf bank_mask:0xf
	v_fmac_f32_dpp v39, v68, v123 quad_perm:[1,0,3,2] row_mask:0xf bank_mask:0xf
	v_cvt_pk_bf16_f32 v148, v23, v39
	ds_write_b32 v151, v148 offset:2992
	v_fmac_f32_e32 v22, v116, v23
	v_fmac_f32_e32 v38, v118, v39
	v_fmac_f32_dpp v22, v23, v122 quad_perm:[1,0,3,2] row_mask:0xf bank_mask:0xf
	v_fmac_f32_dpp v38, v39, v123 quad_perm:[1,0,3,2] row_mask:0xf bank_mask:0xf
	v_cvt_pk_bf16_f32 v149, v22, v38
	ds_write_b32 v151, v149 offset:2720
	v_fmac_f32_e32 v21, v116, v22
	v_fmac_f32_e32 v37, v118, v38
	v_fmac_f32_dpp v21, v22, v122 quad_perm:[1,0,3,2] row_mask:0xf bank_mask:0xf
	v_fmac_f32_dpp v37, v38, v123 quad_perm:[1,0,3,2] row_mask:0xf bank_mask:0xf
	v_cvt_pk_bf16_f32 v148, v21, v37
	ds_write_b32 v151, v148 offset:2448
	v_fmac_f32_e32 v20, v116, v21
	v_fmac_f32_e32 v36, v118, v37
	v_fmac_f32_dpp v20, v21, v122 quad_perm:[1,0,3,2] row_mask:0xf bank_mask:0xf
	v_fmac_f32_dpp v36, v37, v123 quad_perm:[1,0,3,2] row_mask:0xf bank_mask:0xf
	v_cvt_pk_bf16_f32 v149, v20, v36
	ds_write_b32 v151, v149 offset:2176
	v_fmac_f32_e32 v51, v116, v20
	v_fmac_f32_e32 v67, v118, v36
	v_fmac_f32_dpp v51, v20, v122 quad_perm:[1,0,3,2] row_mask:0xf bank_mask:0xf
	v_fmac_f32_dpp v67, v36, v123 quad_perm:[1,0,3,2] row_mask:0xf bank_mask:0xf
	v_cvt_pk_bf16_f32 v148, v51, v67
	ds_write_b32 v151, v148 offset:1904
	v_fmac_f32_e32 v50, v116, v51
	v_fmac_f32_e32 v66, v118, v67
	v_fmac_f32_dpp v50, v51, v122 quad_perm:[1,0,3,2] row_mask:0xf bank_mask:0xf
	v_fmac_f32_dpp v66, v67, v123 quad_perm:[1,0,3,2] row_mask:0xf bank_mask:0xf
	v_cvt_pk_bf16_f32 v149, v50, v66
	ds_write_b32 v151, v149 offset:1632
	v_fmac_f32_e32 v49, v116, v50
	v_fmac_f32_e32 v65, v118, v66
	v_fmac_f32_dpp v49, v50, v122 quad_perm:[1,0,3,2] row_mask:0xf bank_mask:0xf
	v_fmac_f32_dpp v65, v66, v123 quad_perm:[1,0,3,2] row_mask:0xf bank_mask:0xf
	v_cvt_pk_bf16_f32 v148, v49, v65
	ds_write_b32 v151, v148 offset:1360
	v_fmac_f32_e32 v48, v116, v49
	v_fmac_f32_e32 v64, v118, v65
	v_fmac_f32_dpp v48, v49, v122 quad_perm:[1,0,3,2] row_mask:0xf bank_mask:0xf
	v_fmac_f32_dpp v64, v65, v123 quad_perm:[1,0,3,2] row_mask:0xf bank_mask:0xf
	v_cvt_pk_bf16_f32 v149, v48, v64
	ds_write_b32 v151, v149 offset:1088
	v_fmac_f32_e32 v19, v116, v48
	v_fmac_f32_e32 v35, v118, v64
	v_fmac_f32_dpp v19, v48, v122 quad_perm:[1,0,3,2] row_mask:0xf bank_mask:0xf
	v_fmac_f32_dpp v35, v64, v123 quad_perm:[1,0,3,2] row_mask:0xf bank_mask:0xf
	v_cvt_pk_bf16_f32 v148, v19, v35
	ds_write_b32 v151, v148 offset:816
	v_fmac_f32_e32 v18, v116, v19
	v_fmac_f32_e32 v34, v118, v35
	v_fmac_f32_dpp v18, v19, v122 quad_perm:[1,0,3,2] row_mask:0xf bank_mask:0xf
	v_fmac_f32_dpp v34, v35, v123 quad_perm:[1,0,3,2] row_mask:0xf bank_mask:0xf
	v_cvt_pk_bf16_f32 v149, v18, v34
	ds_write_b32 v151, v149 offset:544
	v_fmac_f32_e32 v17, v116, v18
	v_fmac_f32_e32 v33, v118, v34
	v_fmac_f32_dpp v17, v18, v122 quad_perm:[1,0,3,2] row_mask:0xf bank_mask:0xf
	v_fmac_f32_dpp v33, v34, v123 quad_perm:[1,0,3,2] row_mask:0xf bank_mask:0xf
	v_cvt_pk_bf16_f32 v148, v17, v33
	ds_write_b32 v151, v148 offset:272
	v_fmac_f32_e32 v16, v116, v17
	v_fmac_f32_e32 v32, v118, v33
	v_fmac_f32_dpp v16, v17, v122 quad_perm:[1,0,3,2] row_mask:0xf bank_mask:0xf
	v_fmac_f32_dpp v32, v33, v123 quad_perm:[1,0,3,2] row_mask:0xf bank_mask:0xf
	v_cvt_pk_bf16_f32 v149, v16, v32
	ds_write_b32 v151, v149
	v_mov_b32_e32 v120, v16
	v_mov_b32_e32 v121, v32
	ds_read_b128 v[124:127], v152
	ds_read_b128 v[128:131], v152 offset:64
	ds_read_b128 v[132:135], v152 offset:128
	ds_read_b128 v[136:139], v152 offset:192
	s_waitcnt lgkmcnt(3)
	v_mfma_f32_16x16x32_bf16 v[140:143], v[100:103], v[124:127], 0
	s_waitcnt lgkmcnt(2)
	v_mfma_f32_16x16x32_bf16 v[140:143], v[104:107], v[128:131], v[140:143]
	s_waitcnt lgkmcnt(1)
	v_mfma_f32_16x16x32_bf16 v[140:143], v[108:111], v[132:135], v[140:143]
	s_waitcnt lgkmcnt(0)
	v_mfma_f32_16x16x32_bf16 v[140:143], v[112:115], v[136:139], v[140:143]
	s_nop 9
	global_store_dwordx4 v153, v[140:143], s[12:13]
	s_nop 1
	ds_read_b128 v[124:127], v152 offset:4352
	ds_read_b128 v[128:131], v152 offset:4416
	ds_read_b128 v[132:135], v152 offset:4480
	ds_read_b128 v[136:139], v152 offset:4544
	s_waitcnt lgkmcnt(3)
	v_mfma_f32_16x16x32_bf16 v[140:143], v[100:103], v[124:127], 0
	s_waitcnt lgkmcnt(2)
	v_mfma_f32_16x16x32_bf16 v[140:143], v[104:107], v[128:131], v[140:143]
	s_waitcnt lgkmcnt(1)
	v_mfma_f32_16x16x32_bf16 v[140:143], v[108:111], v[132:135], v[140:143]
	s_waitcnt lgkmcnt(0)
	v_mfma_f32_16x16x32_bf16 v[140:143], v[112:115], v[136:139], v[140:143]
	s_nop 9
	global_store_dwordx4 v157, v[140:143], s[12:13]
	s_nop 1
	s_sub_u32 s12, s12, 131072
	s_subb_u32 s13, s13, 0
	s_waitcnt vmcnt(5)
	v_mfma_f32_32x32x16_bf16 v[16:31], v[144:147], v[84:87], 0
	v_mfma_f32_32x32x16_bf16 v[32:47], v[144:147], v[88:91], 0
	v_mfma_f32_32x32x16_bf16 v[48:63], v[144:147], v[92:95], 0
	v_mfma_f32_32x32x16_bf16 v[64:79], v[144:147], v[96:99], 0
	s_nop 11
	global_load_dwordx4 v[144:147], v150, s[10:11]
	s_sub_u32 s34, s34, 196608
	s_subb_u32 s35, s35, 0
	s_sub_u32 s10, s10, 196608
	s_subb_u32 s11, s11, 0
	v_permlane32_swap_b32_e32 v16, v48
	v_permlane32_swap_b32_e32 v17, v49
	v_permlane32_swap_b32_e32 v18, v50
	v_permlane32_swap_b32_e32 v19, v51
	v_permlane32_swap_b32_e32 v20, v52
	v_permlane32_swap_b32_e32 v21, v53
	v_permlane32_swap_b32_e32 v22, v54
	v_permlane32_swap_b32_e32 v23, v55
	v_permlane32_swap_b32_e32 v24, v56
	v_permlane32_swap_b32_e32 v25, v57
	v_permlane32_swap_b32_e32 v26, v58
	v_permlane32_swap_b32_e32 v27, v59
	v_permlane32_swap_b32_e32 v28, v60
	v_permlane32_swap_b32_e32 v29, v61
	v_permlane32_swap_b32_e32 v30, v62
	v_permlane32_swap_b32_e32 v31, v63
	v_permlane32_swap_b32_e32 v32, v64
	v_permlane32_swap_b32_e32 v33, v65
	v_permlane32_swap_b32_e32 v34, v66
	v_permlane32_swap_b32_e32 v35, v67
	v_permlane32_swap_b32_e32 v36, v68
	v_permlane32_swap_b32_e32 v37, v69
	v_permlane32_swap_b32_e32 v38, v70
	v_permlane32_swap_b32_e32 v39, v71
	v_permlane32_swap_b32_e32 v40, v72
	v_permlane32_swap_b32_e32 v41, v73
	v_permlane32_swap_b32_e32 v42, v74
	v_permlane32_swap_b32_e32 v43, v75
	v_permlane32_swap_b32_e32 v44, v76
	v_permlane32_swap_b32_e32 v45, v77
	v_permlane32_swap_b32_e32 v46, v78
	v_permlane32_swap_b32_e32 v47, v79
	v_fmac_f32_e32 v63, v116, v120
	v_fmac_f32_e32 v79, v118, v121
	v_fmac_f32_dpp v63, v120, v122 quad_perm:[1,0,3,2] row_mask:0xf bank_mask:0xf
	v_fmac_f32_dpp v79, v121, v123 quad_perm:[1,0,3,2] row_mask:0xf bank_mask:0xf
	v_cvt_pk_bf16_f32 v148, v63, v79
	ds_write_b32 v151, v148 offset:8432
	v_fmac_f32_e32 v62, v116, v63
	v_fmac_f32_e32 v78, v118, v79
	v_fmac_f32_dpp v62, v63, v122 quad_perm:[1,0,3,2] row_mask:0xf bank_mask:0xf
	v_fmac_f32_dpp v78, v79, v123 quad_perm:[1,0,3,2] row_mask:0xf bank_mask:0xf
	v_cvt_pk_bf16_f32 v149, v62, v78
	ds_write_b32 v151, v149 offset:8160
	v_fmac_f32_e32 v61, v116, v62
	v_fmac_f32_e32 v77, v118, v78
	v_fmac_f32_dpp v61, v62, v122 quad_perm:[1,0,3,2] row_mask:0xf bank_mask:0xf
	v_fmac_f32_dpp v77, v78, v123 quad_perm:[1,0,3,2] row_mask:0xf bank_mask:0xf
	v_cvt_pk_bf16_f32 v148, v61, v77
	ds_write_b32 v151, v148 offset:7888
	v_fmac_f32_e32 v60, v116, v61
	v_fmac_f32_e32 v76, v118, v77
	v_fmac_f32_dpp v60, v61, v122 quad_perm:[1,0,3,2] row_mask:0xf bank_mask:0xf
	v_fmac_f32_dpp v76, v77, v123 quad_perm:[1,0,3,2] row_mask:0xf bank_mask:0xf
	v_cvt_pk_bf16_f32 v149, v60, v76
	ds_write_b32 v151, v149 offset:7616
	v_fmac_f32_e32 v31, v116, v60
	v_fmac_f32_e32 v47, v118, v76
	v_fmac_f32_dpp v31, v60, v122 quad_perm:[1,0,3,2] row_mask:0xf bank_mask:0xf
	v_fmac_f32_dpp v47, v76, v123 quad_perm:[1,0,3,2] row_mask:0xf bank_mask:0xf
	v_cvt_pk_bf16_f32 v148, v31, v47
	ds_write_b32 v151, v148 offset:7344
	v_fmac_f32_e32 v30, v116, v31
	v_fmac_f32_e32 v46, v118, v47
	v_fmac_f32_dpp v30, v31, v122 quad_perm:[1,0,3,2] row_mask:0xf bank_mask:0xf
	v_fmac_f32_dpp v46, v47, v123 quad_perm:[1,0,3,2] row_mask:0xf bank_mask:0xf
	v_cvt_pk_bf16_f32 v149, v30, v46
	ds_write_b32 v151, v149 offset:7072
	v_fmac_f32_e32 v29, v116, v30
	v_fmac_f32_e32 v45, v118, v46
	v_fmac_f32_dpp v29, v30, v122 quad_perm:[1,0,3,2] row_mask:0xf bank_mask:0xf
	v_fmac_f32_dpp v45, v46, v123 quad_perm:[1,0,3,2] row_mask:0xf bank_mask:0xf
	v_cvt_pk_bf16_f32 v148, v29, v45
	ds_write_b32 v151, v148 offset:6800
	v_fmac_f32_e32 v28, v116, v29
	v_fmac_f32_e32 v44, v118, v45
	v_fmac_f32_dpp v28, v29, v122 quad_perm:[1,0,3,2] row_mask:0xf bank_mask:0xf
	v_fmac_f32_dpp v44, v45, v123 quad_perm:[1,0,3,2] row_mask:0xf bank_mask:0xf
	v_cvt_pk_bf16_f32 v149, v28, v44
	ds_write_b32 v151, v149 offset:6528
	v_fmac_f32_e32 v59, v116, v28
	v_fmac_f32_e32 v75, v118, v44
	v_fmac_f32_dpp v59, v28, v122 quad_perm:[1,0,3,2] row_mask:0xf bank_mask:0xf
	v_fmac_f32_dpp v75, v44, v123 quad_perm:[1,0,3,2] row_mask:0xf bank_mask:0xf
	v_cvt_pk_bf16_f32 v148, v59, v75
	ds_write_b32 v151, v148 offset:6256
	v_fmac_f32_e32 v58, v116, v59
	v_fmac_f32_e32 v74, v118, v75
	v_fmac_f32_dpp v58, v59, v122 quad_perm:[1,0,3,2] row_mask:0xf bank_mask:0xf
	v_fmac_f32_dpp v74, v75, v123 quad_perm:[1,0,3,2] row_mask:0xf bank_mask:0xf
	v_cvt_pk_bf16_f32 v149, v58, v74
	ds_write_b32 v151, v149 offset:5984
	v_fmac_f32_e32 v57, v116, v58
	v_fmac_f32_e32 v73, v118, v74
	v_fmac_f32_dpp v57, v58, v122 quad_perm:[1,0,3,2] row_mask:0xf bank_mask:0xf
	v_fmac_f32_dpp v73, v74, v123 quad_perm:[1,0,3,2] row_mask:0xf bank_mask:0xf
	v_cvt_pk_bf16_f32 v148, v57, v73
	ds_write_b32 v151, v148 offset:5712
	v_fmac_f32_e32 v56, v116, v57
	v_fmac_f32_e32 v72, v118, v73
	v_fmac_f32_dpp v56, v57, v122 quad_perm:[1,0,3,2] row_mask:0xf bank_mask:0xf
	v_fmac_f32_dpp v72, v73, v123 quad_perm:[1,0,3,2] row_mask:0xf bank_mask:0xf
	v_cvt_pk_bf16_f32 v149, v56, v72
	ds_write_b32 v151, v149 offset:5440
	v_fmac_f32_e32 v27, v116, v56
	v_fmac_f32_e32 v43, v118, v72
	v_fmac_f32_dpp v27, v56, v122 quad_perm:[1,0,3,2] row_mask:0xf bank_mask:0xf
	v_fmac_f32_dpp v43, v72, v123 quad_perm:[1,0,3,2] row_mask:0xf bank_mask:0xf
	v_cvt_pk_bf16_f32 v148, v27, v43
	ds_write_b32 v151, v148 offset:5168
	v_fmac_f32_e32 v26, v116, v27
	v_fmac_f32_e32 v42, v118, v43
	v_fmac_f32_dpp v26, v27, v122 quad_perm:[1,0,3,2] row_mask:0xf bank_mask:0xf
	v_fmac_f32_dpp v42, v43, v123 quad_perm:[1,0,3,2] row_mask:0xf bank_mask:0xf
	v_cvt_pk_bf16_f32 v149, v26, v42
	ds_write_b32 v151, v149 offset:4896
	v_fmac_f32_e32 v25, v116, v26
	v_fmac_f32_e32 v41, v118, v42
	v_fmac_f32_dpp v25, v26, v122 quad_perm:[1,0,3,2] row_mask:0xf bank_mask:0xf
	v_fmac_f32_dpp v41, v42, v123 quad_perm:[1,0,3,2] row_mask:0xf bank_mask:0xf
	v_cvt_pk_bf16_f32 v148, v25, v41
	ds_write_b32 v151, v148 offset:4624
	v_fmac_f32_e32 v24, v116, v25
	v_fmac_f32_e32 v40, v118, v41
	v_fmac_f32_dpp v24, v25, v122 quad_perm:[1,0,3,2] row_mask:0xf bank_mask:0xf
	v_fmac_f32_dpp v40, v41, v123 quad_perm:[1,0,3,2] row_mask:0xf bank_mask:0xf
	v_cvt_pk_bf16_f32 v149, v24, v40
	ds_write_b32 v151, v149 offset:4352
	v_fmac_f32_e32 v55, v116, v24
	v_fmac_f32_e32 v71, v118, v40
	v_fmac_f32_dpp v55, v24, v122 quad_perm:[1,0,3,2] row_mask:0xf bank_mask:0xf
	v_fmac_f32_dpp v71, v40, v123 quad_perm:[1,0,3,2] row_mask:0xf bank_mask:0xf
	v_cvt_pk_bf16_f32 v148, v55, v71
	ds_write_b32 v151, v148 offset:4080
	v_fmac_f32_e32 v54, v116, v55
	v_fmac_f32_e32 v70, v118, v71
	v_fmac_f32_dpp v54, v55, v122 quad_perm:[1,0,3,2] row_mask:0xf bank_mask:0xf
	v_fmac_f32_dpp v70, v71, v123 quad_perm:[1,0,3,2] row_mask:0xf bank_mask:0xf
	v_cvt_pk_bf16_f32 v149, v54, v70
	ds_write_b32 v151, v149 offset:3808
	v_fmac_f32_e32 v53, v116, v54
	v_fmac_f32_e32 v69, v118, v70
	v_fmac_f32_dpp v53, v54, v122 quad_perm:[1,0,3,2] row_mask:0xf bank_mask:0xf
	v_fmac_f32_dpp v69, v70, v123 quad_perm:[1,0,3,2] row_mask:0xf bank_mask:0xf
	v_cvt_pk_bf16_f32 v148, v53, v69
	ds_write_b32 v151, v148 offset:3536
	v_fmac_f32_e32 v52, v116, v53
	v_fmac_f32_e32 v68, v118, v69
	v_fmac_f32_dpp v52, v53, v122 quad_perm:[1,0,3,2] row_mask:0xf bank_mask:0xf
	v_fmac_f32_dpp v68, v69, v123 quad_perm:[1,0,3,2] row_mask:0xf bank_mask:0xf
	v_cvt_pk_bf16_f32 v149, v52, v68
	ds_write_b32 v151, v149 offset:3264
	v_fmac_f32_e32 v23, v116, v52
	v_fmac_f32_e32 v39, v118, v68
	v_fmac_f32_dpp v23, v52, v122 quad_perm:[1,0,3,2] row_mask:0xf bank_mask:0xf
	v_fmac_f32_dpp v39, v68, v123 quad_perm:[1,0,3,2] row_mask:0xf bank_mask:0xf
	v_cvt_pk_bf16_f32 v148, v23, v39
	ds_write_b32 v151, v148 offset:2992
	v_fmac_f32_e32 v22, v116, v23
	v_fmac_f32_e32 v38, v118, v39
	v_fmac_f32_dpp v22, v23, v122 quad_perm:[1,0,3,2] row_mask:0xf bank_mask:0xf
	v_fmac_f32_dpp v38, v39, v123 quad_perm:[1,0,3,2] row_mask:0xf bank_mask:0xf
	v_cvt_pk_bf16_f32 v149, v22, v38
	ds_write_b32 v151, v149 offset:2720
	v_fmac_f32_e32 v21, v116, v22
	v_fmac_f32_e32 v37, v118, v38
	v_fmac_f32_dpp v21, v22, v122 quad_perm:[1,0,3,2] row_mask:0xf bank_mask:0xf
	v_fmac_f32_dpp v37, v38, v123 quad_perm:[1,0,3,2] row_mask:0xf bank_mask:0xf
	v_cvt_pk_bf16_f32 v148, v21, v37
	ds_write_b32 v151, v148 offset:2448
	v_fmac_f32_e32 v20, v116, v21
	v_fmac_f32_e32 v36, v118, v37
	v_fmac_f32_dpp v20, v21, v122 quad_perm:[1,0,3,2] row_mask:0xf bank_mask:0xf
	v_fmac_f32_dpp v36, v37, v123 quad_perm:[1,0,3,2] row_mask:0xf bank_mask:0xf
	v_cvt_pk_bf16_f32 v149, v20, v36
	ds_write_b32 v151, v149 offset:2176
	v_fmac_f32_e32 v51, v116, v20
	v_fmac_f32_e32 v67, v118, v36
	v_fmac_f32_dpp v51, v20, v122 quad_perm:[1,0,3,2] row_mask:0xf bank_mask:0xf
	v_fmac_f32_dpp v67, v36, v123 quad_perm:[1,0,3,2] row_mask:0xf bank_mask:0xf
	v_cvt_pk_bf16_f32 v148, v51, v67
	ds_write_b32 v151, v148 offset:1904
	v_fmac_f32_e32 v50, v116, v51
	v_fmac_f32_e32 v66, v118, v67
	v_fmac_f32_dpp v50, v51, v122 quad_perm:[1,0,3,2] row_mask:0xf bank_mask:0xf
	v_fmac_f32_dpp v66, v67, v123 quad_perm:[1,0,3,2] row_mask:0xf bank_mask:0xf
	v_cvt_pk_bf16_f32 v149, v50, v66
	ds_write_b32 v151, v149 offset:1632
	v_fmac_f32_e32 v49, v116, v50
	v_fmac_f32_e32 v65, v118, v66
	v_fmac_f32_dpp v49, v50, v122 quad_perm:[1,0,3,2] row_mask:0xf bank_mask:0xf
	v_fmac_f32_dpp v65, v66, v123 quad_perm:[1,0,3,2] row_mask:0xf bank_mask:0xf
	v_cvt_pk_bf16_f32 v148, v49, v65
	ds_write_b32 v151, v148 offset:1360
	v_fmac_f32_e32 v48, v116, v49
	v_fmac_f32_e32 v64, v118, v65
	v_fmac_f32_dpp v48, v49, v122 quad_perm:[1,0,3,2] row_mask:0xf bank_mask:0xf
	v_fmac_f32_dpp v64, v65, v123 quad_perm:[1,0,3,2] row_mask:0xf bank_mask:0xf
	v_cvt_pk_bf16_f32 v149, v48, v64
	ds_write_b32 v151, v149 offset:1088
	v_fmac_f32_e32 v19, v116, v48
	v_fmac_f32_e32 v35, v118, v64
	v_fmac_f32_dpp v19, v48, v122 quad_perm:[1,0,3,2] row_mask:0xf bank_mask:0xf
	v_fmac_f32_dpp v35, v64, v123 quad_perm:[1,0,3,2] row_mask:0xf bank_mask:0xf
	v_cvt_pk_bf16_f32 v148, v19, v35
	ds_write_b32 v151, v148 offset:816
	v_fmac_f32_e32 v18, v116, v19
	v_fmac_f32_e32 v34, v118, v35
	v_fmac_f32_dpp v18, v19, v122 quad_perm:[1,0,3,2] row_mask:0xf bank_mask:0xf
	v_fmac_f32_dpp v34, v35, v123 quad_perm:[1,0,3,2] row_mask:0xf bank_mask:0xf
	v_cvt_pk_bf16_f32 v149, v18, v34
	ds_write_b32 v151, v149 offset:544
	v_fmac_f32_e32 v17, v116, v18
	v_fmac_f32_e32 v33, v118, v34
	v_fmac_f32_dpp v17, v18, v122 quad_perm:[1,0,3,2] row_mask:0xf bank_mask:0xf
	v_fmac_f32_dpp v33, v34, v123 quad_perm:[1,0,3,2] row_mask:0xf bank_mask:0xf
	v_cvt_pk_bf16_f32 v148, v17, v33
	ds_write_b32 v151, v148 offset:272
	v_fmac_f32_e32 v16, v116, v17
	v_fmac_f32_e32 v32, v118, v33
	v_fmac_f32_dpp v16, v17, v122 quad_perm:[1,0,3,2] row_mask:0xf bank_mask:0xf
	v_fmac_f32_dpp v32, v33, v123 quad_perm:[1,0,3,2] row_mask:0xf bank_mask:0xf
	v_cvt_pk_bf16_f32 v149, v16, v32
	ds_write_b32 v151, v149
	v_mov_b32_e32 v120, v16
	v_mov_b32_e32 v121, v32
	ds_read_b128 v[124:127], v152
	ds_read_b128 v[128:131], v152 offset:64
	ds_read_b128 v[132:135], v152 offset:128
	ds_read_b128 v[136:139], v152 offset:192
	s_waitcnt lgkmcnt(3)
	v_mfma_f32_16x16x32_bf16 v[140:143], v[100:103], v[124:127], 0
	s_waitcnt lgkmcnt(2)
	v_mfma_f32_16x16x32_bf16 v[140:143], v[104:107], v[128:131], v[140:143]
	s_waitcnt lgkmcnt(1)
	v_mfma_f32_16x16x32_bf16 v[140:143], v[108:111], v[132:135], v[140:143]
	s_waitcnt lgkmcnt(0)
	v_mfma_f32_16x16x32_bf16 v[140:143], v[112:115], v[136:139], v[140:143]
	s_nop 9
	global_store_dwordx4 v153, v[140:143], s[12:13]
	s_nop 1
	ds_read_b128 v[124:127], v152 offset:4352
	ds_read_b128 v[128:131], v152 offset:4416
	ds_read_b128 v[132:135], v152 offset:4480
	ds_read_b128 v[136:139], v152 offset:4544
	s_waitcnt lgkmcnt(3)
	v_mfma_f32_16x16x32_bf16 v[140:143], v[100:103], v[124:127], 0
	s_waitcnt lgkmcnt(2)
	v_mfma_f32_16x16x32_bf16 v[140:143], v[104:107], v[128:131], v[140:143]
	s_waitcnt lgkmcnt(1)
	v_mfma_f32_16x16x32_bf16 v[140:143], v[108:111], v[132:135], v[140:143]
	s_waitcnt lgkmcnt(0)
	v_mfma_f32_16x16x32_bf16 v[140:143], v[112:115], v[136:139], v[140:143]
	s_nop 9
	global_store_dwordx4 v157, v[140:143], s[12:13]
	s_nop 1
	s_sub_u32 s12, s12, 131072
	s_subb_u32 s13, s13, 0
	s_add_u32 s14, s14, 2
	s_cmp_lt_u32 s14, 32
	s_cbranch_scc1 .Lssm_tile_d1m0
	s_waitcnt vmcnt(0) lgkmcnt(0)
.Lssm_lat_join:
	s_lshr_b32 s21, s89, 1
	s_lshl_b32 s21, s21, 2
	s_add_u32 s37, s21, 0x21000
	v_mov_b32_e32 v2, s37
	v_mov_b32_e32 v3, 1
	v_cmp_eq_u32_e32 vcc, 0, v191
	s_and_saveexec_b64 s[0:1], vcc
	ds_add_u32 v2, v3
	s_mov_b64 exec, s[0:1]
	s_waitcnt lgkmcnt(0)
	s_mov_b32 s38, 0
.Lssm_spin:
	ds_read_b32 v3, v2
	s_waitcnt lgkmcnt(0)
	v_readfirstlane_b32 s39, v3
	s_nop 3
	s_cmp_ge_u32 s39, 2
	s_cbranch_scc1 .Lssm_spin_done
	s_sleep 4
	s_add_u32 s38, s38, 1
	s_cmp_lt_u32 s38, 0x100000
	s_cbranch_scc1 .Lssm_spin
.Lssm_spin_done:
	s_and_b32 s26, s89, 1
	s_lshl_b32 s26, s26, 9
	s_add_u32 s26, s26, s25
	v_lshrrev_b32_e32 v182, 2, v191
	v_and_b32_e32 v183, 3, v191
	v_lshlrev_b32_e32 v184, 12, v182
	v_lshl_add_u32 v184, v183, 4, v184
	v_mul_u32_u24_e32 v185, 0x1800, v182
	v_lshl_add_u32 v185, v183, 3, v185
	v_lshlrev_b32_e32 v186, 11, v182
	v_lshl_add_u32 v186, v183, 3, v186
	v_lshlrev_b32_e32 v187, 4, v183
	s_lshl_b32 s31, s26, 12
	s_lshl_b32 s29, s24, 6
	s_add_u32 s31, s31, s29
	s_add_u32 s4, s60, s31
	s_addc_u32 s5, s61, 0
	s_add_u32 s6, s4, 0x4000000
	s_addc_u32 s7, s5, 0
	s_mul_i32 s31, s26, 0x1800
	s_lshl_b32 s29, s24, 5
	s_add_u32 s31, s31, s29
	s_add_u32 s31, s31, 0x8801000
	s_add_u32 s10, s62, s31
	s_addc_u32 s11, s63, 0
	s_lshl_b32 s31, s26, 11
	s_add_u32 s31, s31, s29
	s_add_u32 s31, s31, 0x14800000
	s_add_u32 s12, s62, s31
	s_addc_u32 s13, s63, 0
	v_readlane_b32 s16, v254, 28
	v_readlane_b32 s17, v254, 29
	s_nop 3
	s_lshl_b32 s31, s24, 6
	s_add_u32 s16, s16, s31
	s_addc_u32 s17, s17, 0
	s_nop 1
	global_load_dwordx4 v[164:167], v187, s[16:17]
	s_mov_b32 s14, 0
.Lssm_comb:
	global_load_dwordx4 v[16:19], v184, s[4:5]
	global_load_dwordx4 v[48:51], v184, s[6:7]
	global_load_dwordx2 v[80:81], v185, s[10:11]
	s_add_u32 s4, s4, 0x10000
	s_addc_u32 s5, s5, 0
	s_add_u32 s6, s6, 0x10000
	s_addc_u32 s7, s7, 0
	s_add_u32 s10, s10, 0x18000
	s_addc_u32 s11, s11, 0
	global_load_dwordx4 v[20:23], v184, s[4:5]
	global_load_dwordx4 v[52:55], v184, s[6:7]
	global_load_dwordx2 v[82:83], v185, s[10:11]
	s_add_u32 s4, s4, 0x10000
	s_addc_u32 s5, s5, 0
	s_add_u32 s6, s6, 0x10000
	s_addc_u32 s7, s7, 0
	s_add_u32 s10, s10, 0x18000
	s_addc_u32 s11, s11, 0
	global_load_dwordx4 v[24:27], v184, s[4:5]
	global_load_dwordx4 v[56:59], v184, s[6:7]
	global_load_dwordx2 v[84:85], v185, s[10:11]
	s_add_u32 s4, s4, 0x10000
	s_addc_u32 s5, s5, 0
	s_add_u32 s6, s6, 0x10000
	s_addc_u32 s7, s7, 0
	s_add_u32 s10, s10, 0x18000
	s_addc_u32 s11, s11, 0
	global_load_dwordx4 v[28:31], v184, s[4:5]
	global_load_dwordx4 v[60:63], v184, s[6:7]
	global_load_dwordx2 v[86:87], v185, s[10:11]
	s_add_u32 s4, s4, 0x10000
	s_addc_u32 s5, s5, 0
	s_add_u32 s6, s6, 0x10000
	s_addc_u32 s7, s7, 0
	s_add_u32 s10, s10, 0x18000
	s_addc_u32 s11, s11, 0
	global_load_dwordx4 v[32:35], v184, s[4:5]
	global_load_dwordx4 v[64:67], v184, s[6:7]
	global_load_dwordx2 v[88:89], v185, s[10:11]
	s_add_u32 s4, s4, 0x10000
	s_addc_u32 s5, s5, 0
	s_add_u32 s6, s6, 0x10000
	s_addc_u32 s7, s7, 0
	s_add_u32 s10, s10, 0x18000
	s_addc_u32 s11, s11, 0
	global_load_dwordx4 v[36:39], v184, s[4:5]
	global_load_dwordx4 v[68:71], v184, s[6:7]
	global_load_dwordx2 v[90:91], v185, s[10:11]
	s_add_u32 s4, s4, 0x10000
	s_addc_u32 s5, s5, 0
	s_add_u32 s6, s6, 0x10000
	s_addc_u32 s7, s7, 0
	s_add_u32 s10, s10, 0x18000
	s_addc_u32 s11, s11, 0
	global_load_dwordx4 v[40:43], v184, s[4:5]
	global_load_dwordx4 v[72:75], v184, s[6:7]
	global_load_dwordx2 v[92:93], v185, s[10:11]
	s_add_u32 s4, s4, 0x10000
	s_addc_u32 s5, s5, 0
	s_add_u32 s6, s6, 0x10000
	s_addc_u32 s7, s7, 0
	s_add_u32 s10, s10, 0x18000
	s_addc_u32 s11, s11, 0
	global_load_dwordx4 v[44:47], v184, s[4:5]
	global_load_dwordx4 v[76:79], v184, s[6:7]
	global_load_dwordx2 v[94:95], v185, s[10:11]
	s_add_u32 s4, s4, 0x10000
	s_addc_u32 s5, s5, 0
	s_add_u32 s6, s6, 0x10000
	s_addc_u32 s7, s7, 0
	s_add_u32 s10, s10, 0x18000
	s_addc_u32 s11, s11, 0
	s_waitcnt vmcnt(21)
	v_lshlrev_b32_e32 v100, 16, v80
	v_and_b32_e32 v101, 0xffff0000, v80
	v_lshlrev_b32_e32 v102, 16, v81
	v_and_b32_e32 v103, 0xffff0000, v81
	v_add_f32_e32 v16, v16, v48
	v_add_f32_e32 v17, v17, v49
	v_add_f32_e32 v18, v18, v50
	v_add_f32_e32 v19, v19, v51
	v_fmac_f32_e32 v16, v164, v100
	v_fmac_f32_e32 v17, v165, v101
	v_fmac_f32_e32 v18, v166, v102
	v_fmac_f32_e32 v19, v167, v103
	v_mul_f32_e32 v104, 0x3d372713, v16
	v_mul_f32_e32 v105, 0x3d372713, v17
	v_mul_f32_e32 v106, 0x3d372713, v18
	v_mul_f32_e32 v107, 0x3d372713, v19
	v_mul_f32_e32 v104, v16, v104
	v_mul_f32_e32 v105, v17, v105
	v_mul_f32_e32 v106, v18, v106
	v_mul_f32_e32 v107, v19, v107
	v_fma_f32 v104, v16, v104, v16
	v_fma_f32 v105, v17, v105, v17
	v_fma_f32 v106, v18, v106, v18
	v_fma_f32 v107, v19, v107, v19
	v_mul_f32_e32 v104, 0xbfcc422a, v104
	v_mul_f32_e32 v105, 0xbfcc422a, v105
	v_mul_f32_e32 v106, 0xbfcc422a, v106
	v_mul_f32_e32 v107, 0xbfcc422a, v107
	v_mul_f32_e32 v104, 0x3fb8aa3b, v104
	v_mul_f32_e32 v105, 0x3fb8aa3b, v105
	v_mul_f32_e32 v106, 0x3fb8aa3b, v106
	v_mul_f32_e32 v107, 0x3fb8aa3b, v107
	v_exp_f32_e32 v104, v104
	v_exp_f32_e32 v105, v105
	v_exp_f32_e32 v106, v106
	v_exp_f32_e32 v107, v107
	v_add_f32_e32 v104, 1.0, v104
	v_add_f32_e32 v105, 1.0, v105
	v_add_f32_e32 v106, 1.0, v106
	v_add_f32_e32 v107, 1.0, v107
	v_rcp_f32_e32 v104, v104
	v_rcp_f32_e32 v105, v105
	v_rcp_f32_e32 v106, v106
	v_rcp_f32_e32 v107, v107
	v_mul_f32_e32 v16, v16, v104
	v_mul_f32_e32 v17, v17, v105
	v_mul_f32_e32 v18, v18, v106
	v_mul_f32_e32 v19, v19, v107
	v_cvt_pk_bf16_f32 v108, v16, v17
	v_cvt_pk_bf16_f32 v109, v18, v19
	global_store_dwordx2 v186, v[108:109], s[12:13]
	s_add_u32 s12, s12, 0x8000
	s_addc_u32 s13, s13, 0
	s_waitcnt vmcnt(19)
	v_lshlrev_b32_e32 v100, 16, v82
	v_and_b32_e32 v101, 0xffff0000, v82
	v_lshlrev_b32_e32 v102, 16, v83
	v_and_b32_e32 v103, 0xffff0000, v83
	v_add_f32_e32 v20, v20, v52
	v_add_f32_e32 v21, v21, v53
	v_add_f32_e32 v22, v22, v54
	v_add_f32_e32 v23, v23, v55
	v_fmac_f32_e32 v20, v164, v100
	v_fmac_f32_e32 v21, v165, v101
	v_fmac_f32_e32 v22, v166, v102
	v_fmac_f32_e32 v23, v167, v103
	v_mul_f32_e32 v104, 0x3d372713, v20
	v_mul_f32_e32 v105, 0x3d372713, v21
	v_mul_f32_e32 v106, 0x3d372713, v22
	v_mul_f32_e32 v107, 0x3d372713, v23
	v_mul_f32_e32 v104, v20, v104
	v_mul_f32_e32 v105, v21, v105
	v_mul_f32_e32 v106, v22, v106
	v_mul_f32_e32 v107, v23, v107
	v_fma_f32 v104, v20, v104, v20
	v_fma_f32 v105, v21, v105, v21
	v_fma_f32 v106, v22, v106, v22
	v_fma_f32 v107, v23, v107, v23
	v_mul_f32_e32 v104, 0xbfcc422a, v104
	v_mul_f32_e32 v105, 0xbfcc422a, v105
	v_mul_f32_e32 v106, 0xbfcc422a, v106
	v_mul_f32_e32 v107, 0xbfcc422a, v107
	v_mul_f32_e32 v104, 0x3fb8aa3b, v104
	v_mul_f32_e32 v105, 0x3fb8aa3b, v105
	v_mul_f32_e32 v106, 0x3fb8aa3b, v106
	v_mul_f32_e32 v107, 0x3fb8aa3b, v107
	v_exp_f32_e32 v104, v104
	v_exp_f32_e32 v105, v105
	v_exp_f32_e32 v106, v106
	v_exp_f32_e32 v107, v107
	v_add_f32_e32 v104, 1.0, v104
	v_add_f32_e32 v105, 1.0, v105
	v_add_f32_e32 v106, 1.0, v106
	v_add_f32_e32 v107, 1.0, v107
	v_rcp_f32_e32 v104, v104
	v_rcp_f32_e32 v105, v105
	v_rcp_f32_e32 v106, v106
	v_rcp_f32_e32 v107, v107
	v_mul_f32_e32 v20, v20, v104
	v_mul_f32_e32 v21, v21, v105
	v_mul_f32_e32 v22, v22, v106
	v_mul_f32_e32 v23, v23, v107
	v_cvt_pk_bf16_f32 v110, v20, v21
	v_cvt_pk_bf16_f32 v111, v22, v23
	global_store_dwordx2 v186, v[110:111], s[12:13]
	s_add_u32 s12, s12, 0x8000
	s_addc_u32 s13, s13, 0
	s_waitcnt vmcnt(17)
	v_lshlrev_b32_e32 v100, 16, v84
	v_and_b32_e32 v101, 0xffff0000, v84
	v_lshlrev_b32_e32 v102, 16, v85
	v_and_b32_e32 v103, 0xffff0000, v85
	v_add_f32_e32 v24, v24, v56
	v_add_f32_e32 v25, v25, v57
	v_add_f32_e32 v26, v26, v58
	v_add_f32_e32 v27, v27, v59
	v_fmac_f32_e32 v24, v164, v100
	v_fmac_f32_e32 v25, v165, v101
	v_fmac_f32_e32 v26, v166, v102
	v_fmac_f32_e32 v27, v167, v103
	v_mul_f32_e32 v104, 0x3d372713, v24
	v_mul_f32_e32 v105, 0x3d372713, v25
	v_mul_f32_e32 v106, 0x3d372713, v26
	v_mul_f32_e32 v107, 0x3d372713, v27
	v_mul_f32_e32 v104, v24, v104
	v_mul_f32_e32 v105, v25, v105
	v_mul_f32_e32 v106, v26, v106
	v_mul_f32_e32 v107, v27, v107
	v_fma_f32 v104, v24, v104, v24
	v_fma_f32 v105, v25, v105, v25
	v_fma_f32 v106, v26, v106, v26
	v_fma_f32 v107, v27, v107, v27
	v_mul_f32_e32 v104, 0xbfcc422a, v104
	v_mul_f32_e32 v105, 0xbfcc422a, v105
	v_mul_f32_e32 v106, 0xbfcc422a, v106
	v_mul_f32_e32 v107, 0xbfcc422a, v107
	v_mul_f32_e32 v104, 0x3fb8aa3b, v104
	v_mul_f32_e32 v105, 0x3fb8aa3b, v105
	v_mul_f32_e32 v106, 0x3fb8aa3b, v106
	v_mul_f32_e32 v107, 0x3fb8aa3b, v107
	v_exp_f32_e32 v104, v104
	v_exp_f32_e32 v105, v105
	v_exp_f32_e32 v106, v106
	v_exp_f32_e32 v107, v107
	v_add_f32_e32 v104, 1.0, v104
	v_add_f32_e32 v105, 1.0, v105
	v_add_f32_e32 v106, 1.0, v106
	v_add_f32_e32 v107, 1.0, v107
	v_rcp_f32_e32 v104, v104
	v_rcp_f32_e32 v105, v105
	v_rcp_f32_e32 v106, v106
	v_rcp_f32_e32 v107, v107
	v_mul_f32_e32 v24, v24, v104
	v_mul_f32_e32 v25, v25, v105
	v_mul_f32_e32 v26, v26, v106
	v_mul_f32_e32 v27, v27, v107
	v_cvt_pk_bf16_f32 v108, v24, v25
	v_cvt_pk_bf16_f32 v109, v26, v27
	global_store_dwordx2 v186, v[108:109], s[12:13]
	s_add_u32 s12, s12, 0x8000
	s_addc_u32 s13, s13, 0
	s_waitcnt vmcnt(15)
	v_lshlrev_b32_e32 v100, 16, v86
	v_and_b32_e32 v101, 0xffff0000, v86
	v_lshlrev_b32_e32 v102, 16, v87
	v_and_b32_e32 v103, 0xffff0000, v87
	v_add_f32_e32 v28, v28, v60
	v_add_f32_e32 v29, v29, v61
	v_add_f32_e32 v30, v30, v62
	v_add_f32_e32 v31, v31, v63
	v_fmac_f32_e32 v28, v164, v100
	v_fmac_f32_e32 v29, v165, v101
	v_fmac_f32_e32 v30, v166, v102
	v_fmac_f32_e32 v31, v167, v103
	v_mul_f32_e32 v104, 0x3d372713, v28
	v_mul_f32_e32 v105, 0x3d372713, v29
	v_mul_f32_e32 v106, 0x3d372713, v30
	v_mul_f32_e32 v107, 0x3d372713, v31
	v_mul_f32_e32 v104, v28, v104
	v_mul_f32_e32 v105, v29, v105
	v_mul_f32_e32 v106, v30, v106
	v_mul_f32_e32 v107, v31, v107
	v_fma_f32 v104, v28, v104, v28
	v_fma_f32 v105, v29, v105, v29
	v_fma_f32 v106, v30, v106, v30
	v_fma_f32 v107, v31, v107, v31
	v_mul_f32_e32 v104, 0xbfcc422a, v104
	v_mul_f32_e32 v105, 0xbfcc422a, v105
	v_mul_f32_e32 v106, 0xbfcc422a, v106
	v_mul_f32_e32 v107, 0xbfcc422a, v107
	v_mul_f32_e32 v104, 0x3fb8aa3b, v104
	v_mul_f32_e32 v105, 0x3fb8aa3b, v105
	v_mul_f32_e32 v106, 0x3fb8aa3b, v106
	v_mul_f32_e32 v107, 0x3fb8aa3b, v107
	v_exp_f32_e32 v104, v104
	v_exp_f32_e32 v105, v105
	v_exp_f32_e32 v106, v106
	v_exp_f32_e32 v107, v107
	v_add_f32_e32 v104, 1.0, v104
	v_add_f32_e32 v105, 1.0, v105
	v_add_f32_e32 v106, 1.0, v106
	v_add_f32_e32 v107, 1.0, v107
	v_rcp_f32_e32 v104, v104
	v_rcp_f32_e32 v105, v105
	v_rcp_f32_e32 v106, v106
	v_rcp_f32_e32 v107, v107
	v_mul_f32_e32 v28, v28, v104
	v_mul_f32_e32 v29, v29, v105
	v_mul_f32_e32 v30, v30, v106
	v_mul_f32_e32 v31, v31, v107
	v_cvt_pk_bf16_f32 v110, v28, v29
	v_cvt_pk_bf16_f32 v111, v30, v31
	global_store_dwordx2 v186, v[110:111], s[12:13]
	s_add_u32 s12, s12, 0x8000
	s_addc_u32 s13, s13, 0
	s_waitcnt vmcnt(13)
	v_lshlrev_b32_e32 v100, 16, v88
	v_and_b32_e32 v101, 0xffff0000, v88
	v_lshlrev_b32_e32 v102, 16, v89
	v_and_b32_e32 v103, 0xffff0000, v89
	v_add_f32_e32 v32, v32, v64
	v_add_f32_e32 v33, v33, v65
	v_add_f32_e32 v34, v34, v66
	v_add_f32_e32 v35, v35, v67
	v_fmac_f32_e32 v32, v164, v100
	v_fmac_f32_e32 v33, v165, v101
	v_fmac_f32_e32 v34, v166, v102
	v_fmac_f32_e32 v35, v167, v103
	v_mul_f32_e32 v104, 0x3d372713, v32
	v_mul_f32_e32 v105, 0x3d372713, v33
	v_mul_f32_e32 v106, 0x3d372713, v34
	v_mul_f32_e32 v107, 0x3d372713, v35
	v_mul_f32_e32 v104, v32, v104
	v_mul_f32_e32 v105, v33, v105
	v_mul_f32_e32 v106, v34, v106
	v_mul_f32_e32 v107, v35, v107
	v_fma_f32 v104, v32, v104, v32
	v_fma_f32 v105, v33, v105, v33
	v_fma_f32 v106, v34, v106, v34
	v_fma_f32 v107, v35, v107, v35
	v_mul_f32_e32 v104, 0xbfcc422a, v104
	v_mul_f32_e32 v105, 0xbfcc422a, v105
	v_mul_f32_e32 v106, 0xbfcc422a, v106
	v_mul_f32_e32 v107, 0xbfcc422a, v107
	v_mul_f32_e32 v104, 0x3fb8aa3b, v104
	v_mul_f32_e32 v105, 0x3fb8aa3b, v105
	v_mul_f32_e32 v106, 0x3fb8aa3b, v106
	v_mul_f32_e32 v107, 0x3fb8aa3b, v107
	v_exp_f32_e32 v104, v104
	v_exp_f32_e32 v105, v105
	v_exp_f32_e32 v106, v106
	v_exp_f32_e32 v107, v107
	v_add_f32_e32 v104, 1.0, v104
	v_add_f32_e32 v105, 1.0, v105
	v_add_f32_e32 v106, 1.0, v106
	v_add_f32_e32 v107, 1.0, v107
	v_rcp_f32_e32 v104, v104
	v_rcp_f32_e32 v105, v105
	v_rcp_f32_e32 v106, v106
	v_rcp_f32_e32 v107, v107
	v_mul_f32_e32 v32, v32, v104
	v_mul_f32_e32 v33, v33, v105
	v_mul_f32_e32 v34, v34, v106
	v_mul_f32_e32 v35, v35, v107
	v_cvt_pk_bf16_f32 v108, v32, v33
	v_cvt_pk_bf16_f32 v109, v34, v35
	global_store_dwordx2 v186, v[108:109], s[12:13]
	s_add_u32 s12, s12, 0x8000
	s_addc_u32 s13, s13, 0
	s_waitcnt vmcnt(11)
	v_lshlrev_b32_e32 v100, 16, v90
	v_and_b32_e32 v101, 0xffff0000, v90
	v_lshlrev_b32_e32 v102, 16, v91
	v_and_b32_e32 v103, 0xffff0000, v91
	v_add_f32_e32 v36, v36, v68
	v_add_f32_e32 v37, v37, v69
	v_add_f32_e32 v38, v38, v70
	v_add_f32_e32 v39, v39, v71
	v_fmac_f32_e32 v36, v164, v100
	v_fmac_f32_e32 v37, v165, v101
	v_fmac_f32_e32 v38, v166, v102
	v_fmac_f32_e32 v39, v167, v103
	v_mul_f32_e32 v104, 0x3d372713, v36
	v_mul_f32_e32 v105, 0x3d372713, v37
	v_mul_f32_e32 v106, 0x3d372713, v38
	v_mul_f32_e32 v107, 0x3d372713, v39
	v_mul_f32_e32 v104, v36, v104
	v_mul_f32_e32 v105, v37, v105
	v_mul_f32_e32 v106, v38, v106
	v_mul_f32_e32 v107, v39, v107
	v_fma_f32 v104, v36, v104, v36
	v_fma_f32 v105, v37, v105, v37
	v_fma_f32 v106, v38, v106, v38
	v_fma_f32 v107, v39, v107, v39
	v_mul_f32_e32 v104, 0xbfcc422a, v104
	v_mul_f32_e32 v105, 0xbfcc422a, v105
	v_mul_f32_e32 v106, 0xbfcc422a, v106
	v_mul_f32_e32 v107, 0xbfcc422a, v107
	v_mul_f32_e32 v104, 0x3fb8aa3b, v104
	v_mul_f32_e32 v105, 0x3fb8aa3b, v105
	v_mul_f32_e32 v106, 0x3fb8aa3b, v106
	v_mul_f32_e32 v107, 0x3fb8aa3b, v107
	v_exp_f32_e32 v104, v104
	v_exp_f32_e32 v105, v105
	v_exp_f32_e32 v106, v106
	v_exp_f32_e32 v107, v107
	v_add_f32_e32 v104, 1.0, v104
	v_add_f32_e32 v105, 1.0, v105
	v_add_f32_e32 v106, 1.0, v106
	v_add_f32_e32 v107, 1.0, v107
	v_rcp_f32_e32 v104, v104
	v_rcp_f32_e32 v105, v105
	v_rcp_f32_e32 v106, v106
	v_rcp_f32_e32 v107, v107
	v_mul_f32_e32 v36, v36, v104
	v_mul_f32_e32 v37, v37, v105
	v_mul_f32_e32 v38, v38, v106
	v_mul_f32_e32 v39, v39, v107
	v_cvt_pk_bf16_f32 v110, v36, v37
	v_cvt_pk_bf16_f32 v111, v38, v39
	global_store_dwordx2 v186, v[110:111], s[12:13]
	s_add_u32 s12, s12, 0x8000
	s_addc_u32 s13, s13, 0
	s_waitcnt vmcnt(9)
	v_lshlrev_b32_e32 v100, 16, v92
	v_and_b32_e32 v101, 0xffff0000, v92
	v_lshlrev_b32_e32 v102, 16, v93
	v_and_b32_e32 v103, 0xffff0000, v93
	v_add_f32_e32 v40, v40, v72
	v_add_f32_e32 v41, v41, v73
	v_add_f32_e32 v42, v42, v74
	v_add_f32_e32 v43, v43, v75
	v_fmac_f32_e32 v40, v164, v100
	v_fmac_f32_e32 v41, v165, v101
	v_fmac_f32_e32 v42, v166, v102
	v_fmac_f32_e32 v43, v167, v103
	v_mul_f32_e32 v104, 0x3d372713, v40
	v_mul_f32_e32 v105, 0x3d372713, v41
	v_mul_f32_e32 v106, 0x3d372713, v42
	v_mul_f32_e32 v107, 0x3d372713, v43
	v_mul_f32_e32 v104, v40, v104
	v_mul_f32_e32 v105, v41, v105
	v_mul_f32_e32 v106, v42, v106
	v_mul_f32_e32 v107, v43, v107
	v_fma_f32 v104, v40, v104, v40
	v_fma_f32 v105, v41, v105, v41
	v_fma_f32 v106, v42, v106, v42
	v_fma_f32 v107, v43, v107, v43
	v_mul_f32_e32 v104, 0xbfcc422a, v104
	v_mul_f32_e32 v105, 0xbfcc422a, v105
	v_mul_f32_e32 v106, 0xbfcc422a, v106
	v_mul_f32_e32 v107, 0xbfcc422a, v107
	v_mul_f32_e32 v104, 0x3fb8aa3b, v104
	v_mul_f32_e32 v105, 0x3fb8aa3b, v105
	v_mul_f32_e32 v106, 0x3fb8aa3b, v106
	v_mul_f32_e32 v107, 0x3fb8aa3b, v107
	v_exp_f32_e32 v104, v104
	v_exp_f32_e32 v105, v105
	v_exp_f32_e32 v106, v106
	v_exp_f32_e32 v107, v107
	v_add_f32_e32 v104, 1.0, v104
	v_add_f32_e32 v105, 1.0, v105
	v_add_f32_e32 v106, 1.0, v106
	v_add_f32_e32 v107, 1.0, v107
	v_rcp_f32_e32 v104, v104
	v_rcp_f32_e32 v105, v105
	v_rcp_f32_e32 v106, v106
	v_rcp_f32_e32 v107, v107
	v_mul_f32_e32 v40, v40, v104
	v_mul_f32_e32 v41, v41, v105
	v_mul_f32_e32 v42, v42, v106
	v_mul_f32_e32 v43, v43, v107
	v_cvt_pk_bf16_f32 v108, v40, v41
	v_cvt_pk_bf16_f32 v109, v42, v43
	global_store_dwordx2 v186, v[108:109], s[12:13]
	s_add_u32 s12, s12, 0x8000
	s_addc_u32 s13, s13, 0
	s_waitcnt vmcnt(7)
	v_lshlrev_b32_e32 v100, 16, v94
	v_and_b32_e32 v101, 0xffff0000, v94
	v_lshlrev_b32_e32 v102, 16, v95
	v_and_b32_e32 v103, 0xffff0000, v95
	v_add_f32_e32 v44, v44, v76
	v_add_f32_e32 v45, v45, v77
	v_add_f32_e32 v46, v46, v78
	v_add_f32_e32 v47, v47, v79
	v_fmac_f32_e32 v44, v164, v100
	v_fmac_f32_e32 v45, v165, v101
	v_fmac_f32_e32 v46, v166, v102
	v_fmac_f32_e32 v47, v167, v103
	v_mul_f32_e32 v104, 0x3d372713, v44
	v_mul_f32_e32 v105, 0x3d372713, v45
	v_mul_f32_e32 v106, 0x3d372713, v46
	v_mul_f32_e32 v107, 0x3d372713, v47
	v_mul_f32_e32 v104, v44, v104
	v_mul_f32_e32 v105, v45, v105
	v_mul_f32_e32 v106, v46, v106
	v_mul_f32_e32 v107, v47, v107
	v_fma_f32 v104, v44, v104, v44
	v_fma_f32 v105, v45, v105, v45
	v_fma_f32 v106, v46, v106, v46
	v_fma_f32 v107, v47, v107, v47
	v_mul_f32_e32 v104, 0xbfcc422a, v104
	v_mul_f32_e32 v105, 0xbfcc422a, v105
	v_mul_f32_e32 v106, 0xbfcc422a, v106
	v_mul_f32_e32 v107, 0xbfcc422a, v107
	v_mul_f32_e32 v104, 0x3fb8aa3b, v104
	v_mul_f32_e32 v105, 0x3fb8aa3b, v105
	v_mul_f32_e32 v106, 0x3fb8aa3b, v106
	v_mul_f32_e32 v107, 0x3fb8aa3b, v107
	v_exp_f32_e32 v104, v104
	v_exp_f32_e32 v105, v105
	v_exp_f32_e32 v106, v106
	v_exp_f32_e32 v107, v107
	v_add_f32_e32 v104, 1.0, v104
	v_add_f32_e32 v105, 1.0, v105
	v_add_f32_e32 v106, 1.0, v106
	v_add_f32_e32 v107, 1.0, v107
	v_rcp_f32_e32 v104, v104
	v_rcp_f32_e32 v105, v105
	v_rcp_f32_e32 v106, v106
	v_rcp_f32_e32 v107, v107
	v_mul_f32_e32 v44, v44, v104
	v_mul_f32_e32 v45, v45, v105
	v_mul_f32_e32 v46, v46, v106
	v_mul_f32_e32 v47, v47, v107
	v_cvt_pk_bf16_f32 v110, v44, v45
	v_cvt_pk_bf16_f32 v111, v46, v47
	global_store_dwordx2 v186, v[110:111], s[12:13]
	s_add_u32 s12, s12, 0x8000
	s_addc_u32 s13, s13, 0
	s_add_u32 s14, s14, 8
	s_cmp_lt_u32 s14, 32
	s_cbranch_scc1 .Lssm_comb
	s_branch .Lssm_done
.Lssm_ctx:
	s_mov_b32 s27, 0
.Lssm_ctx_loop:
	s_lshl_b32 s22, s2, 3
	s_sub_u32 s21, s89, 4
	s_add_u32 s22, s22, s21
	s_lshl_b32 s21, s27, 2
	s_add_u32 s22, s22, s21
	s_lshr_b32 s23, s22, 6
	s_and_b32 s24, s22, 63
	s_lshl_b32 s25, s23, 8
	s_add_u32 s28, s24, 0
	s_lshl_b32 s29, s28, 13
	s_add_u32 s29, s29, 0x200000
	s_add_u32 s10, s62, s29
	s_addc_u32 s11, s63, 0
	global_load_dwordx4 v[84:87], v177, s[10:11]
	global_load_dwordx4 v[88:91], v177, s[10:11] offset:2048
	s_add_u32 s12, s10, 0x1000
	s_addc_u32 s13, s11, 0
	global_load_dwordx4 v[92:95], v177, s[12:13]
	global_load_dwordx4 v[96:99], v177, s[12:13] offset:2048
	s_lshl_b32 s29, s28, 12
	s_add_u32 s29, s29, 0x300000
	s_add_u32 s16, s62, s29
	s_addc_u32 s17, s63, 0
	global_load_dwordx2 v[2:3], v178, s[16:17]
	global_load_dwordx2 v[4:5], v178, s[16:17] offset:1024
	global_load_dwordx2 v[6:7], v178, s[16:17] offset:512
	global_load_dwordx2 v[8:9], v178, s[16:17] offset:1536
	global_load_dwordx2 v[10:11], v178, s[16:17] offset:2048
	global_load_dwordx2 v[12:13], v178, s[16:17] offset:3072
	global_load_dwordx2 v[14:15], v178, s[16:17] offset:2560
	global_load_dwordx2 v[16:17], v178, s[16:17] offset:3584
	s_lshl_b32 s29, s28, 9
	s_add_u32 s29, s29, 0x100000
	s_add_u32 s18, s62, s29
	s_addc_u32 s19, s63, 0
	global_load_dwordx2 v[116:117], v179, s[18:19]
	global_load_dwordx2 v[118:119], v179, s[18:19] offset:128
	s_lshl_b32 s30, s23, 1
	s_lshl_b32 s30, s30, 15
	s_lshl_b32 s31, s24, 8
	s_add_u32 s30, s30, s31
	v_mov_b32_e32 v120, 0
	v_mov_b32_e32 v121, 0
	s_mul_i32 s31, s25, 0x1800
	s_lshl_b32 s29, s24, 5
	s_add_u32 s31, s31, s29
	s_add_u32 s31, s31, 0x8801000
	s_add_u32 s4, s62, s31
	s_addc_u32 s5, s63, 0
	s_add_u32 s34, s4, 0
	s_addc_u32 s35, s5, 0
	global_load_dwordx4 v[80:83], v150, s[34:35]
	s_mov_b64 s[10:11], s[34:35]
	s_add_u32 s10, s10, 196608
	s_addc_u32 s11, s11, 0
	global_load_dwordx4 v[144:147], v150, s[10:11]
	s_mov_b64 s[34:35], s[10:11]
	s_add_u32 s10, s10, 196608
	s_addc_u32 s11, s11, 0
	s_mov_b32 s36, 0
	s_mov_b32 s14, 0
	s_mov_b32 s40, 0xffff0000
	s_waitcnt vmcnt(0)
	v_and_b32_e32 v182, 0xffff, v2
	v_lshrrev_b32_e32 v183, 16, v2
	v_and_b32_e32 v184, 0xffff, v3
	v_lshrrev_b32_e32 v185, 16, v3
	v_lshl_or_b32 v100, v4, 16, v182
	v_and_or_b32 v101, v4, s40, v183
	v_lshl_or_b32 v102, v5, 16, v184
	v_and_or_b32 v103, v5, s40, v185
	v_and_b32_e32 v182, 0xffff, v6
	v_lshrrev_b32_e32 v183, 16, v6
	v_and_b32_e32 v184, 0xffff, v7
	v_lshrrev_b32_e32 v185, 16, v7
	v_lshl_or_b32 v104, v8, 16, v182
	v_and_or_b32 v105, v8, s40, v183
	v_lshl_or_b32 v106, v9, 16, v184
	v_and_or_b32 v107, v9, s40, v185
	v_and_b32_e32 v182, 0xffff, v10
	v_lshrrev_b32_e32 v183, 16, v10
	v_and_b32_e32 v184, 0xffff, v11
	v_lshrrev_b32_e32 v185, 16, v11
	v_lshl_or_b32 v108, v12, 16, v182
	v_and_or_b32 v109, v12, s40, v183
	v_lshl_or_b32 v110, v13, 16, v184
	v_and_or_b32 v111, v13, s40, v185
	v_and_b32_e32 v182, 0xffff, v14
	v_lshrrev_b32_e32 v183, 16, v14
	v_and_b32_e32 v184, 0xffff, v15
	v_lshrrev_b32_e32 v185, 16, v15
	v_lshl_or_b32 v112, v16, 16, v182
	v_and_or_b32 v113, v16, s40, v183
	v_lshl_or_b32 v114, v17, 16, v184
	v_and_or_b32 v115, v17, s40, v185
	v_cmp_eq_u32_e32 vcc, 1, v174
	v_xor_b32_e32 v182, 0x80000000, v117
	v_xor_b32_e32 v183, 0x80000000, v119
	s_nop 1
	v_cndmask_b32_e32 v122, v182, v117, vcc
	v_cndmask_b32_e32 v123, v183, v119, vcc
.Lssm_tile_d0m1:
	s_waitcnt vmcnt(1)
	v_mfma_f32_32x32x16_bf16 v[16:31], v[80:83], v[84:87], 0
	v_mfma_f32_32x32x16_bf16 v[32:47], v[80:83], v[88:91], 0
	v_mfma_f32_32x32x16_bf16 v[48:63], v[80:83], v[92:95], 0
	v_mfma_f32_32x32x16_bf16 v[64:79], v[80:83], v[96:99], 0
	v_add_u32_e32 v171, s36, v155
	s_nop 11
	global_load_dwordx4 v[80:83], v150, s[10:11]
	s_add_u32 s34, s34, 196608
	s_addc_u32 s35, s35, 0
	s_add_u32 s10, s10, 196608
	s_addc_u32 s11, s11, 0
	v_permlane32_swap_b32_e32 v16, v48
	v_permlane32_swap_b32_e32 v17, v49
	v_permlane32_swap_b32_e32 v18, v50
	v_permlane32_swap_b32_e32 v19, v51
	v_permlane32_swap_b32_e32 v20, v52
	v_permlane32_swap_b32_e32 v21, v53
	v_permlane32_swap_b32_e32 v22, v54
	v_permlane32_swap_b32_e32 v23, v55
	v_permlane32_swap_b32_e32 v24, v56
	v_permlane32_swap_b32_e32 v25, v57
	v_permlane32_swap_b32_e32 v26, v58
	v_permlane32_swap_b32_e32 v27, v59
	v_permlane32_swap_b32_e32 v28, v60
	v_permlane32_swap_b32_e32 v29, v61
	v_permlane32_swap_b32_e32 v30, v62
	v_permlane32_swap_b32_e32 v31, v63
	v_permlane32_swap_b32_e32 v32, v64
	v_permlane32_swap_b32_e32 v33, v65
	v_permlane32_swap_b32_e32 v34, v66
	v_permlane32_swap_b32_e32 v35, v67
	v_permlane32_swap_b32_e32 v36, v68
	v_permlane32_swap_b32_e32 v37, v69
	v_permlane32_swap_b32_e32 v38, v70
	v_permlane32_swap_b32_e32 v39, v71
	v_permlane32_swap_b32_e32 v40, v72
	v_permlane32_swap_b32_e32 v41, v73
	v_permlane32_swap_b32_e32 v42, v74
	v_permlane32_swap_b32_e32 v43, v75
	v_permlane32_swap_b32_e32 v44, v76
	v_permlane32_swap_b32_e32 v45, v77
	v_permlane32_swap_b32_e32 v46, v78
	v_permlane32_swap_b32_e32 v47, v79
	v_fmac_f32_e32 v16, v116, v120
	v_fmac_f32_e32 v32, v118, v121
	v_fmac_f32_dpp v16, v120, v122 quad_perm:[1,0,3,2] row_mask:0xf bank_mask:0xf
	v_fmac_f32_dpp v32, v121, v123 quad_perm:[1,0,3,2] row_mask:0xf bank_mask:0xf
	v_cvt_pk_bf16_f32 v148, v16, v32
	ds_write_b32 v151, v148
	v_fmac_f32_e32 v17, v116, v16
	v_fmac_f32_e32 v33, v118, v32
	v_fmac_f32_dpp v17, v16, v122 quad_perm:[1,0,3,2] row_mask:0xf bank_mask:0xf
	v_fmac_f32_dpp v33, v32, v123 quad_perm:[1,0,3,2] row_mask:0xf bank_mask:0xf
	v_cvt_pk_bf16_f32 v149, v17, v33
	ds_write_b32 v151, v149 offset:272
	v_fmac_f32_e32 v18, v116, v17
	v_fmac_f32_e32 v34, v118, v33
	v_fmac_f32_dpp v18, v17, v122 quad_perm:[1,0,3,2] row_mask:0xf bank_mask:0xf
	v_fmac_f32_dpp v34, v33, v123 quad_perm:[1,0,3,2] row_mask:0xf bank_mask:0xf
	v_cvt_pk_bf16_f32 v148, v18, v34
	ds_write_b32 v151, v148 offset:544
	v_fmac_f32_e32 v19, v116, v18
	v_fmac_f32_e32 v35, v118, v34
	v_fmac_f32_dpp v19, v18, v122 quad_perm:[1,0,3,2] row_mask:0xf bank_mask:0xf
	v_fmac_f32_dpp v35, v34, v123 quad_perm:[1,0,3,2] row_mask:0xf bank_mask:0xf
	v_cvt_pk_bf16_f32 v149, v19, v35
	ds_write_b32 v151, v149 offset:816
	v_fmac_f32_e32 v48, v116, v19
	v_fmac_f32_e32 v64, v118, v35
	v_fmac_f32_dpp v48, v19, v122 quad_perm:[1,0,3,2] row_mask:0xf bank_mask:0xf
	v_fmac_f32_dpp v64, v35, v123 quad_perm:[1,0,3,2] row_mask:0xf bank_mask:0xf
	v_cvt_pk_bf16_f32 v148, v48, v64
	ds_write_b32 v151, v148 offset:1088
	v_fmac_f32_e32 v49, v116, v48
	v_fmac_f32_e32 v65, v118, v64
	v_fmac_f32_dpp v49, v48, v122 quad_perm:[1,0,3,2] row_mask:0xf bank_mask:0xf
	v_fmac_f32_dpp v65, v64, v123 quad_perm:[1,0,3,2] row_mask:0xf bank_mask:0xf
	v_cvt_pk_bf16_f32 v149, v49, v65
	ds_write_b32 v151, v149 offset:1360
	v_fmac_f32_e32 v50, v116, v49
	v_fmac_f32_e32 v66, v118, v65
	v_fmac_f32_dpp v50, v49, v122 quad_perm:[1,0,3,2] row_mask:0xf bank_mask:0xf
	v_fmac_f32_dpp v66, v65, v123 quad_perm:[1,0,3,2] row_mask:0xf bank_mask:0xf
	v_cvt_pk_bf16_f32 v148, v50, v66
	ds_write_b32 v151, v148 offset:1632
	v_fmac_f32_e32 v51, v116, v50
	v_fmac_f32_e32 v67, v118, v66
	v_fmac_f32_dpp v51, v50, v122 quad_perm:[1,0,3,2] row_mask:0xf bank_mask:0xf
	v_fmac_f32_dpp v67, v66, v123 quad_perm:[1,0,3,2] row_mask:0xf bank_mask:0xf
	v_cvt_pk_bf16_f32 v149, v51, v67
	ds_write_b32 v151, v149 offset:1904
	v_fmac_f32_e32 v20, v116, v51
	v_fmac_f32_e32 v36, v118, v67
	v_fmac_f32_dpp v20, v51, v122 quad_perm:[1,0,3,2] row_mask:0xf bank_mask:0xf
	v_fmac_f32_dpp v36, v67, v123 quad_perm:[1,0,3,2] row_mask:0xf bank_mask:0xf
	v_cvt_pk_bf16_f32 v148, v20, v36
	ds_write_b32 v151, v148 offset:2176
	v_fmac_f32_e32 v21, v116, v20
	v_fmac_f32_e32 v37, v118, v36
	v_fmac_f32_dpp v21, v20, v122 quad_perm:[1,0,3,2] row_mask:0xf bank_mask:0xf
	v_fmac_f32_dpp v37, v36, v123 quad_perm:[1,0,3,2] row_mask:0xf bank_mask:0xf
	v_cvt_pk_bf16_f32 v149, v21, v37
	ds_write_b32 v151, v149 offset:2448
	v_fmac_f32_e32 v22, v116, v21
	v_fmac_f32_e32 v38, v118, v37
	v_fmac_f32_dpp v22, v21, v122 quad_perm:[1,0,3,2] row_mask:0xf bank_mask:0xf
	v_fmac_f32_dpp v38, v37, v123 quad_perm:[1,0,3,2] row_mask:0xf bank_mask:0xf
	v_cvt_pk_bf16_f32 v148, v22, v38
	ds_write_b32 v151, v148 offset:2720
	v_fmac_f32_e32 v23, v116, v22
	v_fmac_f32_e32 v39, v118, v38
	v_fmac_f32_dpp v23, v22, v122 quad_perm:[1,0,3,2] row_mask:0xf bank_mask:0xf
	v_fmac_f32_dpp v39, v38, v123 quad_perm:[1,0,3,2] row_mask:0xf bank_mask:0xf
	v_cvt_pk_bf16_f32 v149, v23, v39
	ds_write_b32 v151, v149 offset:2992
	v_fmac_f32_e32 v52, v116, v23
	v_fmac_f32_e32 v68, v118, v39
	v_fmac_f32_dpp v52, v23, v122 quad_perm:[1,0,3,2] row_mask:0xf bank_mask:0xf
	v_fmac_f32_dpp v68, v39, v123 quad_perm:[1,0,3,2] row_mask:0xf bank_mask:0xf
	v_cvt_pk_bf16_f32 v148, v52, v68
	ds_write_b32 v151, v148 offset:3264
	v_fmac_f32_e32 v53, v116, v52
	v_fmac_f32_e32 v69, v118, v68
	v_fmac_f32_dpp v53, v52, v122 quad_perm:[1,0,3,2] row_mask:0xf bank_mask:0xf
	v_fmac_f32_dpp v69, v68, v123 quad_perm:[1,0,3,2] row_mask:0xf bank_mask:0xf
	v_cvt_pk_bf16_f32 v149, v53, v69
	ds_write_b32 v151, v149 offset:3536
	v_fmac_f32_e32 v54, v116, v53
	v_fmac_f32_e32 v70, v118, v69
	v_fmac_f32_dpp v54, v53, v122 quad_perm:[1,0,3,2] row_mask:0xf bank_mask:0xf
	v_fmac_f32_dpp v70, v69, v123 quad_perm:[1,0,3,2] row_mask:0xf bank_mask:0xf
	v_cvt_pk_bf16_f32 v148, v54, v70
	ds_write_b32 v151, v148 offset:3808
	v_fmac_f32_e32 v55, v116, v54
	v_fmac_f32_e32 v71, v118, v70
	v_fmac_f32_dpp v55, v54, v122 quad_perm:[1,0,3,2] row_mask:0xf bank_mask:0xf
	v_fmac_f32_dpp v71, v70, v123 quad_perm:[1,0,3,2] row_mask:0xf bank_mask:0xf
	v_cvt_pk_bf16_f32 v149, v55, v71
	ds_write_b32 v151, v149 offset:4080
	v_fmac_f32_e32 v24, v116, v55
	v_fmac_f32_e32 v40, v118, v71
	v_fmac_f32_dpp v24, v55, v122 quad_perm:[1,0,3,2] row_mask:0xf bank_mask:0xf
	v_fmac_f32_dpp v40, v71, v123 quad_perm:[1,0,3,2] row_mask:0xf bank_mask:0xf
	v_cvt_pk_bf16_f32 v148, v24, v40
	ds_write_b32 v151, v148 offset:4352
	v_fmac_f32_e32 v25, v116, v24
	v_fmac_f32_e32 v41, v118, v40
	v_fmac_f32_dpp v25, v24, v122 quad_perm:[1,0,3,2] row_mask:0xf bank_mask:0xf
	v_fmac_f32_dpp v41, v40, v123 quad_perm:[1,0,3,2] row_mask:0xf bank_mask:0xf
	v_cvt_pk_bf16_f32 v149, v25, v41
	ds_write_b32 v151, v149 offset:4624
	v_fmac_f32_e32 v26, v116, v25
	v_fmac_f32_e32 v42, v118, v41
	v_fmac_f32_dpp v26, v25, v122 quad_perm:[1,0,3,2] row_mask:0xf bank_mask:0xf
	v_fmac_f32_dpp v42, v41, v123 quad_perm:[1,0,3,2] row_mask:0xf bank_mask:0xf
	v_cvt_pk_bf16_f32 v148, v26, v42
	ds_write_b32 v151, v148 offset:4896
	v_fmac_f32_e32 v27, v116, v26
	v_fmac_f32_e32 v43, v118, v42
	v_fmac_f32_dpp v27, v26, v122 quad_perm:[1,0,3,2] row_mask:0xf bank_mask:0xf
	v_fmac_f32_dpp v43, v42, v123 quad_perm:[1,0,3,2] row_mask:0xf bank_mask:0xf
	v_cvt_pk_bf16_f32 v149, v27, v43
	ds_write_b32 v151, v149 offset:5168
	v_fmac_f32_e32 v56, v116, v27
	v_fmac_f32_e32 v72, v118, v43
	v_fmac_f32_dpp v56, v27, v122 quad_perm:[1,0,3,2] row_mask:0xf bank_mask:0xf
	v_fmac_f32_dpp v72, v43, v123 quad_perm:[1,0,3,2] row_mask:0xf bank_mask:0xf
	v_cvt_pk_bf16_f32 v148, v56, v72
	ds_write_b32 v151, v148 offset:5440
	v_fmac_f32_e32 v57, v116, v56
	v_fmac_f32_e32 v73, v118, v72
	v_fmac_f32_dpp v57, v56, v122 quad_perm:[1,0,3,2] row_mask:0xf bank_mask:0xf
	v_fmac_f32_dpp v73, v72, v123 quad_perm:[1,0,3,2] row_mask:0xf bank_mask:0xf
	v_cvt_pk_bf16_f32 v149, v57, v73
	ds_write_b32 v151, v149 offset:5712
	v_fmac_f32_e32 v58, v116, v57
	v_fmac_f32_e32 v74, v118, v73
	v_fmac_f32_dpp v58, v57, v122 quad_perm:[1,0,3,2] row_mask:0xf bank_mask:0xf
	v_fmac_f32_dpp v74, v73, v123 quad_perm:[1,0,3,2] row_mask:0xf bank_mask:0xf
	v_cvt_pk_bf16_f32 v148, v58, v74
	ds_write_b32 v151, v148 offset:5984
	v_fmac_f32_e32 v59, v116, v58
	v_fmac_f32_e32 v75, v118, v74
	v_fmac_f32_dpp v59, v58, v122 quad_perm:[1,0,3,2] row_mask:0xf bank_mask:0xf
	v_fmac_f32_dpp v75, v74, v123 quad_perm:[1,0,3,2] row_mask:0xf bank_mask:0xf
	v_cvt_pk_bf16_f32 v149, v59, v75
	ds_write_b32 v151, v149 offset:6256
	v_fmac_f32_e32 v28, v116, v59
	v_fmac_f32_e32 v44, v118, v75
	v_fmac_f32_dpp v28, v59, v122 quad_perm:[1,0,3,2] row_mask:0xf bank_mask:0xf
	v_fmac_f32_dpp v44, v75, v123 quad_perm:[1,0,3,2] row_mask:0xf bank_mask:0xf
	v_cvt_pk_bf16_f32 v148, v28, v44
	ds_write_b32 v151, v148 offset:6528
	v_fmac_f32_e32 v29, v116, v28
	v_fmac_f32_e32 v45, v118, v44
	v_fmac_f32_dpp v29, v28, v122 quad_perm:[1,0,3,2] row_mask:0xf bank_mask:0xf
	v_fmac_f32_dpp v45, v44, v123 quad_perm:[1,0,3,2] row_mask:0xf bank_mask:0xf
	v_cvt_pk_bf16_f32 v149, v29, v45
	ds_write_b32 v151, v149 offset:6800
	v_fmac_f32_e32 v30, v116, v29
	v_fmac_f32_e32 v46, v118, v45
	v_fmac_f32_dpp v30, v29, v122 quad_perm:[1,0,3,2] row_mask:0xf bank_mask:0xf
	v_fmac_f32_dpp v46, v45, v123 quad_perm:[1,0,3,2] row_mask:0xf bank_mask:0xf
	v_cvt_pk_bf16_f32 v148, v30, v46
	ds_write_b32 v151, v148 offset:7072
	v_fmac_f32_e32 v31, v116, v30
	v_fmac_f32_e32 v47, v118, v46
	v_fmac_f32_dpp v31, v30, v122 quad_perm:[1,0,3,2] row_mask:0xf bank_mask:0xf
	v_fmac_f32_dpp v47, v46, v123 quad_perm:[1,0,3,2] row_mask:0xf bank_mask:0xf
	v_cvt_pk_bf16_f32 v149, v31, v47
	ds_write_b32 v151, v149 offset:7344
	v_fmac_f32_e32 v60, v116, v31
	v_fmac_f32_e32 v76, v118, v47
	v_fmac_f32_dpp v60, v31, v122 quad_perm:[1,0,3,2] row_mask:0xf bank_mask:0xf
	v_fmac_f32_dpp v76, v47, v123 quad_perm:[1,0,3,2] row_mask:0xf bank_mask:0xf
	v_cvt_pk_bf16_f32 v148, v60, v76
	ds_write_b32 v151, v148 offset:7616
	v_fmac_f32_e32 v61, v116, v60
	v_fmac_f32_e32 v77, v118, v76
	v_fmac_f32_dpp v61, v60, v122 quad_perm:[1,0,3,2] row_mask:0xf bank_mask:0xf
	v_fmac_f32_dpp v77, v76, v123 quad_perm:[1,0,3,2] row_mask:0xf bank_mask:0xf
	v_cvt_pk_bf16_f32 v149, v61, v77
	ds_write_b32 v151, v149 offset:7888
	v_fmac_f32_e32 v62, v116, v61
	v_fmac_f32_e32 v78, v118, v77
	v_fmac_f32_dpp v62, v61, v122 quad_perm:[1,0,3,2] row_mask:0xf bank_mask:0xf
	v_fmac_f32_dpp v78, v77, v123 quad_perm:[1,0,3,2] row_mask:0xf bank_mask:0xf
	v_cvt_pk_bf16_f32 v148, v62, v78
	ds_write_b32 v151, v148 offset:8160
	v_fmac_f32_e32 v63, v116, v62
	v_fmac_f32_e32 v79, v118, v78
	v_fmac_f32_dpp v63, v62, v122 quad_perm:[1,0,3,2] row_mask:0xf bank_mask:0xf
	v_fmac_f32_dpp v79, v78, v123 quad_perm:[1,0,3,2] row_mask:0xf bank_mask:0xf
	v_cvt_pk_bf16_f32 v149, v63, v79
	ds_write_b32 v151, v149 offset:8432
	v_mov_b32_e32 v120, v63
	v_mov_b32_e32 v121, v79
	ds_read_b128 v[124:127], v152
	ds_read_b128 v[128:131], v152 offset:64
	ds_read_b128 v[132:135], v152 offset:128
	ds_read_b128 v[136:139], v152 offset:192
	s_waitcnt lgkmcnt(3)
	v_mfma_f32_16x16x32_bf16 v[140:143], v[100:103], v[124:127], 0
	s_waitcnt lgkmcnt(2)
	v_mfma_f32_16x16x32_bf16 v[140:143], v[104:107], v[128:131], v[140:143]
	s_waitcnt lgkmcnt(1)
	v_mfma_f32_16x16x32_bf16 v[140:143], v[108:111], v[132:135], v[140:143]
	s_waitcnt lgkmcnt(0)
	v_mfma_f32_16x16x32_bf16 v[140:143], v[112:115], v[136:139], v[140:143]
	s_nop 9
	v_cvt_pk_bf16_f32 v182, v140, v141
	v_cvt_pk_bf16_f32 v183, v142, v143
	ds_write_b64 v171, v[182:183]
	ds_read_b128 v[124:127], v152 offset:4352
	ds_read_b128 v[128:131], v152 offset:4416
	ds_read_b128 v[132:135], v152 offset:4480
	ds_read_b128 v[136:139], v152 offset:4544
	s_waitcnt lgkmcnt(3)
	v_mfma_f32_16x16x32_bf16 v[140:143], v[100:103], v[124:127], 0
	s_waitcnt lgkmcnt(2)
	v_mfma_f32_16x16x32_bf16 v[140:143], v[104:107], v[128:131], v[140:143]
	s_waitcnt lgkmcnt(1)
	v_mfma_f32_16x16x32_bf16 v[140:143], v[108:111], v[132:135], v[140:143]
	s_waitcnt lgkmcnt(0)
	v_mfma_f32_16x16x32_bf16 v[140:143], v[112:115], v[136:139], v[140:143]
	s_nop 9
	v_cvt_pk_bf16_f32 v182, v140, v141
	v_cvt_pk_bf16_f32 v183, v142, v143
	ds_write_b64 v171, v[182:183] offset:512
	s_add_u32 s36, s36, 1024
	s_waitcnt vmcnt(1)
	v_mfma_f32_32x32x16_bf16 v[16:31], v[144:147], v[84:87], 0
	v_mfma_f32_32x32x16_bf16 v[32:47], v[144:147], v[88:91], 0
	v_mfma_f32_32x32x16_bf16 v[48:63], v[144:147], v[92:95], 0
	v_mfma_f32_32x32x16_bf16 v[64:79], v[144:147], v[96:99], 0
	v_add_u32_e32 v171, s36, v155
	s_nop 11
	global_load_dwordx4 v[144:147], v150, s[10:11]
	s_add_u32 s34, s34, 196608
	s_addc_u32 s35, s35, 0
	s_add_u32 s10, s10, 196608
	s_addc_u32 s11, s11, 0
	v_permlane32_swap_b32_e32 v16, v48
	v_permlane32_swap_b32_e32 v17, v49
	v_permlane32_swap_b32_e32 v18, v50
	v_permlane32_swap_b32_e32 v19, v51
	v_permlane32_swap_b32_e32 v20, v52
	v_permlane32_swap_b32_e32 v21, v53
	v_permlane32_swap_b32_e32 v22, v54
	v_permlane32_swap_b32_e32 v23, v55
	v_permlane32_swap_b32_e32 v24, v56
	v_permlane32_swap_b32_e32 v25, v57
	v_permlane32_swap_b32_e32 v26, v58
	v_permlane32_swap_b32_e32 v27, v59
	v_permlane32_swap_b32_e32 v28, v60
	v_permlane32_swap_b32_e32 v29, v61
	v_permlane32_swap_b32_e32 v30, v62
	v_permlane32_swap_b32_e32 v31, v63
	v_permlane32_swap_b32_e32 v32, v64
	v_permlane32_swap_b32_e32 v33, v65
	v_permlane32_swap_b32_e32 v34, v66
	v_permlane32_swap_b32_e32 v35, v67
	v_permlane32_swap_b32_e32 v36, v68
	v_permlane32_swap_b32_e32 v37, v69
	v_permlane32_swap_b32_e32 v38, v70
	v_permlane32_swap_b32_e32 v39, v71
	v_permlane32_swap_b32_e32 v40, v72
	v_permlane32_swap_b32_e32 v41, v73
	v_permlane32_swap_b32_e32 v42, v74
	v_permlane32_swap_b32_e32 v43, v75
	v_permlane32_swap_b32_e32 v44, v76
	v_permlane32_swap_b32_e32 v45, v77
	v_permlane32_swap_b32_e32 v46, v78
	v_permlane32_swap_b32_e32 v47, v79
	v_fmac_f32_e32 v16, v116, v120
	v_fmac_f32_e32 v32, v118, v121
	v_fmac_f32_dpp v16, v120, v122 quad_perm:[1,0,3,2] row_mask:0xf bank_mask:0xf
	v_fmac_f32_dpp v32, v121, v123 quad_perm:[1,0,3,2] row_mask:0xf bank_mask:0xf
	v_cvt_pk_bf16_f32 v148, v16, v32
	ds_write_b32 v151, v148
	v_fmac_f32_e32 v17, v116, v16
	v_fmac_f32_e32 v33, v118, v32
	v_fmac_f32_dpp v17, v16, v122 quad_perm:[1,0,3,2] row_mask:0xf bank_mask:0xf
	v_fmac_f32_dpp v33, v32, v123 quad_perm:[1,0,3,2] row_mask:0xf bank_mask:0xf
	v_cvt_pk_bf16_f32 v149, v17, v33
	ds_write_b32 v151, v149 offset:272
	v_fmac_f32_e32 v18, v116, v17
	v_fmac_f32_e32 v34, v118, v33
	v_fmac_f32_dpp v18, v17, v122 quad_perm:[1,0,3,2] row_mask:0xf bank_mask:0xf
	v_fmac_f32_dpp v34, v33, v123 quad_perm:[1,0,3,2] row_mask:0xf bank_mask:0xf
	v_cvt_pk_bf16_f32 v148, v18, v34
	ds_write_b32 v151, v148 offset:544
	v_fmac_f32_e32 v19, v116, v18
	v_fmac_f32_e32 v35, v118, v34
	v_fmac_f32_dpp v19, v18, v122 quad_perm:[1,0,3,2] row_mask:0xf bank_mask:0xf
	v_fmac_f32_dpp v35, v34, v123 quad_perm:[1,0,3,2] row_mask:0xf bank_mask:0xf
	v_cvt_pk_bf16_f32 v149, v19, v35
	ds_write_b32 v151, v149 offset:816
	v_fmac_f32_e32 v48, v116, v19
	v_fmac_f32_e32 v64, v118, v35
	v_fmac_f32_dpp v48, v19, v122 quad_perm:[1,0,3,2] row_mask:0xf bank_mask:0xf
	v_fmac_f32_dpp v64, v35, v123 quad_perm:[1,0,3,2] row_mask:0xf bank_mask:0xf
	v_cvt_pk_bf16_f32 v148, v48, v64
	ds_write_b32 v151, v148 offset:1088
	v_fmac_f32_e32 v49, v116, v48
	v_fmac_f32_e32 v65, v118, v64
	v_fmac_f32_dpp v49, v48, v122 quad_perm:[1,0,3,2] row_mask:0xf bank_mask:0xf
	v_fmac_f32_dpp v65, v64, v123 quad_perm:[1,0,3,2] row_mask:0xf bank_mask:0xf
	v_cvt_pk_bf16_f32 v149, v49, v65
	ds_write_b32 v151, v149 offset:1360
	v_fmac_f32_e32 v50, v116, v49
	v_fmac_f32_e32 v66, v118, v65
	v_fmac_f32_dpp v50, v49, v122 quad_perm:[1,0,3,2] row_mask:0xf bank_mask:0xf
	v_fmac_f32_dpp v66, v65, v123 quad_perm:[1,0,3,2] row_mask:0xf bank_mask:0xf
	v_cvt_pk_bf16_f32 v148, v50, v66
	ds_write_b32 v151, v148 offset:1632
	v_fmac_f32_e32 v51, v116, v50
	v_fmac_f32_e32 v67, v118, v66
	v_fmac_f32_dpp v51, v50, v122 quad_perm:[1,0,3,2] row_mask:0xf bank_mask:0xf
	v_fmac_f32_dpp v67, v66, v123 quad_perm:[1,0,3,2] row_mask:0xf bank_mask:0xf
	v_cvt_pk_bf16_f32 v149, v51, v67
	ds_write_b32 v151, v149 offset:1904
	v_fmac_f32_e32 v20, v116, v51
	v_fmac_f32_e32 v36, v118, v67
	v_fmac_f32_dpp v20, v51, v122 quad_perm:[1,0,3,2] row_mask:0xf bank_mask:0xf
	v_fmac_f32_dpp v36, v67, v123 quad_perm:[1,0,3,2] row_mask:0xf bank_mask:0xf
	v_cvt_pk_bf16_f32 v148, v20, v36
	ds_write_b32 v151, v148 offset:2176
	v_fmac_f32_e32 v21, v116, v20
	v_fmac_f32_e32 v37, v118, v36
	v_fmac_f32_dpp v21, v20, v122 quad_perm:[1,0,3,2] row_mask:0xf bank_mask:0xf
	v_fmac_f32_dpp v37, v36, v123 quad_perm:[1,0,3,2] row_mask:0xf bank_mask:0xf
	v_cvt_pk_bf16_f32 v149, v21, v37
	ds_write_b32 v151, v149 offset:2448
	v_fmac_f32_e32 v22, v116, v21
	v_fmac_f32_e32 v38, v118, v37
	v_fmac_f32_dpp v22, v21, v122 quad_perm:[1,0,3,2] row_mask:0xf bank_mask:0xf
	v_fmac_f32_dpp v38, v37, v123 quad_perm:[1,0,3,2] row_mask:0xf bank_mask:0xf
	v_cvt_pk_bf16_f32 v148, v22, v38
	ds_write_b32 v151, v148 offset:2720
	v_fmac_f32_e32 v23, v116, v22
	v_fmac_f32_e32 v39, v118, v38
	v_fmac_f32_dpp v23, v22, v122 quad_perm:[1,0,3,2] row_mask:0xf bank_mask:0xf
	v_fmac_f32_dpp v39, v38, v123 quad_perm:[1,0,3,2] row_mask:0xf bank_mask:0xf
	v_cvt_pk_bf16_f32 v149, v23, v39
	ds_write_b32 v151, v149 offset:2992
	v_fmac_f32_e32 v52, v116, v23
	v_fmac_f32_e32 v68, v118, v39
	v_fmac_f32_dpp v52, v23, v122 quad_perm:[1,0,3,2] row_mask:0xf bank_mask:0xf
	v_fmac_f32_dpp v68, v39, v123 quad_perm:[1,0,3,2] row_mask:0xf bank_mask:0xf
	v_cvt_pk_bf16_f32 v148, v52, v68
	ds_write_b32 v151, v148 offset:3264
	v_fmac_f32_e32 v53, v116, v52
	v_fmac_f32_e32 v69, v118, v68
	v_fmac_f32_dpp v53, v52, v122 quad_perm:[1,0,3,2] row_mask:0xf bank_mask:0xf
	v_fmac_f32_dpp v69, v68, v123 quad_perm:[1,0,3,2] row_mask:0xf bank_mask:0xf
	v_cvt_pk_bf16_f32 v149, v53, v69
	ds_write_b32 v151, v149 offset:3536
	v_fmac_f32_e32 v54, v116, v53
	v_fmac_f32_e32 v70, v118, v69
	v_fmac_f32_dpp v54, v53, v122 quad_perm:[1,0,3,2] row_mask:0xf bank_mask:0xf
	v_fmac_f32_dpp v70, v69, v123 quad_perm:[1,0,3,2] row_mask:0xf bank_mask:0xf
	v_cvt_pk_bf16_f32 v148, v54, v70
	ds_write_b32 v151, v148 offset:3808
	v_fmac_f32_e32 v55, v116, v54
	v_fmac_f32_e32 v71, v118, v70
	v_fmac_f32_dpp v55, v54, v122 quad_perm:[1,0,3,2] row_mask:0xf bank_mask:0xf
	v_fmac_f32_dpp v71, v70, v123 quad_perm:[1,0,3,2] row_mask:0xf bank_mask:0xf
	v_cvt_pk_bf16_f32 v149, v55, v71
	ds_write_b32 v151, v149 offset:4080
	v_fmac_f32_e32 v24, v116, v55
	v_fmac_f32_e32 v40, v118, v71
	v_fmac_f32_dpp v24, v55, v122 quad_perm:[1,0,3,2] row_mask:0xf bank_mask:0xf
	v_fmac_f32_dpp v40, v71, v123 quad_perm:[1,0,3,2] row_mask:0xf bank_mask:0xf
	v_cvt_pk_bf16_f32 v148, v24, v40
	ds_write_b32 v151, v148 offset:4352
	v_fmac_f32_e32 v25, v116, v24
	v_fmac_f32_e32 v41, v118, v40
	v_fmac_f32_dpp v25, v24, v122 quad_perm:[1,0,3,2] row_mask:0xf bank_mask:0xf
	v_fmac_f32_dpp v41, v40, v123 quad_perm:[1,0,3,2] row_mask:0xf bank_mask:0xf
	v_cvt_pk_bf16_f32 v149, v25, v41
	ds_write_b32 v151, v149 offset:4624
	v_fmac_f32_e32 v26, v116, v25
	v_fmac_f32_e32 v42, v118, v41
	v_fmac_f32_dpp v26, v25, v122 quad_perm:[1,0,3,2] row_mask:0xf bank_mask:0xf
	v_fmac_f32_dpp v42, v41, v123 quad_perm:[1,0,3,2] row_mask:0xf bank_mask:0xf
	v_cvt_pk_bf16_f32 v148, v26, v42
	ds_write_b32 v151, v148 offset:4896
	v_fmac_f32_e32 v27, v116, v26
	v_fmac_f32_e32 v43, v118, v42
	v_fmac_f32_dpp v27, v26, v122 quad_perm:[1,0,3,2] row_mask:0xf bank_mask:0xf
	v_fmac_f32_dpp v43, v42, v123 quad_perm:[1,0,3,2] row_mask:0xf bank_mask:0xf
	v_cvt_pk_bf16_f32 v149, v27, v43
	ds_write_b32 v151, v149 offset:5168
	v_fmac_f32_e32 v56, v116, v27
	v_fmac_f32_e32 v72, v118, v43
	v_fmac_f32_dpp v56, v27, v122 quad_perm:[1,0,3,2] row_mask:0xf bank_mask:0xf
	v_fmac_f32_dpp v72, v43, v123 quad_perm:[1,0,3,2] row_mask:0xf bank_mask:0xf
	v_cvt_pk_bf16_f32 v148, v56, v72
	ds_write_b32 v151, v148 offset:5440
	v_fmac_f32_e32 v57, v116, v56
	v_fmac_f32_e32 v73, v118, v72
	v_fmac_f32_dpp v57, v56, v122 quad_perm:[1,0,3,2] row_mask:0xf bank_mask:0xf
	v_fmac_f32_dpp v73, v72, v123 quad_perm:[1,0,3,2] row_mask:0xf bank_mask:0xf
	v_cvt_pk_bf16_f32 v149, v57, v73
	ds_write_b32 v151, v149 offset:5712
	v_fmac_f32_e32 v58, v116, v57
	v_fmac_f32_e32 v74, v118, v73
	v_fmac_f32_dpp v58, v57, v122 quad_perm:[1,0,3,2] row_mask:0xf bank_mask:0xf
	v_fmac_f32_dpp v74, v73, v123 quad_perm:[1,0,3,2] row_mask:0xf bank_mask:0xf
	v_cvt_pk_bf16_f32 v148, v58, v74
	ds_write_b32 v151, v148 offset:5984
	v_fmac_f32_e32 v59, v116, v58
	v_fmac_f32_e32 v75, v118, v74
	v_fmac_f32_dpp v59, v58, v122 quad_perm:[1,0,3,2] row_mask:0xf bank_mask:0xf
	v_fmac_f32_dpp v75, v74, v123 quad_perm:[1,0,3,2] row_mask:0xf bank_mask:0xf
	v_cvt_pk_bf16_f32 v149, v59, v75
	ds_write_b32 v151, v149 offset:6256
	v_fmac_f32_e32 v28, v116, v59
	v_fmac_f32_e32 v44, v118, v75
	v_fmac_f32_dpp v28, v59, v122 quad_perm:[1,0,3,2] row_mask:0xf bank_mask:0xf
	v_fmac_f32_dpp v44, v75, v123 quad_perm:[1,0,3,2] row_mask:0xf bank_mask:0xf
	v_cvt_pk_bf16_f32 v148, v28, v44
	ds_write_b32 v151, v148 offset:6528
	v_fmac_f32_e32 v29, v116, v28
	v_fmac_f32_e32 v45, v118, v44
	v_fmac_f32_dpp v29, v28, v122 quad_perm:[1,0,3,2] row_mask:0xf bank_mask:0xf
	v_fmac_f32_dpp v45, v44, v123 quad_perm:[1,0,3,2] row_mask:0xf bank_mask:0xf
	v_cvt_pk_bf16_f32 v149, v29, v45
	ds_write_b32 v151, v149 offset:6800
	v_fmac_f32_e32 v30, v116, v29
	v_fmac_f32_e32 v46, v118, v45
	v_fmac_f32_dpp v30, v29, v122 quad_perm:[1,0,3,2] row_mask:0xf bank_mask:0xf
	v_fmac_f32_dpp v46, v45, v123 quad_perm:[1,0,3,2] row_mask:0xf bank_mask:0xf
	v_cvt_pk_bf16_f32 v148, v30, v46
	ds_write_b32 v151, v148 offset:7072
	v_fmac_f32_e32 v31, v116, v30
	v_fmac_f32_e32 v47, v118, v46
	v_fmac_f32_dpp v31, v30, v122 quad_perm:[1,0,3,2] row_mask:0xf bank_mask:0xf
	v_fmac_f32_dpp v47, v46, v123 quad_perm:[1,0,3,2] row_mask:0xf bank_mask:0xf
	v_cvt_pk_bf16_f32 v149, v31, v47
	ds_write_b32 v151, v149 offset:7344
	v_fmac_f32_e32 v60, v116, v31
	v_fmac_f32_e32 v76, v118, v47
	v_fmac_f32_dpp v60, v31, v122 quad_perm:[1,0,3,2] row_mask:0xf bank_mask:0xf
	v_fmac_f32_dpp v76, v47, v123 quad_perm:[1,0,3,2] row_mask:0xf bank_mask:0xf
	v_cvt_pk_bf16_f32 v148, v60, v76
	ds_write_b32 v151, v148 offset:7616
	v_fmac_f32_e32 v61, v116, v60
	v_fmac_f32_e32 v77, v118, v76
	v_fmac_f32_dpp v61, v60, v122 quad_perm:[1,0,3,2] row_mask:0xf bank_mask:0xf
	v_fmac_f32_dpp v77, v76, v123 quad_perm:[1,0,3,2] row_mask:0xf bank_mask:0xf
	v_cvt_pk_bf16_f32 v149, v61, v77
	ds_write_b32 v151, v149 offset:7888
	v_fmac_f32_e32 v62, v116, v61
	v_fmac_f32_e32 v78, v118, v77
	v_fmac_f32_dpp v62, v61, v122 quad_perm:[1,0,3,2] row_mask:0xf bank_mask:0xf
	v_fmac_f32_dpp v78, v77, v123 quad_perm:[1,0,3,2] row_mask:0xf bank_mask:0xf
	v_cvt_pk_bf16_f32 v148, v62, v78
	ds_write_b32 v151, v148 offset:8160
	v_fmac_f32_e32 v63, v116, v62
	v_fmac_f32_e32 v79, v118, v78
	v_fmac_f32_dpp v63, v62, v122 quad_perm:[1,0,3,2] row_mask:0xf bank_mask:0xf
	v_fmac_f32_dpp v79, v78, v123 quad_perm:[1,0,3,2] row_mask:0xf bank_mask:0xf
	v_cvt_pk_bf16_f32 v149, v63, v79
	ds_write_b32 v151, v149 offset:8432
	v_mov_b32_e32 v120, v63
	v_mov_b32_e32 v121, v79
	ds_read_b128 v[124:127], v152
	ds_read_b128 v[128:131], v152 offset:64
	ds_read_b128 v[132:135], v152 offset:128
	ds_read_b128 v[136:139], v152 offset:192
	s_waitcnt lgkmcnt(3)
	v_mfma_f32_16x16x32_bf16 v[140:143], v[100:103], v[124:127], 0
	s_waitcnt lgkmcnt(2)
	v_mfma_f32_16x16x32_bf16 v[140:143], v[104:107], v[128:131], v[140:143]
	s_waitcnt lgkmcnt(1)
	v_mfma_f32_16x16x32_bf16 v[140:143], v[108:111], v[132:135], v[140:143]
	s_waitcnt lgkmcnt(0)
	v_mfma_f32_16x16x32_bf16 v[140:143], v[112:115], v[136:139], v[140:143]
	s_nop 9
	v_cvt_pk_bf16_f32 v182, v140, v141
	v_cvt_pk_bf16_f32 v183, v142, v143
	ds_write_b64 v171, v[182:183]
	ds_read_b128 v[124:127], v152 offset:4352
	ds_read_b128 v[128:131], v152 offset:4416
	ds_read_b128 v[132:135], v152 offset:4480
	ds_read_b128 v[136:139], v152 offset:4544
	s_waitcnt lgkmcnt(3)
	v_mfma_f32_16x16x32_bf16 v[140:143], v[100:103], v[124:127], 0
	s_waitcnt lgkmcnt(2)
	v_mfma_f32_16x16x32_bf16 v[140:143], v[104:107], v[128:131], v[140:143]
	s_waitcnt lgkmcnt(1)
	v_mfma_f32_16x16x32_bf16 v[140:143], v[108:111], v[132:135], v[140:143]
	s_waitcnt lgkmcnt(0)
	v_mfma_f32_16x16x32_bf16 v[140:143], v[112:115], v[136:139], v[140:143]
	s_nop 9
	v_cvt_pk_bf16_f32 v182, v140, v141
	v_cvt_pk_bf16_f32 v183, v142, v143
	ds_write_b64 v171, v[182:183] offset:512
	s_add_u32 s36, s36, 1024
	s_add_u32 s14, s14, 2
	s_cmp_lt_u32 s14, 8
	s_cbranch_scc1 .Lssm_tile_d0m1
	s_add_u32 s30, s30, 0x8000000
	s_add_u32 s16, s60, s30
	s_addc_u32 s17, s61, 0
	global_store_dword v180, v120, s[16:17]
	global_store_dword v180, v121, s[16:17] offset:64
	s_waitcnt vmcnt(0) lgkmcnt(0)
	s_add_u32 s28, s24, 64
	s_lshl_b32 s29, s28, 13
	s_add_u32 s29, s29, 0x200000
	s_add_u32 s10, s62, s29
	s_addc_u32 s11, s63, 0
	global_load_dwordx4 v[84:87], v177, s[10:11]
	global_load_dwordx4 v[88:91], v177, s[10:11] offset:2048
	s_add_u32 s12, s10, 0x1000
	s_addc_u32 s13, s11, 0
	global_load_dwordx4 v[92:95], v177, s[12:13]
	global_load_dwordx4 v[96:99], v177, s[12:13] offset:2048
	s_lshl_b32 s29, s28, 12
	s_add_u32 s29, s29, 0x300000
	s_add_u32 s16, s62, s29
	s_addc_u32 s17, s63, 0
	global_load_dwordx2 v[2:3], v178, s[16:17]
	global_load_dwordx2 v[4:5], v178, s[16:17] offset:1024
	global_load_dwordx2 v[6:7], v178, s[16:17] offset:512
	global_load_dwordx2 v[8:9], v178, s[16:17] offset:1536
	global_load_dwordx2 v[10:11], v178, s[16:17] offset:2048
	global_load_dwordx2 v[12:13], v178, s[16:17] offset:3072
	global_load_dwordx2 v[14:15], v178, s[16:17] offset:2560
	global_load_dwordx2 v[16:17], v178, s[16:17] offset:3584
	s_lshl_b32 s29, s28, 9
	s_add_u32 s29, s29, 0x100000
	s_add_u32 s18, s62, s29
	s_addc_u32 s19, s63, 0
	global_load_dwordx2 v[116:117], v179, s[18:19]
	global_load_dwordx2 v[118:119], v179, s[18:19] offset:128
	s_lshl_b32 s30, s23, 1
	s_add_u32 s30, s30, 1
	s_lshl_b32 s30, s30, 15
	s_lshl_b32 s31, s24, 8
	s_add_u32 s30, s30, s31
	v_mov_b32_e32 v120, 0
	v_mov_b32_e32 v121, 0
	v_readlane_b32 s34, v254, 28
	v_readlane_b32 s35, v254, 29
	s_nop 3
	s_lshl_b32 s31, s24, 6
	s_add_u32 s34, s34, s31
	s_addc_u32 s35, s35, 0
	global_load_dwordx4 v[164:167], v181, s[34:35]
	s_mul_i32 s31, s25, 0x1800
	s_lshl_b32 s29, s24, 5
	s_add_u32 s31, s31, s29
	s_add_u32 s31, s31, 0x8801000
	s_add_u32 s4, s62, s31
	s_addc_u32 s5, s63, 0
	s_lshl_b32 s31, s25, 11
	s_lshl_b32 s29, s24, 5
	s_add_u32 s31, s31, s29
	s_add_u32 s31, s31, 0x14800000
	s_add_u32 s6, s62, s31
	s_addc_u32 s7, s63, 0
	s_add_u32 s34, s4, 1376256
	s_addc_u32 s35, s5, 0
	global_load_dwordx4 v[80:83], v150, s[34:35]
	global_load_dwordx2 v[160:161], v154, s[34:35]
	global_load_dwordx2 v[162:163], v158, s[34:35]
	s_mov_b64 s[10:11], s[34:35]
	s_sub_u32 s10, s10, 196608
	s_subb_u32 s11, s11, 0
	global_load_dwordx4 v[144:147], v150, s[10:11]
	s_mov_b64 s[34:35], s[10:11]
	s_sub_u32 s10, s10, 196608
	s_subb_u32 s11, s11, 0
	s_add_u32 s12, s6, 458752
	s_addc_u32 s13, s7, 0
	s_mov_b32 s36, 7168
	s_mov_b32 s14, 0
	s_mov_b32 s40, 0xffff0000
	s_waitcnt vmcnt(0)
	v_and_b32_e32 v182, 0xffff, v2
	v_lshrrev_b32_e32 v183, 16, v2
	v_and_b32_e32 v184, 0xffff, v3
	v_lshrrev_b32_e32 v185, 16, v3
	v_lshl_or_b32 v100, v4, 16, v182
	v_and_or_b32 v101, v4, s40, v183
	v_lshl_or_b32 v102, v5, 16, v184
	v_and_or_b32 v103, v5, s40, v185
	v_and_b32_e32 v182, 0xffff, v6
	v_lshrrev_b32_e32 v183, 16, v6
	v_and_b32_e32 v184, 0xffff, v7
	v_lshrrev_b32_e32 v185, 16, v7
	v_lshl_or_b32 v104, v8, 16, v182
	v_and_or_b32 v105, v8, s40, v183
	v_lshl_or_b32 v106, v9, 16, v184
	v_and_or_b32 v107, v9, s40, v185
	v_and_b32_e32 v182, 0xffff, v10
	v_lshrrev_b32_e32 v183, 16, v10
	v_and_b32_e32 v184, 0xffff, v11
	v_lshrrev_b32_e32 v185, 16, v11
	v_lshl_or_b32 v108, v12, 16, v182
	v_and_or_b32 v109, v12, s40, v183
	v_lshl_or_b32 v110, v13, 16, v184
	v_and_or_b32 v111, v13, s40, v185
	v_and_b32_e32 v182, 0xffff, v14
	v_lshrrev_b32_e32 v183, 16, v14
	v_and_b32_e32 v184, 0xffff, v15
	v_lshrrev_b32_e32 v185, 16, v15
	v_lshl_or_b32 v112, v16, 16, v182
	v_and_or_b32 v113, v16, s40, v183
	v_lshl_or_b32 v114, v17, 16, v184
	v_and_or_b32 v115, v17, s40, v185
	v_cmp_eq_u32_e32 vcc, 1, v174
	v_xor_b32_e32 v182, 0x80000000, v117
	v_xor_b32_e32 v183, 0x80000000, v119
	s_nop 1
	v_cndmask_b32_e32 v122, v182, v117, vcc
	v_cndmask_b32_e32 v123, v183, v119, vcc
.Lssm_tile_d1m2:
	s_waitcnt vmcnt(7)
	v_mfma_f32_32x32x16_bf16 v[16:31], v[80:83], v[84:87], 0
	v_mfma_f32_32x32x16_bf16 v[32:47], v[80:83], v[88:91], 0
	v_mfma_f32_32x32x16_bf16 v[48:63], v[80:83], v[92:95], 0
	v_mfma_f32_32x32x16_bf16 v[64:79], v[80:83], v[96:99], 0
	v_add_u32_e32 v171, s36, v155
	global_load_dwordx2 v[2:3], v154, s[34:35]
	global_load_dwordx2 v[4:5], v158, s[34:35]
	s_nop 11
	global_load_dwordx4 v[80:83], v150, s[10:11]
	s_sub_u32 s34, s34, 196608
	s_subb_u32 s35, s35, 0
	s_sub_u32 s10, s10, 196608
	s_subb_u32 s11, s11, 0
	v_permlane32_swap_b32_e32 v16, v48
	v_permlane32_swap_b32_e32 v17, v49
	v_permlane32_swap_b32_e32 v18, v50
	v_permlane32_swap_b32_e32 v19, v51
	v_permlane32_swap_b32_e32 v20, v52
	v_permlane32_swap_b32_e32 v21, v53
	v_permlane32_swap_b32_e32 v22, v54
	v_permlane32_swap_b32_e32 v23, v55
	v_permlane32_swap_b32_e32 v24, v56
	v_permlane32_swap_b32_e32 v25, v57
	v_permlane32_swap_b32_e32 v26, v58
	v_permlane32_swap_b32_e32 v27, v59
	v_permlane32_swap_b32_e32 v28, v60
	v_permlane32_swap_b32_e32 v29, v61
	v_permlane32_swap_b32_e32 v30, v62
	v_permlane32_swap_b32_e32 v31, v63
	v_permlane32_swap_b32_e32 v32, v64
	v_permlane32_swap_b32_e32 v33, v65
	v_permlane32_swap_b32_e32 v34, v66
	v_permlane32_swap_b32_e32 v35, v67
	v_permlane32_swap_b32_e32 v36, v68
	v_permlane32_swap_b32_e32 v37, v69
	v_permlane32_swap_b32_e32 v38, v70
	v_permlane32_swap_b32_e32 v39, v71
	v_permlane32_swap_b32_e32 v40, v72
	v_permlane32_swap_b32_e32 v41, v73
	v_permlane32_swap_b32_e32 v42, v74
	v_permlane32_swap_b32_e32 v43, v75
	v_permlane32_swap_b32_e32 v44, v76
	v_permlane32_swap_b32_e32 v45, v77
	v_permlane32_swap_b32_e32 v46, v78
	v_permlane32_swap_b32_e32 v47, v79
	v_fmac_f32_e32 v63, v116, v120
	v_fmac_f32_e32 v79, v118, v121
	v_fmac_f32_dpp v63, v120, v122 quad_perm:[1,0,3,2] row_mask:0xf bank_mask:0xf
	v_fmac_f32_dpp v79, v121, v123 quad_perm:[1,0,3,2] row_mask:0xf bank_mask:0xf
	v_cvt_pk_bf16_f32 v148, v63, v79
	ds_write_b32 v151, v148 offset:8432
	v_fmac_f32_e32 v62, v116, v63
	v_fmac_f32_e32 v78, v118, v79
	v_fmac_f32_dpp v62, v63, v122 quad_perm:[1,0,3,2] row_mask:0xf bank_mask:0xf
	v_fmac_f32_dpp v78, v79, v123 quad_perm:[1,0,3,2] row_mask:0xf bank_mask:0xf
	v_cvt_pk_bf16_f32 v149, v62, v78
	ds_write_b32 v151, v149 offset:8160
	v_fmac_f32_e32 v61, v116, v62
	v_fmac_f32_e32 v77, v118, v78
	v_fmac_f32_dpp v61, v62, v122 quad_perm:[1,0,3,2] row_mask:0xf bank_mask:0xf
	v_fmac_f32_dpp v77, v78, v123 quad_perm:[1,0,3,2] row_mask:0xf bank_mask:0xf
	v_cvt_pk_bf16_f32 v148, v61, v77
	ds_write_b32 v151, v148 offset:7888
	v_fmac_f32_e32 v60, v116, v61
	v_fmac_f32_e32 v76, v118, v77
	v_fmac_f32_dpp v60, v61, v122 quad_perm:[1,0,3,2] row_mask:0xf bank_mask:0xf
	v_fmac_f32_dpp v76, v77, v123 quad_perm:[1,0,3,2] row_mask:0xf bank_mask:0xf
	v_cvt_pk_bf16_f32 v149, v60, v76
	ds_write_b32 v151, v149 offset:7616
	v_fmac_f32_e32 v31, v116, v60
	v_fmac_f32_e32 v47, v118, v76
	v_fmac_f32_dpp v31, v60, v122 quad_perm:[1,0,3,2] row_mask:0xf bank_mask:0xf
	v_fmac_f32_dpp v47, v76, v123 quad_perm:[1,0,3,2] row_mask:0xf bank_mask:0xf
	v_cvt_pk_bf16_f32 v148, v31, v47
	ds_write_b32 v151, v148 offset:7344
	v_fmac_f32_e32 v30, v116, v31
	v_fmac_f32_e32 v46, v118, v47
	v_fmac_f32_dpp v30, v31, v122 quad_perm:[1,0,3,2] row_mask:0xf bank_mask:0xf
	v_fmac_f32_dpp v46, v47, v123 quad_perm:[1,0,3,2] row_mask:0xf bank_mask:0xf
	v_cvt_pk_bf16_f32 v149, v30, v46
	ds_write_b32 v151, v149 offset:7072
	v_fmac_f32_e32 v29, v116, v30
	v_fmac_f32_e32 v45, v118, v46
	v_fmac_f32_dpp v29, v30, v122 quad_perm:[1,0,3,2] row_mask:0xf bank_mask:0xf
	v_fmac_f32_dpp v45, v46, v123 quad_perm:[1,0,3,2] row_mask:0xf bank_mask:0xf
	v_cvt_pk_bf16_f32 v148, v29, v45
	ds_write_b32 v151, v148 offset:6800
	v_fmac_f32_e32 v28, v116, v29
	v_fmac_f32_e32 v44, v118, v45
	v_fmac_f32_dpp v28, v29, v122 quad_perm:[1,0,3,2] row_mask:0xf bank_mask:0xf
	v_fmac_f32_dpp v44, v45, v123 quad_perm:[1,0,3,2] row_mask:0xf bank_mask:0xf
	v_cvt_pk_bf16_f32 v149, v28, v44
	ds_write_b32 v151, v149 offset:6528
	v_fmac_f32_e32 v59, v116, v28
	v_fmac_f32_e32 v75, v118, v44
	v_fmac_f32_dpp v59, v28, v122 quad_perm:[1,0,3,2] row_mask:0xf bank_mask:0xf
	v_fmac_f32_dpp v75, v44, v123 quad_perm:[1,0,3,2] row_mask:0xf bank_mask:0xf
	v_cvt_pk_bf16_f32 v148, v59, v75
	ds_write_b32 v151, v148 offset:6256
	v_fmac_f32_e32 v58, v116, v59
	v_fmac_f32_e32 v74, v118, v75
	v_fmac_f32_dpp v58, v59, v122 quad_perm:[1,0,3,2] row_mask:0xf bank_mask:0xf
	v_fmac_f32_dpp v74, v75, v123 quad_perm:[1,0,3,2] row_mask:0xf bank_mask:0xf
	v_cvt_pk_bf16_f32 v149, v58, v74
	ds_write_b32 v151, v149 offset:5984
	v_fmac_f32_e32 v57, v116, v58
	v_fmac_f32_e32 v73, v118, v74
	v_fmac_f32_dpp v57, v58, v122 quad_perm:[1,0,3,2] row_mask:0xf bank_mask:0xf
	v_fmac_f32_dpp v73, v74, v123 quad_perm:[1,0,3,2] row_mask:0xf bank_mask:0xf
	v_cvt_pk_bf16_f32 v148, v57, v73
	ds_write_b32 v151, v148 offset:5712
	v_fmac_f32_e32 v56, v116, v57
	v_fmac_f32_e32 v72, v118, v73
	v_fmac_f32_dpp v56, v57, v122 quad_perm:[1,0,3,2] row_mask:0xf bank_mask:0xf
	v_fmac_f32_dpp v72, v73, v123 quad_perm:[1,0,3,2] row_mask:0xf bank_mask:0xf
	v_cvt_pk_bf16_f32 v149, v56, v72
	ds_write_b32 v151, v149 offset:5440
	v_fmac_f32_e32 v27, v116, v56
	v_fmac_f32_e32 v43, v118, v72
	v_fmac_f32_dpp v27, v56, v122 quad_perm:[1,0,3,2] row_mask:0xf bank_mask:0xf
	v_fmac_f32_dpp v43, v72, v123 quad_perm:[1,0,3,2] row_mask:0xf bank_mask:0xf
	v_cvt_pk_bf16_f32 v148, v27, v43
	ds_write_b32 v151, v148 offset:5168
	v_fmac_f32_e32 v26, v116, v27
	v_fmac_f32_e32 v42, v118, v43
	v_fmac_f32_dpp v26, v27, v122 quad_perm:[1,0,3,2] row_mask:0xf bank_mask:0xf
	v_fmac_f32_dpp v42, v43, v123 quad_perm:[1,0,3,2] row_mask:0xf bank_mask:0xf
	v_cvt_pk_bf16_f32 v149, v26, v42
	ds_write_b32 v151, v149 offset:4896
	v_fmac_f32_e32 v25, v116, v26
	v_fmac_f32_e32 v41, v118, v42
	v_fmac_f32_dpp v25, v26, v122 quad_perm:[1,0,3,2] row_mask:0xf bank_mask:0xf
	v_fmac_f32_dpp v41, v42, v123 quad_perm:[1,0,3,2] row_mask:0xf bank_mask:0xf
	v_cvt_pk_bf16_f32 v148, v25, v41
	ds_write_b32 v151, v148 offset:4624
	v_fmac_f32_e32 v24, v116, v25
	v_fmac_f32_e32 v40, v118, v41
	v_fmac_f32_dpp v24, v25, v122 quad_perm:[1,0,3,2] row_mask:0xf bank_mask:0xf
	v_fmac_f32_dpp v40, v41, v123 quad_perm:[1,0,3,2] row_mask:0xf bank_mask:0xf
	v_cvt_pk_bf16_f32 v149, v24, v40
	ds_write_b32 v151, v149 offset:4352
	v_fmac_f32_e32 v55, v116, v24
	v_fmac_f32_e32 v71, v118, v40
	v_fmac_f32_dpp v55, v24, v122 quad_perm:[1,0,3,2] row_mask:0xf bank_mask:0xf
	v_fmac_f32_dpp v71, v40, v123 quad_perm:[1,0,3,2] row_mask:0xf bank_mask:0xf
	v_cvt_pk_bf16_f32 v148, v55, v71
	ds_write_b32 v151, v148 offset:4080
	v_fmac_f32_e32 v54, v116, v55
	v_fmac_f32_e32 v70, v118, v71
	v_fmac_f32_dpp v54, v55, v122 quad_perm:[1,0,3,2] row_mask:0xf bank_mask:0xf
	v_fmac_f32_dpp v70, v71, v123 quad_perm:[1,0,3,2] row_mask:0xf bank_mask:0xf
	v_cvt_pk_bf16_f32 v149, v54, v70
	ds_write_b32 v151, v149 offset:3808
	v_fmac_f32_e32 v53, v116, v54
	v_fmac_f32_e32 v69, v118, v70
	v_fmac_f32_dpp v53, v54, v122 quad_perm:[1,0,3,2] row_mask:0xf bank_mask:0xf
	v_fmac_f32_dpp v69, v70, v123 quad_perm:[1,0,3,2] row_mask:0xf bank_mask:0xf
	v_cvt_pk_bf16_f32 v148, v53, v69
	ds_write_b32 v151, v148 offset:3536
	v_fmac_f32_e32 v52, v116, v53
	v_fmac_f32_e32 v68, v118, v69
	v_fmac_f32_dpp v52, v53, v122 quad_perm:[1,0,3,2] row_mask:0xf bank_mask:0xf
	v_fmac_f32_dpp v68, v69, v123 quad_perm:[1,0,3,2] row_mask:0xf bank_mask:0xf
	v_cvt_pk_bf16_f32 v149, v52, v68
	ds_write_b32 v151, v149 offset:3264
	v_fmac_f32_e32 v23, v116, v52
	v_fmac_f32_e32 v39, v118, v68
	v_fmac_f32_dpp v23, v52, v122 quad_perm:[1,0,3,2] row_mask:0xf bank_mask:0xf
	v_fmac_f32_dpp v39, v68, v123 quad_perm:[1,0,3,2] row_mask:0xf bank_mask:0xf
	v_cvt_pk_bf16_f32 v148, v23, v39
	ds_write_b32 v151, v148 offset:2992
	v_fmac_f32_e32 v22, v116, v23
	v_fmac_f32_e32 v38, v118, v39
	v_fmac_f32_dpp v22, v23, v122 quad_perm:[1,0,3,2] row_mask:0xf bank_mask:0xf
	v_fmac_f32_dpp v38, v39, v123 quad_perm:[1,0,3,2] row_mask:0xf bank_mask:0xf
	v_cvt_pk_bf16_f32 v149, v22, v38
	ds_write_b32 v151, v149 offset:2720
	v_fmac_f32_e32 v21, v116, v22
	v_fmac_f32_e32 v37, v118, v38
	v_fmac_f32_dpp v21, v22, v122 quad_perm:[1,0,3,2] row_mask:0xf bank_mask:0xf
	v_fmac_f32_dpp v37, v38, v123 quad_perm:[1,0,3,2] row_mask:0xf bank_mask:0xf
	v_cvt_pk_bf16_f32 v148, v21, v37
	ds_write_b32 v151, v148 offset:2448
	v_fmac_f32_e32 v20, v116, v21
	v_fmac_f32_e32 v36, v118, v37
	v_fmac_f32_dpp v20, v21, v122 quad_perm:[1,0,3,2] row_mask:0xf bank_mask:0xf
	v_fmac_f32_dpp v36, v37, v123 quad_perm:[1,0,3,2] row_mask:0xf bank_mask:0xf
	v_cvt_pk_bf16_f32 v149, v20, v36
	ds_write_b32 v151, v149 offset:2176
	v_fmac_f32_e32 v51, v116, v20
	v_fmac_f32_e32 v67, v118, v36
	v_fmac_f32_dpp v51, v20, v122 quad_perm:[1,0,3,2] row_mask:0xf bank_mask:0xf
	v_fmac_f32_dpp v67, v36, v123 quad_perm:[1,0,3,2] row_mask:0xf bank_mask:0xf
	v_cvt_pk_bf16_f32 v148, v51, v67
	ds_write_b32 v151, v148 offset:1904
	v_fmac_f32_e32 v50, v116, v51
	v_fmac_f32_e32 v66, v118, v67
	v_fmac_f32_dpp v50, v51, v122 quad_perm:[1,0,3,2] row_mask:0xf bank_mask:0xf
	v_fmac_f32_dpp v66, v67, v123 quad_perm:[1,0,3,2] row_mask:0xf bank_mask:0xf
	v_cvt_pk_bf16_f32 v149, v50, v66
	ds_write_b32 v151, v149 offset:1632
	v_fmac_f32_e32 v49, v116, v50
	v_fmac_f32_e32 v65, v118, v66
	v_fmac_f32_dpp v49, v50, v122 quad_perm:[1,0,3,2] row_mask:0xf bank_mask:0xf
	v_fmac_f32_dpp v65, v66, v123 quad_perm:[1,0,3,2] row_mask:0xf bank_mask:0xf
	v_cvt_pk_bf16_f32 v148, v49, v65
	ds_write_b32 v151, v148 offset:1360
	v_fmac_f32_e32 v48, v116, v49
	v_fmac_f32_e32 v64, v118, v65
	v_fmac_f32_dpp v48, v49, v122 quad_perm:[1,0,3,2] row_mask:0xf bank_mask:0xf
	v_fmac_f32_dpp v64, v65, v123 quad_perm:[1,0,3,2] row_mask:0xf bank_mask:0xf
	v_cvt_pk_bf16_f32 v149, v48, v64
	ds_write_b32 v151, v149 offset:1088
	v_fmac_f32_e32 v19, v116, v48
	v_fmac_f32_e32 v35, v118, v64
	v_fmac_f32_dpp v19, v48, v122 quad_perm:[1,0,3,2] row_mask:0xf bank_mask:0xf
	v_fmac_f32_dpp v35, v64, v123 quad_perm:[1,0,3,2] row_mask:0xf bank_mask:0xf
	v_cvt_pk_bf16_f32 v148, v19, v35
	ds_write_b32 v151, v148 offset:816
	v_fmac_f32_e32 v18, v116, v19
	v_fmac_f32_e32 v34, v118, v35
	v_fmac_f32_dpp v18, v19, v122 quad_perm:[1,0,3,2] row_mask:0xf bank_mask:0xf
	v_fmac_f32_dpp v34, v35, v123 quad_perm:[1,0,3,2] row_mask:0xf bank_mask:0xf
	v_cvt_pk_bf16_f32 v149, v18, v34
	ds_write_b32 v151, v149 offset:544
	v_fmac_f32_e32 v17, v116, v18
	v_fmac_f32_e32 v33, v118, v34
	v_fmac_f32_dpp v17, v18, v122 quad_perm:[1,0,3,2] row_mask:0xf bank_mask:0xf
	v_fmac_f32_dpp v33, v34, v123 quad_perm:[1,0,3,2] row_mask:0xf bank_mask:0xf
	v_cvt_pk_bf16_f32 v148, v17, v33
	ds_write_b32 v151, v148 offset:272
	v_fmac_f32_e32 v16, v116, v17
	v_fmac_f32_e32 v32, v118, v33
	v_fmac_f32_dpp v16, v17, v122 quad_perm:[1,0,3,2] row_mask:0xf bank_mask:0xf
	v_fmac_f32_dpp v32, v33, v123 quad_perm:[1,0,3,2] row_mask:0xf bank_mask:0xf
	v_cvt_pk_bf16_f32 v149, v16, v32
	ds_write_b32 v151, v149
	v_mov_b32_e32 v120, v16
	v_mov_b32_e32 v121, v32
	ds_read_b128 v[124:127], v152
	ds_read_b128 v[128:131], v152 offset:64
	ds_read_b128 v[132:135], v152 offset:128
	ds_read_b128 v[136:139], v152 offset:192
	ds_read_b64 v[168:169], v171
	s_waitcnt lgkmcnt(4)
	v_mfma_f32_16x16x32_bf16 v[140:143], v[100:103], v[124:127], 0
	s_waitcnt lgkmcnt(3)
	v_mfma_f32_16x16x32_bf16 v[140:143], v[104:107], v[128:131], v[140:143]
	s_waitcnt lgkmcnt(2)
	v_mfma_f32_16x16x32_bf16 v[140:143], v[108:111], v[132:135], v[140:143]
	s_waitcnt lgkmcnt(1)
	v_mfma_f32_16x16x32_bf16 v[140:143], v[112:115], v[136:139], v[140:143]
	s_nop 9
	s_waitcnt vmcnt(6) lgkmcnt(0)
	v_lshlrev_b32_e32 v182, 16, v168
	v_and_b32_e32 v183, 0xffff0000, v168
	v_lshlrev_b32_e32 v184, 16, v169
	v_and_b32_e32 v185, 0xffff0000, v169
	v_lshlrev_b32_e32 v186, 16, v160
	v_and_b32_e32 v187, 0xffff0000, v160
	v_lshlrev_b32_e32 v188, 16, v161
	v_and_b32_e32 v189, 0xffff0000, v161
	v_add_f32_e32 v182, v182, v140
	v_add_f32_e32 v183, v183, v141
	v_add_f32_e32 v184, v184, v142
	v_add_f32_e32 v185, v185, v143
	v_fmac_f32_e32 v182, v164, v186
	v_fmac_f32_e32 v183, v165, v187
	v_fmac_f32_e32 v184, v166, v188
	v_fmac_f32_e32 v185, v167, v189
	v_mul_f32_e32 v186, 0x3d372713, v182
	v_mul_f32_e32 v187, 0x3d372713, v183
	v_mul_f32_e32 v188, 0x3d372713, v184
	v_mul_f32_e32 v189, 0x3d372713, v185
	v_mul_f32_e32 v186, v182, v186
	v_mul_f32_e32 v187, v183, v187
	v_mul_f32_e32 v188, v184, v188
	v_mul_f32_e32 v189, v185, v189
	v_fma_f32 v186, v182, v186, v182
	v_fma_f32 v187, v183, v187, v183
	v_fma_f32 v188, v184, v188, v184
	v_fma_f32 v189, v185, v189, v185
	v_mul_f32_e32 v186, 0xbfcc422a, v186
	v_mul_f32_e32 v187, 0xbfcc422a, v187
	v_mul_f32_e32 v188, 0xbfcc422a, v188
	v_mul_f32_e32 v189, 0xbfcc422a, v189
	v_mul_f32_e32 v186, 0x3fb8aa3b, v186
	v_mul_f32_e32 v187, 0x3fb8aa3b, v187
	v_mul_f32_e32 v188, 0x3fb8aa3b, v188
	v_mul_f32_e32 v189, 0x3fb8aa3b, v189
	v_exp_f32_e32 v186, v186
	v_exp_f32_e32 v187, v187
	v_exp_f32_e32 v188, v188
	v_exp_f32_e32 v189, v189
	v_add_f32_e32 v186, 1.0, v186
	v_add_f32_e32 v187, 1.0, v187
	v_add_f32_e32 v188, 1.0, v188
	v_add_f32_e32 v189, 1.0, v189
	v_rcp_f32_e32 v186, v186
	v_rcp_f32_e32 v187, v187
	v_rcp_f32_e32 v188, v188
	v_rcp_f32_e32 v189, v189
	v_mul_f32_e32 v182, v182, v186
	v_mul_f32_e32 v183, v183, v187
	v_mul_f32_e32 v184, v184, v188
	v_mul_f32_e32 v185, v185, v189
	v_cvt_pk_bf16_f32 v148, v182, v183
	v_cvt_pk_bf16_f32 v149, v184, v185
	global_store_dwordx2 v156, v[148:149], s[12:13]
	ds_read_b128 v[124:127], v152 offset:4352
	ds_read_b128 v[128:131], v152 offset:4416
	ds_read_b128 v[132:135], v152 offset:4480
	ds_read_b128 v[136:139], v152 offset:4544
	ds_read_b64 v[168:169], v171 offset:512
	s_waitcnt lgkmcnt(4)
	v_mfma_f32_16x16x32_bf16 v[140:143], v[100:103], v[124:127], 0
	s_waitcnt lgkmcnt(3)
	v_mfma_f32_16x16x32_bf16 v[140:143], v[104:107], v[128:131], v[140:143]
	s_waitcnt lgkmcnt(2)
	v_mfma_f32_16x16x32_bf16 v[140:143], v[108:111], v[132:135], v[140:143]
	s_waitcnt lgkmcnt(1)
	v_mfma_f32_16x16x32_bf16 v[140:143], v[112:115], v[136:139], v[140:143]
	s_nop 9
	s_waitcnt vmcnt(7) lgkmcnt(0)
	v_lshlrev_b32_e32 v182, 16, v168
	v_and_b32_e32 v183, 0xffff0000, v168
	v_lshlrev_b32_e32 v184, 16, v169
	v_and_b32_e32 v185, 0xffff0000, v169
	v_lshlrev_b32_e32 v186, 16, v162
	v_and_b32_e32 v187, 0xffff0000, v162
	v_lshlrev_b32_e32 v188, 16, v163
	v_and_b32_e32 v189, 0xffff0000, v163
	v_add_f32_e32 v182, v182, v140
	v_add_f32_e32 v183, v183, v141
	v_add_f32_e32 v184, v184, v142
	v_add_f32_e32 v185, v185, v143
	v_fmac_f32_e32 v182, v164, v186
	v_fmac_f32_e32 v183, v165, v187
	v_fmac_f32_e32 v184, v166, v188
	v_fmac_f32_e32 v185, v167, v189
	v_mul_f32_e32 v186, 0x3d372713, v182
	v_mul_f32_e32 v187, 0x3d372713, v183
	v_mul_f32_e32 v188, 0x3d372713, v184
	v_mul_f32_e32 v189, 0x3d372713, v185
	v_mul_f32_e32 v186, v182, v186
	v_mul_f32_e32 v187, v183, v187
	v_mul_f32_e32 v188, v184, v188
	v_mul_f32_e32 v189, v185, v189
	v_fma_f32 v186, v182, v186, v182
	v_fma_f32 v187, v183, v187, v183
	v_fma_f32 v188, v184, v188, v184
	v_fma_f32 v189, v185, v189, v185
	v_mul_f32_e32 v186, 0xbfcc422a, v186
	v_mul_f32_e32 v187, 0xbfcc422a, v187
	v_mul_f32_e32 v188, 0xbfcc422a, v188
	v_mul_f32_e32 v189, 0xbfcc422a, v189
	v_mul_f32_e32 v186, 0x3fb8aa3b, v186
	v_mul_f32_e32 v187, 0x3fb8aa3b, v187
	v_mul_f32_e32 v188, 0x3fb8aa3b, v188
	v_mul_f32_e32 v189, 0x3fb8aa3b, v189
	v_exp_f32_e32 v186, v186
	v_exp_f32_e32 v187, v187
	v_exp_f32_e32 v188, v188
	v_exp_f32_e32 v189, v189
	v_add_f32_e32 v186, 1.0, v186
	v_add_f32_e32 v187, 1.0, v187
	v_add_f32_e32 v188, 1.0, v188
	v_add_f32_e32 v189, 1.0, v189
	v_rcp_f32_e32 v186, v186
	v_rcp_f32_e32 v187, v187
	v_rcp_f32_e32 v188, v188
	v_rcp_f32_e32 v189, v189
	v_mul_f32_e32 v182, v182, v186
	v_mul_f32_e32 v183, v183, v187
	v_mul_f32_e32 v184, v184, v188
	v_mul_f32_e32 v185, v185, v189
	v_cvt_pk_bf16_f32 v148, v182, v183
	v_cvt_pk_bf16_f32 v149, v184, v185
	global_store_dwordx2 v159, v[148:149], s[12:13]
	s_sub_u32 s12, s12, 65536
	s_subb_u32 s13, s13, 0
	s_sub_u32 s36, s36, 1024
	s_waitcnt vmcnt(7)
	v_mfma_f32_32x32x16_bf16 v[16:31], v[144:147], v[84:87], 0
	v_mfma_f32_32x32x16_bf16 v[32:47], v[144:147], v[88:91], 0
	v_mfma_f32_32x32x16_bf16 v[48:63], v[144:147], v[92:95], 0
	v_mfma_f32_32x32x16_bf16 v[64:79], v[144:147], v[96:99], 0
	v_add_u32_e32 v171, s36, v155
	global_load_dwordx2 v[160:161], v154, s[34:35]
	global_load_dwordx2 v[162:163], v158, s[34:35]
	s_nop 11
	global_load_dwordx4 v[144:147], v150, s[10:11]
	s_sub_u32 s34, s34, 196608
	s_subb_u32 s35, s35, 0
	s_sub_u32 s10, s10, 196608
	s_subb_u32 s11, s11, 0
	v_permlane32_swap_b32_e32 v16, v48
	v_permlane32_swap_b32_e32 v17, v49
	v_permlane32_swap_b32_e32 v18, v50
	v_permlane32_swap_b32_e32 v19, v51
	v_permlane32_swap_b32_e32 v20, v52
	v_permlane32_swap_b32_e32 v21, v53
	v_permlane32_swap_b32_e32 v22, v54
	v_permlane32_swap_b32_e32 v23, v55
	v_permlane32_swap_b32_e32 v24, v56
	v_permlane32_swap_b32_e32 v25, v57
	v_permlane32_swap_b32_e32 v26, v58
	v_permlane32_swap_b32_e32 v27, v59
	v_permlane32_swap_b32_e32 v28, v60
	v_permlane32_swap_b32_e32 v29, v61
	v_permlane32_swap_b32_e32 v30, v62
	v_permlane32_swap_b32_e32 v31, v63
	v_permlane32_swap_b32_e32 v32, v64
	v_permlane32_swap_b32_e32 v33, v65
	v_permlane32_swap_b32_e32 v34, v66
	v_permlane32_swap_b32_e32 v35, v67
	v_permlane32_swap_b32_e32 v36, v68
	v_permlane32_swap_b32_e32 v37, v69
	v_permlane32_swap_b32_e32 v38, v70
	v_permlane32_swap_b32_e32 v39, v71
	v_permlane32_swap_b32_e32 v40, v72
	v_permlane32_swap_b32_e32 v41, v73
	v_permlane32_swap_b32_e32 v42, v74
	v_permlane32_swap_b32_e32 v43, v75
	v_permlane32_swap_b32_e32 v44, v76
	v_permlane32_swap_b32_e32 v45, v77
	v_permlane32_swap_b32_e32 v46, v78
	v_permlane32_swap_b32_e32 v47, v79
	v_fmac_f32_e32 v63, v116, v120
	v_fmac_f32_e32 v79, v118, v121
	v_fmac_f32_dpp v63, v120, v122 quad_perm:[1,0,3,2] row_mask:0xf bank_mask:0xf
	v_fmac_f32_dpp v79, v121, v123 quad_perm:[1,0,3,2] row_mask:0xf bank_mask:0xf
	v_cvt_pk_bf16_f32 v148, v63, v79
	ds_write_b32 v151, v148 offset:8432
	v_fmac_f32_e32 v62, v116, v63
	v_fmac_f32_e32 v78, v118, v79
	v_fmac_f32_dpp v62, v63, v122 quad_perm:[1,0,3,2] row_mask:0xf bank_mask:0xf
	v_fmac_f32_dpp v78, v79, v123 quad_perm:[1,0,3,2] row_mask:0xf bank_mask:0xf
	v_cvt_pk_bf16_f32 v149, v62, v78
	ds_write_b32 v151, v149 offset:8160
	v_fmac_f32_e32 v61, v116, v62
	v_fmac_f32_e32 v77, v118, v78
	v_fmac_f32_dpp v61, v62, v122 quad_perm:[1,0,3,2] row_mask:0xf bank_mask:0xf
	v_fmac_f32_dpp v77, v78, v123 quad_perm:[1,0,3,2] row_mask:0xf bank_mask:0xf
	v_cvt_pk_bf16_f32 v148, v61, v77
	ds_write_b32 v151, v148 offset:7888
	v_fmac_f32_e32 v60, v116, v61
	v_fmac_f32_e32 v76, v118, v77
	v_fmac_f32_dpp v60, v61, v122 quad_perm:[1,0,3,2] row_mask:0xf bank_mask:0xf
	v_fmac_f32_dpp v76, v77, v123 quad_perm:[1,0,3,2] row_mask:0xf bank_mask:0xf
	v_cvt_pk_bf16_f32 v149, v60, v76
	ds_write_b32 v151, v149 offset:7616
	v_fmac_f32_e32 v31, v116, v60
	v_fmac_f32_e32 v47, v118, v76
	v_fmac_f32_dpp v31, v60, v122 quad_perm:[1,0,3,2] row_mask:0xf bank_mask:0xf
	v_fmac_f32_dpp v47, v76, v123 quad_perm:[1,0,3,2] row_mask:0xf bank_mask:0xf
	v_cvt_pk_bf16_f32 v148, v31, v47
	ds_write_b32 v151, v148 offset:7344
	v_fmac_f32_e32 v30, v116, v31
	v_fmac_f32_e32 v46, v118, v47
	v_fmac_f32_dpp v30, v31, v122 quad_perm:[1,0,3,2] row_mask:0xf bank_mask:0xf
	v_fmac_f32_dpp v46, v47, v123 quad_perm:[1,0,3,2] row_mask:0xf bank_mask:0xf
	v_cvt_pk_bf16_f32 v149, v30, v46
	ds_write_b32 v151, v149 offset:7072
	v_fmac_f32_e32 v29, v116, v30
	v_fmac_f32_e32 v45, v118, v46
	v_fmac_f32_dpp v29, v30, v122 quad_perm:[1,0,3,2] row_mask:0xf bank_mask:0xf
	v_fmac_f32_dpp v45, v46, v123 quad_perm:[1,0,3,2] row_mask:0xf bank_mask:0xf
	v_cvt_pk_bf16_f32 v148, v29, v45
	ds_write_b32 v151, v148 offset:6800
	v_fmac_f32_e32 v28, v116, v29
	v_fmac_f32_e32 v44, v118, v45
	v_fmac_f32_dpp v28, v29, v122 quad_perm:[1,0,3,2] row_mask:0xf bank_mask:0xf
	v_fmac_f32_dpp v44, v45, v123 quad_perm:[1,0,3,2] row_mask:0xf bank_mask:0xf
	v_cvt_pk_bf16_f32 v149, v28, v44
	ds_write_b32 v151, v149 offset:6528
	v_fmac_f32_e32 v59, v116, v28
	v_fmac_f32_e32 v75, v118, v44
	v_fmac_f32_dpp v59, v28, v122 quad_perm:[1,0,3,2] row_mask:0xf bank_mask:0xf
	v_fmac_f32_dpp v75, v44, v123 quad_perm:[1,0,3,2] row_mask:0xf bank_mask:0xf
	v_cvt_pk_bf16_f32 v148, v59, v75
	ds_write_b32 v151, v148 offset:6256
	v_fmac_f32_e32 v58, v116, v59
	v_fmac_f32_e32 v74, v118, v75
	v_fmac_f32_dpp v58, v59, v122 quad_perm:[1,0,3,2] row_mask:0xf bank_mask:0xf
	v_fmac_f32_dpp v74, v75, v123 quad_perm:[1,0,3,2] row_mask:0xf bank_mask:0xf
	v_cvt_pk_bf16_f32 v149, v58, v74
	ds_write_b32 v151, v149 offset:5984
	v_fmac_f32_e32 v57, v116, v58
	v_fmac_f32_e32 v73, v118, v74
	v_fmac_f32_dpp v57, v58, v122 quad_perm:[1,0,3,2] row_mask:0xf bank_mask:0xf
	v_fmac_f32_dpp v73, v74, v123 quad_perm:[1,0,3,2] row_mask:0xf bank_mask:0xf
	v_cvt_pk_bf16_f32 v148, v57, v73
	ds_write_b32 v151, v148 offset:5712
	v_fmac_f32_e32 v56, v116, v57
	v_fmac_f32_e32 v72, v118, v73
	v_fmac_f32_dpp v56, v57, v122 quad_perm:[1,0,3,2] row_mask:0xf bank_mask:0xf
	v_fmac_f32_dpp v72, v73, v123 quad_perm:[1,0,3,2] row_mask:0xf bank_mask:0xf
	v_cvt_pk_bf16_f32 v149, v56, v72
	ds_write_b32 v151, v149 offset:5440
	v_fmac_f32_e32 v27, v116, v56
	v_fmac_f32_e32 v43, v118, v72
	v_fmac_f32_dpp v27, v56, v122 quad_perm:[1,0,3,2] row_mask:0xf bank_mask:0xf
	v_fmac_f32_dpp v43, v72, v123 quad_perm:[1,0,3,2] row_mask:0xf bank_mask:0xf
	v_cvt_pk_bf16_f32 v148, v27, v43
	ds_write_b32 v151, v148 offset:5168
	v_fmac_f32_e32 v26, v116, v27
	v_fmac_f32_e32 v42, v118, v43
	v_fmac_f32_dpp v26, v27, v122 quad_perm:[1,0,3,2] row_mask:0xf bank_mask:0xf
	v_fmac_f32_dpp v42, v43, v123 quad_perm:[1,0,3,2] row_mask:0xf bank_mask:0xf
	v_cvt_pk_bf16_f32 v149, v26, v42
	ds_write_b32 v151, v149 offset:4896
	v_fmac_f32_e32 v25, v116, v26
	v_fmac_f32_e32 v41, v118, v42
	v_fmac_f32_dpp v25, v26, v122 quad_perm:[1,0,3,2] row_mask:0xf bank_mask:0xf
	v_fmac_f32_dpp v41, v42, v123 quad_perm:[1,0,3,2] row_mask:0xf bank_mask:0xf
	v_cvt_pk_bf16_f32 v148, v25, v41
	ds_write_b32 v151, v148 offset:4624
	v_fmac_f32_e32 v24, v116, v25
	v_fmac_f32_e32 v40, v118, v41
	v_fmac_f32_dpp v24, v25, v122 quad_perm:[1,0,3,2] row_mask:0xf bank_mask:0xf
	v_fmac_f32_dpp v40, v41, v123 quad_perm:[1,0,3,2] row_mask:0xf bank_mask:0xf
	v_cvt_pk_bf16_f32 v149, v24, v40
	ds_write_b32 v151, v149 offset:4352
	v_fmac_f32_e32 v55, v116, v24
	v_fmac_f32_e32 v71, v118, v40
	v_fmac_f32_dpp v55, v24, v122 quad_perm:[1,0,3,2] row_mask:0xf bank_mask:0xf
	v_fmac_f32_dpp v71, v40, v123 quad_perm:[1,0,3,2] row_mask:0xf bank_mask:0xf
	v_cvt_pk_bf16_f32 v148, v55, v71
	ds_write_b32 v151, v148 offset:4080
	v_fmac_f32_e32 v54, v116, v55
	v_fmac_f32_e32 v70, v118, v71
	v_fmac_f32_dpp v54, v55, v122 quad_perm:[1,0,3,2] row_mask:0xf bank_mask:0xf
	v_fmac_f32_dpp v70, v71, v123 quad_perm:[1,0,3,2] row_mask:0xf bank_mask:0xf
	v_cvt_pk_bf16_f32 v149, v54, v70
	ds_write_b32 v151, v149 offset:3808
	v_fmac_f32_e32 v53, v116, v54
	v_fmac_f32_e32 v69, v118, v70
	v_fmac_f32_dpp v53, v54, v122 quad_perm:[1,0,3,2] row_mask:0xf bank_mask:0xf
	v_fmac_f32_dpp v69, v70, v123 quad_perm:[1,0,3,2] row_mask:0xf bank_mask:0xf
	v_cvt_pk_bf16_f32 v148, v53, v69
	ds_write_b32 v151, v148 offset:3536
	v_fmac_f32_e32 v52, v116, v53
	v_fmac_f32_e32 v68, v118, v69
	v_fmac_f32_dpp v52, v53, v122 quad_perm:[1,0,3,2] row_mask:0xf bank_mask:0xf
	v_fmac_f32_dpp v68, v69, v123 quad_perm:[1,0,3,2] row_mask:0xf bank_mask:0xf
	v_cvt_pk_bf16_f32 v149, v52, v68
	ds_write_b32 v151, v149 offset:3264
	v_fmac_f32_e32 v23, v116, v52
	v_fmac_f32_e32 v39, v118, v68
	v_fmac_f32_dpp v23, v52, v122 quad_perm:[1,0,3,2] row_mask:0xf bank_mask:0xf
	v_fmac_f32_dpp v39, v68, v123 quad_perm:[1,0,3,2] row_mask:0xf bank_mask:0xf
	v_cvt_pk_bf16_f32 v148, v23, v39
	ds_write_b32 v151, v148 offset:2992
	v_fmac_f32_e32 v22, v116, v23
	v_fmac_f32_e32 v38, v118, v39
	v_fmac_f32_dpp v22, v23, v122 quad_perm:[1,0,3,2] row_mask:0xf bank_mask:0xf
	v_fmac_f32_dpp v38, v39, v123 quad_perm:[1,0,3,2] row_mask:0xf bank_mask:0xf
	v_cvt_pk_bf16_f32 v149, v22, v38
	ds_write_b32 v151, v149 offset:2720
	v_fmac_f32_e32 v21, v116, v22
	v_fmac_f32_e32 v37, v118, v38
	v_fmac_f32_dpp v21, v22, v122 quad_perm:[1,0,3,2] row_mask:0xf bank_mask:0xf
	v_fmac_f32_dpp v37, v38, v123 quad_perm:[1,0,3,2] row_mask:0xf bank_mask:0xf
	v_cvt_pk_bf16_f32 v148, v21, v37
	ds_write_b32 v151, v148 offset:2448
	v_fmac_f32_e32 v20, v116, v21
	v_fmac_f32_e32 v36, v118, v37
	v_fmac_f32_dpp v20, v21, v122 quad_perm:[1,0,3,2] row_mask:0xf bank_mask:0xf
	v_fmac_f32_dpp v36, v37, v123 quad_perm:[1,0,3,2] row_mask:0xf bank_mask:0xf
	v_cvt_pk_bf16_f32 v149, v20, v36
	ds_write_b32 v151, v149 offset:2176
	v_fmac_f32_e32 v51, v116, v20
	v_fmac_f32_e32 v67, v118, v36
	v_fmac_f32_dpp v51, v20, v122 quad_perm:[1,0,3,2] row_mask:0xf bank_mask:0xf
	v_fmac_f32_dpp v67, v36, v123 quad_perm:[1,0,3,2] row_mask:0xf bank_mask:0xf
	v_cvt_pk_bf16_f32 v148, v51, v67
	ds_write_b32 v151, v148 offset:1904
	v_fmac_f32_e32 v50, v116, v51
	v_fmac_f32_e32 v66, v118, v67
	v_fmac_f32_dpp v50, v51, v122 quad_perm:[1,0,3,2] row_mask:0xf bank_mask:0xf
	v_fmac_f32_dpp v66, v67, v123 quad_perm:[1,0,3,2] row_mask:0xf bank_mask:0xf
	v_cvt_pk_bf16_f32 v149, v50, v66
	ds_write_b32 v151, v149 offset:1632
	v_fmac_f32_e32 v49, v116, v50
	v_fmac_f32_e32 v65, v118, v66
	v_fmac_f32_dpp v49, v50, v122 quad_perm:[1,0,3,2] row_mask:0xf bank_mask:0xf
	v_fmac_f32_dpp v65, v66, v123 quad_perm:[1,0,3,2] row_mask:0xf bank_mask:0xf
	v_cvt_pk_bf16_f32 v148, v49, v65
	ds_write_b32 v151, v148 offset:1360
	v_fmac_f32_e32 v48, v116, v49
	v_fmac_f32_e32 v64, v118, v65
	v_fmac_f32_dpp v48, v49, v122 quad_perm:[1,0,3,2] row_mask:0xf bank_mask:0xf
	v_fmac_f32_dpp v64, v65, v123 quad_perm:[1,0,3,2] row_mask:0xf bank_mask:0xf
	v_cvt_pk_bf16_f32 v149, v48, v64
	ds_write_b32 v151, v149 offset:1088
	v_fmac_f32_e32 v19, v116, v48
	v_fmac_f32_e32 v35, v118, v64
	v_fmac_f32_dpp v19, v48, v122 quad_perm:[1,0,3,2] row_mask:0xf bank_mask:0xf
	v_fmac_f32_dpp v35, v64, v123 quad_perm:[1,0,3,2] row_mask:0xf bank_mask:0xf
	v_cvt_pk_bf16_f32 v148, v19, v35
	ds_write_b32 v151, v148 offset:816
	v_fmac_f32_e32 v18, v116, v19
	v_fmac_f32_e32 v34, v118, v35
	v_fmac_f32_dpp v18, v19, v122 quad_perm:[1,0,3,2] row_mask:0xf bank_mask:0xf
	v_fmac_f32_dpp v34, v35, v123 quad_perm:[1,0,3,2] row_mask:0xf bank_mask:0xf
	v_cvt_pk_bf16_f32 v149, v18, v34
	ds_write_b32 v151, v149 offset:544
	v_fmac_f32_e32 v17, v116, v18
	v_fmac_f32_e32 v33, v118, v34
	v_fmac_f32_dpp v17, v18, v122 quad_perm:[1,0,3,2] row_mask:0xf bank_mask:0xf
	v_fmac_f32_dpp v33, v34, v123 quad_perm:[1,0,3,2] row_mask:0xf bank_mask:0xf
	v_cvt_pk_bf16_f32 v148, v17, v33
	ds_write_b32 v151, v148 offset:272
	v_fmac_f32_e32 v16, v116, v17
	v_fmac_f32_e32 v32, v118, v33
	v_fmac_f32_dpp v16, v17, v122 quad_perm:[1,0,3,2] row_mask:0xf bank_mask:0xf
	v_fmac_f32_dpp v32, v33, v123 quad_perm:[1,0,3,2] row_mask:0xf bank_mask:0xf
	v_cvt_pk_bf16_f32 v149, v16, v32
	ds_write_b32 v151, v149
	v_mov_b32_e32 v120, v16
	v_mov_b32_e32 v121, v32
	ds_read_b128 v[124:127], v152
	ds_read_b128 v[128:131], v152 offset:64
	ds_read_b128 v[132:135], v152 offset:128
	ds_read_b128 v[136:139], v152 offset:192
	ds_read_b64 v[168:169], v171
	s_waitcnt lgkmcnt(4)
	v_mfma_f32_16x16x32_bf16 v[140:143], v[100:103], v[124:127], 0
	s_waitcnt lgkmcnt(3)
	v_mfma_f32_16x16x32_bf16 v[140:143], v[104:107], v[128:131], v[140:143]
	s_waitcnt lgkmcnt(2)
	v_mfma_f32_16x16x32_bf16 v[140:143], v[108:111], v[132:135], v[140:143]
	s_waitcnt lgkmcnt(1)
	v_mfma_f32_16x16x32_bf16 v[140:143], v[112:115], v[136:139], v[140:143]
	s_nop 9
	s_waitcnt vmcnt(6) lgkmcnt(0)
	v_lshlrev_b32_e32 v182, 16, v168
	v_and_b32_e32 v183, 0xffff0000, v168
	v_lshlrev_b32_e32 v184, 16, v169
	v_and_b32_e32 v185, 0xffff0000, v169
	v_lshlrev_b32_e32 v186, 16, v2
	v_and_b32_e32 v187, 0xffff0000, v2
	v_lshlrev_b32_e32 v188, 16, v3
	v_and_b32_e32 v189, 0xffff0000, v3
	v_add_f32_e32 v182, v182, v140
	v_add_f32_e32 v183, v183, v141
	v_add_f32_e32 v184, v184, v142
	v_add_f32_e32 v185, v185, v143
	v_fmac_f32_e32 v182, v164, v186
	v_fmac_f32_e32 v183, v165, v187
	v_fmac_f32_e32 v184, v166, v188
	v_fmac_f32_e32 v185, v167, v189
	v_mul_f32_e32 v186, 0x3d372713, v182
	v_mul_f32_e32 v187, 0x3d372713, v183
	v_mul_f32_e32 v188, 0x3d372713, v184
	v_mul_f32_e32 v189, 0x3d372713, v185
	v_mul_f32_e32 v186, v182, v186
	v_mul_f32_e32 v187, v183, v187
	v_mul_f32_e32 v188, v184, v188
	v_mul_f32_e32 v189, v185, v189
	v_fma_f32 v186, v182, v186, v182
	v_fma_f32 v187, v183, v187, v183
	v_fma_f32 v188, v184, v188, v184
	v_fma_f32 v189, v185, v189, v185
	v_mul_f32_e32 v186, 0xbfcc422a, v186
	v_mul_f32_e32 v187, 0xbfcc422a, v187
	v_mul_f32_e32 v188, 0xbfcc422a, v188
	v_mul_f32_e32 v189, 0xbfcc422a, v189
	v_mul_f32_e32 v186, 0x3fb8aa3b, v186
	v_mul_f32_e32 v187, 0x3fb8aa3b, v187
	v_mul_f32_e32 v188, 0x3fb8aa3b, v188
	v_mul_f32_e32 v189, 0x3fb8aa3b, v189
	v_exp_f32_e32 v186, v186
	v_exp_f32_e32 v187, v187
	v_exp_f32_e32 v188, v188
	v_exp_f32_e32 v189, v189
	v_add_f32_e32 v186, 1.0, v186
	v_add_f32_e32 v187, 1.0, v187
	v_add_f32_e32 v188, 1.0, v188
	v_add_f32_e32 v189, 1.0, v189
	v_rcp_f32_e32 v186, v186
	v_rcp_f32_e32 v187, v187
	v_rcp_f32_e32 v188, v188
	v_rcp_f32_e32 v189, v189
	v_mul_f32_e32 v182, v182, v186
	v_mul_f32_e32 v183, v183, v187
	v_mul_f32_e32 v184, v184, v188
	v_mul_f32_e32 v185, v185, v189
	v_cvt_pk_bf16_f32 v148, v182, v183
	v_cvt_pk_bf16_f32 v149, v184, v185
	global_store_dwordx2 v156, v[148:149], s[12:13]
	ds_read_b128 v[124:127], v152 offset:4352
	ds_read_b128 v[128:131], v152 offset:4416
	ds_read_b128 v[132:135], v152 offset:4480
	ds_read_b128 v[136:139], v152 offset:4544
	ds_read_b64 v[168:169], v171 offset:512
	s_waitcnt lgkmcnt(4)
	v_mfma_f32_16x16x32_bf16 v[140:143], v[100:103], v[124:127], 0
	s_waitcnt lgkmcnt(3)
	v_mfma_f32_16x16x32_bf16 v[140:143], v[104:107], v[128:131], v[140:143]
	s_waitcnt lgkmcnt(2)
	v_mfma_f32_16x16x32_bf16 v[140:143], v[108:111], v[132:135], v[140:143]
	s_waitcnt lgkmcnt(1)
	v_mfma_f32_16x16x32_bf16 v[140:143], v[112:115], v[136:139], v[140:143]
	s_nop 9
	s_waitcnt vmcnt(7) lgkmcnt(0)
	v_lshlrev_b32_e32 v182, 16, v168
	v_and_b32_e32 v183, 0xffff0000, v168
	v_lshlrev_b32_e32 v184, 16, v169
	v_and_b32_e32 v185, 0xffff0000, v169
	v_lshlrev_b32_e32 v186, 16, v4
	v_and_b32_e32 v187, 0xffff0000, v4
	v_lshlrev_b32_e32 v188, 16, v5
	v_and_b32_e32 v189, 0xffff0000, v5
	v_add_f32_e32 v182, v182, v140
	v_add_f32_e32 v183, v183, v141
	v_add_f32_e32 v184, v184, v142
	v_add_f32_e32 v185, v185, v143
	v_fmac_f32_e32 v182, v164, v186
	v_fmac_f32_e32 v183, v165, v187
	v_fmac_f32_e32 v184, v166, v188
	v_fmac_f32_e32 v185, v167, v189
	v_mul_f32_e32 v186, 0x3d372713, v182
	v_mul_f32_e32 v187, 0x3d372713, v183
	v_mul_f32_e32 v188, 0x3d372713, v184
	v_mul_f32_e32 v189, 0x3d372713, v185
	v_mul_f32_e32 v186, v182, v186
	v_mul_f32_e32 v187, v183, v187
	v_mul_f32_e32 v188, v184, v188
	v_mul_f32_e32 v189, v185, v189
	v_fma_f32 v186, v182, v186, v182
	v_fma_f32 v187, v183, v187, v183
	v_fma_f32 v188, v184, v188, v184
	v_fma_f32 v189, v185, v189, v185
	v_mul_f32_e32 v186, 0xbfcc422a, v186
	v_mul_f32_e32 v187, 0xbfcc422a, v187
	v_mul_f32_e32 v188, 0xbfcc422a, v188
	v_mul_f32_e32 v189, 0xbfcc422a, v189
	v_mul_f32_e32 v186, 0x3fb8aa3b, v186
	v_mul_f32_e32 v187, 0x3fb8aa3b, v187
	v_mul_f32_e32 v188, 0x3fb8aa3b, v188
	v_mul_f32_e32 v189, 0x3fb8aa3b, v189
	v_exp_f32_e32 v186, v186
	v_exp_f32_e32 v187, v187
	v_exp_f32_e32 v188, v188
	v_exp_f32_e32 v189, v189
	v_add_f32_e32 v186, 1.0, v186
	v_add_f32_e32 v187, 1.0, v187
	v_add_f32_e32 v188, 1.0, v188
	v_add_f32_e32 v189, 1.0, v189
	v_rcp_f32_e32 v186, v186
	v_rcp_f32_e32 v187, v187
	v_rcp_f32_e32 v188, v188
	v_rcp_f32_e32 v189, v189
	v_mul_f32_e32 v182, v182, v186
	v_mul_f32_e32 v183, v183, v187
	v_mul_f32_e32 v184, v184, v188
	v_mul_f32_e32 v185, v185, v189
	v_cvt_pk_bf16_f32 v148, v182, v183
	v_cvt_pk_bf16_f32 v149, v184, v185
	global_store_dwordx2 v159, v[148:149], s[12:13]
	s_sub_u32 s12, s12, 65536
	s_subb_u32 s13, s13, 0
	s_sub_u32 s36, s36, 1024
	s_add_u32 s14, s14, 2
	s_cmp_lt_u32 s14, 8
	s_cbranch_scc1 .Lssm_tile_d1m2
	s_add_u32 s30, s30, 0x8000000
	s_add_u32 s16, s60, s30
	s_addc_u32 s17, s61, 0
	global_store_dword v180, v120, s[16:17]
	global_store_dword v180, v121, s[16:17] offset:64
	s_waitcnt vmcnt(0) lgkmcnt(0)
	s_add_u32 s27, s27, 1
	s_cmp_lt_u32 s27, 2
	s_cbranch_scc1 .Lssm_ctx_loop
.Lssm_done:
	v_and_b32_e32 v1, 15, v190
	v_lshrrev_b32_e32 v114, 1, v190
	v_lshrrev_b32_e32 v115, 2, v190
	v_and_b32_e32 v115, 12, v115
